# code placement: GEMM K-loop headers and peeled copies pinned to 8-byte phase (as in the baseline); pad before the pre-MMA barrier keeps the loop body byte layout
# baseline (speedup 1.0000x reference)
; #define PG8_STAGE(bufoff, gbase, voff) do { _Pragma("unroll") for (int _i = 0; _i < 2; ++_i) \
;         __builtin_amdgcn_global_load_lds((const unsigned*)((const char*)(gbase) + (voff)[_i]), (PG8_LAS unsigned*)(lds + (bufoff) + ldsw + _i * 8192), 16, 0, 0); } while (0)
; #define PG8_LDA(dst, b, h) do { _Pragma("unroll") for (int m = 0; m < 4; ++m) _Pragma("unroll") for (int k = 0; k < 2; ++k) dst[m][k] = *(const PG8_LAS bf16x8*)(lds + PG8_SA(b, h) + aoff + m * 2048 + k * 1024); } while (0)
; #define PG8_LDB(dst, b, h) do { _Pragma("unroll") for (int n = 0; n < 2; ++n) _Pragma("unroll") for (int k = 0; k < 2; ++k) dst[n][k] = *(const PG8_LAS bf16x8*)(lds + PG8_SB(b, h) + boff + n * 2048 + k * 1024); } while (0)
; #define PG8_MMA(ai, bj, At, Bt) do { __builtin_amdgcn_s_setprio(1); _Pragma("unroll") for (int m = 0; m < 4; ++m) _Pragma("unroll") for (int n = 0; n < 2; ++n) _Pragma("unroll") for (int k = 0; k < 2; ++k) \
;         acc[ai][bj][m][n] = __builtin_amdgcn_mfma_f32_16x16x32_bf16(Bt[n][k], At[m][k], acc[ai][bj][m][n], 0, 0, 0); __builtin_amdgcn_s_setprio(0); } while (0)
; #define PG8_BAR __builtin_amdgcn_s_barrier()
; template <class Epi, class Sched, bool ALIGN_EPI = false, bool SP2 = false>
; __device__ __forceinline__ void gemm_phase(PG8_LAS unsigned char* lds, const Gemm g, const Sched& S, const Epi& E) {
;     ...
;         const bool has_next = S.next(ui + 1, nxt);
;         const char* nA = has_next ? (const char*)g.A + (size_t)nxt.pm * tstep : cA; const char* nB = has_next ? (const char*)g.Bt + (size_t)nxt.pn * tstep : cB;
;         for (int t = 0; t < nt; t += 2) {
;             const bool last = (t == nt - 2);
;             const char* a1 = cA + (size_t)(t + 1) * kstep;
;             const char* a2 = last ? nA : cA + (size_t)(t + 2) * kstep; const char* b2 = last ? nB : cB + (size_t)(t + 2) * kstep;
;             const char* a3 = a2 + kstep; const char* b3 = b2 + kstep;
;             if (last && has_next) S.a_ready(nxt);
;             if constexpr (SP2) {
;             PG8_LDB(B0, 0, 0); PG8_LDB(B1, 0, 1); PG8_SCHED; PG8_LDA(At, 0, 0); PG8_STAGE(PG8_SA(1, 1), a1 + hstep, voffA);
;             PG8_WAIT_V(8); PG8_WAIT_L(0); PG8_BAR; PG8_MMA(0, 0, At, B0); PG8_MMA(0, 1, At, B1); PG8_BAR; PG8_SCHED;
;             PG8_LDA(At, 0, 1); PG8_STAGE(PG8_SB(0, 0), b2, voffB); PG8_STAGE(PG8_SB(0, 1), b2 + hstep, voffB); PG8_STAGE(PG8_SA(0, 0), a2, voffA);
.LBB0_131:
	s_ashr_i32 s35, s34, 31
	s_lshl_b64 s[38:39], s[34:35], 21
	s_add_u32 s38, s51, s38
	s_addc_u32 s39, s52, s39
	s_and_b64 s[40:41], s[36:37], exec
	s_cselect_b32 s35, s39, s3
	s_cselect_b32 s43, s38, s2
	s_ashr_i32 s17, s16, 31
	s_lshl_b64 s[40:41], s[16:17], 21
	s_add_u32 s40, s53, s40
	s_addc_u32 s41, s54, s41
	s_and_b64 s[48:49], s[36:37], exec
	s_cselect_b32 s17, s41, s47
	s_cselect_b32 s79, s40, s46
	s_add_u32 s2, s2, 0x100080
	s_addc_u32 s3, s3, 0
	s_add_u32 s80, s46, 0x100
	s_addc_u32 s81, s47, 0
	s_mov_b32 s82, -2
	.p2align	3
	ds_read_b128 v[152:155], v171
	ds_read_b128 v[176:179], v171 offset:1024
	ds_read_b128 v[180:183], v171 offset:2048
	ds_read_b128 v[184:187], v171 offset:3072
	ds_read_b128 v[188:191], v172
	ds_read_b128 v[192:195], v172 offset:1024
	ds_read_b128 v[198:201], v172 offset:2048
	ds_read_b128 v[202:205], v172 offset:3072
	s_add_u32 s46, s2, 0xfff00080
	s_addc_u32 s47, s3, -1
	s_cmp_eq_u32 s82, 60
	s_cselect_b32 s49, s35, s47
	s_cselect_b32 s48, s43, s46
	s_cselect_b32 s47, s17, s81
	s_cselect_b32 s46, s79, s80
	v_lshl_add_u64 v[156:157], s[2:3], 0, v[144:145]
	s_add_i32 m0, s45, 0xc000
	ds_read_b128 v[206:209], v173
	ds_read_b128 v[210:213], v173 offset:1024
	ds_read_b128 v[214:217], v173 offset:2048
	ds_read_b128 v[218:221], v173 offset:3072
	ds_read_b128 v[222:225], v173 offset:4096
	ds_read_b128 v[226:229], v173 offset:5120
	ds_read_b128 v[230:233], v173 offset:6144
	ds_read_b128 v[234:237], v173 offset:7168
	global_load_lds_dwordx4 v[156:157], off
	v_lshl_add_u64 v[156:157], s[2:3], 0, v[146:147]
	s_add_i32 m0, s45, 0xe000
	s_nop 0
	global_load_lds_dwordx4 v[156:157], off
	s_waitcnt vmcnt(8)
	s_waitcnt lgkmcnt(0)
	s_nop 0
	s_setprio 1
	s_barrier
	v_mfma_f32_16x16x32_bf16 v[126:129], v[152:155], v[206:209], 0
	v_mfma_f32_16x16x32_bf16 v[122:125], v[180:183], v[206:209], 0
	v_mfma_f32_16x16x32_bf16 v[110:113], v[152:155], v[214:217], 0
	v_mfma_f32_16x16x32_bf16 v[106:109], v[180:183], v[214:217], 0
	v_mfma_f32_16x16x32_bf16 v[94:97], v[152:155], v[222:225], 0
	v_mfma_f32_16x16x32_bf16 v[90:93], v[180:183], v[222:225], 0
	v_mfma_f32_16x16x32_bf16 v[78:81], v[152:155], v[230:233], 0
	v_mfma_f32_16x16x32_bf16 v[74:77], v[180:183], v[230:233], 0
	v_mfma_f32_16x16x32_bf16 v[126:129], v[176:179], v[210:213], v[126:129]
	v_mfma_f32_16x16x32_bf16 v[122:125], v[184:187], v[210:213], v[122:125]
	v_mfma_f32_16x16x32_bf16 v[110:113], v[176:179], v[218:221], v[110:113]
	v_mfma_f32_16x16x32_bf16 v[106:109], v[184:187], v[218:221], v[106:109]
	v_mfma_f32_16x16x32_bf16 v[94:97], v[176:179], v[226:229], v[94:97]
	v_mfma_f32_16x16x32_bf16 v[90:93], v[184:187], v[226:229], v[90:93]
	v_mfma_f32_16x16x32_bf16 v[78:81], v[176:179], v[234:237], v[78:81]
	v_mfma_f32_16x16x32_bf16 v[74:77], v[184:187], v[234:237], v[74:77]
	s_setprio 0
	s_setprio 1
	v_mfma_f32_16x16x32_bf16 v[118:121], v[188:191], v[206:209], 0
	v_mfma_f32_16x16x32_bf16 v[114:117], v[198:201], v[206:209], 0
	v_mfma_f32_16x16x32_bf16 v[102:105], v[188:191], v[214:217], 0
	v_mfma_f32_16x16x32_bf16 v[98:101], v[198:201], v[214:217], 0
	v_mfma_f32_16x16x32_bf16 v[86:89], v[188:191], v[222:225], 0
	v_mfma_f32_16x16x32_bf16 v[82:85], v[198:201], v[222:225], 0
	v_mfma_f32_16x16x32_bf16 v[70:73], v[188:191], v[230:233], 0
	v_mfma_f32_16x16x32_bf16 v[66:69], v[198:201], v[230:233], 0
	v_mfma_f32_16x16x32_bf16 v[118:121], v[192:195], v[210:213], v[118:121]
	v_mfma_f32_16x16x32_bf16 v[114:117], v[202:205], v[210:213], v[114:117]
	v_mfma_f32_16x16x32_bf16 v[102:105], v[192:195], v[218:221], v[102:105]
	v_mfma_f32_16x16x32_bf16 v[98:101], v[202:205], v[218:221], v[98:101]
	v_mfma_f32_16x16x32_bf16 v[86:89], v[192:195], v[226:229], v[86:89]
	v_mfma_f32_16x16x32_bf16 v[82:85], v[202:205], v[226:229], v[82:85]
	v_mfma_f32_16x16x32_bf16 v[70:73], v[192:195], v[234:237], v[70:73]
	v_mfma_f32_16x16x32_bf16 v[66:69], v[202:205], v[234:237], v[66:69]
	s_setprio 0
	s_barrier
	s_add_i32 s83, s74, s55
	v_lshl_add_u64 v[156:157], s[46:47], 0, v[132:133]
	s_mov_b32 m0, s83
	ds_read_b128 v[206:209], v173 offset:16384
	ds_read_b128 v[210:213], v173 offset:17408
	ds_read_b128 v[214:217], v173 offset:18432
	ds_read_b128 v[218:221], v173 offset:19456
	ds_read_b128 v[222:225], v173 offset:20480
	ds_read_b128 v[226:229], v173 offset:21504
	ds_read_b128 v[230:233], v173 offset:22528
	ds_read_b128 v[234:237], v173 offset:23552
	global_load_lds_dwordx4 v[156:157], off
	s_add_i32 m0, s83, 0x2000
	s_add_u32 s84, s46, 0x100000
	v_lshl_add_u64 v[238:239], s[46:47], 0, v[136:137]
	s_addc_u32 s85, s47, 0
	s_add_i32 s83, s75, s55
	global_load_lds_dwordx4 v[238:239], off
	v_lshl_add_u64 v[240:241], s[84:85], 0, v[132:133]
	s_mov_b32 m0, s83
	v_lshl_add_u64 v[242:243], s[48:49], 0, v[134:135]
	global_load_lds_dwordx4 v[240:241], off
	v_lshl_add_u64 v[240:241], s[84:85], 0, v[136:137]
	s_add_i32 m0, s83, 0x2000
	s_nop 0
	global_load_lds_dwordx4 v[240:241], off
	v_lshl_add_u64 v[240:241], s[48:49], 0, v[130:131]
	s_mov_b32 m0, s45
	s_nop 0
	global_load_lds_dwordx4 v[240:241], off
	s_mov_b32 m0, s56
	s_nop 0
	global_load_lds_dwordx4 v[242:243], off
	s_waitcnt vmcnt(8)
	s_waitcnt lgkmcnt(0)
	s_nop 0
	s_setprio 1
	s_barrier
; #define PG8_STAGE(bufoff, gbase, voff) do { _Pragma("unroll") for (int _i = 0; _i < 2; ++_i) \
;         __builtin_amdgcn_global_load_lds((const unsigned*)((const char*)(gbase) + (voff)[_i]), (PG8_LAS unsigned*)(lds + (bufoff) + ldsw + _i * 8192), 16, 0, 0); } while (0)
; #define PG8_LDA(dst, b, h) do { _Pragma("unroll") for (int m = 0; m < 4; ++m) _Pragma("unroll") for (int k = 0; k < 2; ++k) dst[m][k] = *(const PG8_LAS bf16x8*)(lds + PG8_SA(b, h) + aoff + m * 2048 + k * 1024); } while (0)
; #define PG8_LDB(dst, b, h) do { _Pragma("unroll") for (int n = 0; n < 2; ++n) _Pragma("unroll") for (int k = 0; k < 2; ++k) dst[n][k] = *(const PG8_LAS bf16x8*)(lds + PG8_SB(b, h) + boff + n * 2048 + k * 1024); } while (0)
; #define PG8_MMA(ai, bj, At, Bt) do { __builtin_amdgcn_s_setprio(1); _Pragma("unroll") for (int m = 0; m < 4; ++m) _Pragma("unroll") for (int n = 0; n < 2; ++n) _Pragma("unroll") for (int k = 0; k < 2; ++k) \
;         acc[ai][bj][m][n] = __builtin_amdgcn_mfma_f32_16x16x32_bf16(Bt[n][k], At[m][k], acc[ai][bj][m][n], 0, 0, 0); __builtin_amdgcn_s_setprio(0); } while (0)
; #define PG8_WAIT_V(n) asm volatile("s_waitcnt vmcnt(" #n ")" ::: "memory")
; #define PG8_WAIT_L(n) asm volatile("s_waitcnt lgkmcnt(" #n ")" ::: "memory")
; #define PG8_BAR __builtin_amdgcn_s_barrier()
; #define PG8_SCHED __builtin_amdgcn_sched_barrier(0)
; template <class Epi, class Sched, bool ALIGN_EPI = false, bool SP2 = false>
; __device__ __forceinline__ void gemm_phase(PG8_LAS unsigned char* lds, const Gemm g, const Sched& S, const Epi& E) {
;     ...
;             PG8_WAIT_V(8); PG8_WAIT_L(0); PG8_BAR; PG8_MMA(1, 0, At, B0); PG8_MMA(1, 1, At, B1); PG8_BAR; PG8_SCHED;
;             PG8_LDB(B0, 1, 0); PG8_LDB(B1, 1, 1); PG8_SCHED; PG8_LDA(At, 1, 0); PG8_STAGE(PG8_SA(0, 1), a2 + hstep, voffA);
;             PG8_WAIT_V(8); PG8_WAIT_L(0); PG8_BAR; PG8_MMA(0, 0, At, B0); PG8_MMA(0, 1, At, B1); PG8_BAR; PG8_SCHED;
	v_mfma_f32_16x16x32_bf16 v[62:65], v[152:155], v[206:209], 0
	v_mfma_f32_16x16x32_bf16 v[58:61], v[180:183], v[206:209], 0
	v_mfma_f32_16x16x32_bf16 v[46:49], v[152:155], v[214:217], 0
	v_mfma_f32_16x16x32_bf16 v[42:45], v[180:183], v[214:217], 0
	v_mfma_f32_16x16x32_bf16 v[30:33], v[152:155], v[222:225], 0
	v_mfma_f32_16x16x32_bf16 v[26:29], v[180:183], v[222:225], 0
	v_mfma_f32_16x16x32_bf16 v[14:17], v[152:155], v[230:233], 0
	v_mfma_f32_16x16x32_bf16 v[10:13], v[180:183], v[230:233], 0
	v_mfma_f32_16x16x32_bf16 v[62:65], v[176:179], v[210:213], v[62:65]
	v_mfma_f32_16x16x32_bf16 v[58:61], v[184:187], v[210:213], v[58:61]
	v_mfma_f32_16x16x32_bf16 v[46:49], v[176:179], v[218:221], v[46:49]
	v_mfma_f32_16x16x32_bf16 v[42:45], v[184:187], v[218:221], v[42:45]
	v_mfma_f32_16x16x32_bf16 v[30:33], v[176:179], v[226:229], v[30:33]
	v_mfma_f32_16x16x32_bf16 v[26:29], v[184:187], v[226:229], v[26:29]
	v_mfma_f32_16x16x32_bf16 v[14:17], v[176:179], v[234:237], v[14:17]
	v_mfma_f32_16x16x32_bf16 v[10:13], v[184:187], v[234:237], v[10:13]
	s_setprio 0
	s_setprio 1
	v_mfma_f32_16x16x32_bf16 v[54:57], v[188:191], v[206:209], 0
	v_mfma_f32_16x16x32_bf16 v[50:53], v[198:201], v[206:209], 0
	v_mfma_f32_16x16x32_bf16 v[38:41], v[188:191], v[214:217], 0
	v_mfma_f32_16x16x32_bf16 v[34:37], v[198:201], v[214:217], 0
	v_mfma_f32_16x16x32_bf16 v[22:25], v[188:191], v[222:225], 0
	v_mfma_f32_16x16x32_bf16 v[18:21], v[198:201], v[222:225], 0
	v_mfma_f32_16x16x32_bf16 v[6:9], v[188:191], v[230:233], 0
	v_mfma_f32_16x16x32_bf16 v[2:5], v[198:201], v[230:233], 0
	v_mfma_f32_16x16x32_bf16 v[54:57], v[192:195], v[210:213], v[54:57]
	v_mfma_f32_16x16x32_bf16 v[50:53], v[202:205], v[210:213], v[50:53]
	v_mfma_f32_16x16x32_bf16 v[38:41], v[192:195], v[218:221], v[38:41]
	v_mfma_f32_16x16x32_bf16 v[34:37], v[202:205], v[218:221], v[34:37]
	v_mfma_f32_16x16x32_bf16 v[22:25], v[192:195], v[226:229], v[22:25]
	v_mfma_f32_16x16x32_bf16 v[18:21], v[202:205], v[226:229], v[18:21]
	v_mfma_f32_16x16x32_bf16 v[6:9], v[192:195], v[234:237], v[6:9]
	v_mfma_f32_16x16x32_bf16 v[2:5], v[202:205], v[234:237], v[2:5]
	s_setprio 0
	s_barrier
	s_add_i32 s83, 0, 0x18000
	v_add_u32_e32 v149, s83, v167
	s_add_i32 s84, 0, 0x1c000
	ds_read_b128 v[152:155], v149
	ds_read_b128 v[176:179], v149 offset:1024
	ds_read_b128 v[180:183], v149 offset:2048
	ds_read_b128 v[184:187], v149 offset:3072
	v_add_u32_e32 v149, s84, v167
	ds_read_b128 v[188:191], v149
	ds_read_b128 v[192:195], v149 offset:1024
	ds_read_b128 v[198:201], v149 offset:2048
	ds_read_b128 v[202:205], v149 offset:3072
	s_add_u32 s48, s48, 0x100000
	s_addc_u32 s49, s49, 0
	s_mov_b32 m0, s57
	v_lshl_add_u64 v[244:245], s[48:49], 0, v[130:131]
	ds_read_b128 v[206:209], v173 offset:32768
	ds_read_b128 v[210:213], v173 offset:33792
	ds_read_b128 v[214:217], v173 offset:34816
	ds_read_b128 v[218:221], v173 offset:35840
	ds_read_b128 v[222:225], v173 offset:36864
	ds_read_b128 v[226:229], v173 offset:37888
	ds_read_b128 v[230:233], v173 offset:38912
	ds_read_b128 v[234:237], v173 offset:39936
	global_load_lds_dwordx4 v[244:245], off
	v_lshl_add_u64 v[244:245], s[48:49], 0, v[134:135]
	s_mov_b32 m0, s58
	s_nop 0
	global_load_lds_dwordx4 v[244:245], off
	s_waitcnt vmcnt(8)
	s_waitcnt lgkmcnt(0)
	s_nop 0
	s_setprio 1
	s_barrier
	v_mfma_f32_16x16x32_bf16 v[126:129], v[152:155], v[206:209], v[126:129]
	v_mfma_f32_16x16x32_bf16 v[122:125], v[180:183], v[206:209], v[122:125]
	v_mfma_f32_16x16x32_bf16 v[110:113], v[152:155], v[214:217], v[110:113]
	v_mfma_f32_16x16x32_bf16 v[106:109], v[180:183], v[214:217], v[106:109]
	v_mfma_f32_16x16x32_bf16 v[94:97], v[152:155], v[222:225], v[94:97]
	v_mfma_f32_16x16x32_bf16 v[90:93], v[180:183], v[222:225], v[90:93]
	v_mfma_f32_16x16x32_bf16 v[78:81], v[152:155], v[230:233], v[78:81]
	v_mfma_f32_16x16x32_bf16 v[74:77], v[180:183], v[230:233], v[74:77]
	v_mfma_f32_16x16x32_bf16 v[126:129], v[176:179], v[210:213], v[126:129]
	v_mfma_f32_16x16x32_bf16 v[122:125], v[184:187], v[210:213], v[122:125]
	v_mfma_f32_16x16x32_bf16 v[110:113], v[176:179], v[218:221], v[110:113]
	v_mfma_f32_16x16x32_bf16 v[106:109], v[184:187], v[218:221], v[106:109]
	v_mfma_f32_16x16x32_bf16 v[94:97], v[176:179], v[226:229], v[94:97]
	v_mfma_f32_16x16x32_bf16 v[90:93], v[184:187], v[226:229], v[90:93]
	v_mfma_f32_16x16x32_bf16 v[78:81], v[176:179], v[234:237], v[78:81]
	v_mfma_f32_16x16x32_bf16 v[74:77], v[184:187], v[234:237], v[74:77]
	s_setprio 0
	s_setprio 1
	v_mfma_f32_16x16x32_bf16 v[118:121], v[188:191], v[206:209], v[118:121]
	v_mfma_f32_16x16x32_bf16 v[114:117], v[198:201], v[206:209], v[114:117]
	v_mfma_f32_16x16x32_bf16 v[102:105], v[188:191], v[214:217], v[102:105]
	v_mfma_f32_16x16x32_bf16 v[98:101], v[198:201], v[214:217], v[98:101]
	v_mfma_f32_16x16x32_bf16 v[86:89], v[188:191], v[222:225], v[86:89]
	v_mfma_f32_16x16x32_bf16 v[82:85], v[198:201], v[222:225], v[82:85]
	v_mfma_f32_16x16x32_bf16 v[70:73], v[188:191], v[230:233], v[70:73]
	v_mfma_f32_16x16x32_bf16 v[66:69], v[198:201], v[230:233], v[66:69]
	v_mfma_f32_16x16x32_bf16 v[118:121], v[192:195], v[210:213], v[118:121]
	v_mfma_f32_16x16x32_bf16 v[114:117], v[202:205], v[210:213], v[114:117]
	v_mfma_f32_16x16x32_bf16 v[102:105], v[192:195], v[218:221], v[102:105]
	v_mfma_f32_16x16x32_bf16 v[98:101], v[202:205], v[218:221], v[98:101]
	v_mfma_f32_16x16x32_bf16 v[86:89], v[192:195], v[226:229], v[86:89]
	v_mfma_f32_16x16x32_bf16 v[82:85], v[202:205], v[226:229], v[82:85]
	v_mfma_f32_16x16x32_bf16 v[70:73], v[192:195], v[234:237], v[70:73]
	v_mfma_f32_16x16x32_bf16 v[66:69], v[202:205], v[234:237], v[66:69]
	s_setprio 0
	s_barrier
; #define PG8_STAGE(bufoff, gbase, voff) do { _Pragma("unroll") for (int _i = 0; _i < 2; ++_i) \
;         __builtin_amdgcn_global_load_lds((const unsigned*)((const char*)(gbase) + (voff)[_i]), (PG8_LAS unsigned*)(lds + (bufoff) + ldsw + _i * 8192), 16, 0, 0); } while (0)
; #define PG8_LDA(dst, b, h) do { _Pragma("unroll") for (int m = 0; m < 4; ++m) _Pragma("unroll") for (int k = 0; k < 2; ++k) dst[m][k] = *(const PG8_LAS bf16x8*)(lds + PG8_SA(b, h) + aoff + m * 2048 + k * 1024); } while (0)
; #define PG8_LDB(dst, b, h) do { _Pragma("unroll") for (int n = 0; n < 2; ++n) _Pragma("unroll") for (int k = 0; k < 2; ++k) dst[n][k] = *(const PG8_LAS bf16x8*)(lds + PG8_SB(b, h) + boff + n * 2048 + k * 1024); } while (0)
; #define PG8_MMA(ai, bj, At, Bt) do { __builtin_amdgcn_s_setprio(1); _Pragma("unroll") for (int m = 0; m < 4; ++m) _Pragma("unroll") for (int n = 0; n < 2; ++n) _Pragma("unroll") for (int k = 0; k < 2; ++k) \
;         acc[ai][bj][m][n] = __builtin_amdgcn_mfma_f32_16x16x32_bf16(Bt[n][k], At[m][k], acc[ai][bj][m][n], 0, 0, 0); __builtin_amdgcn_s_setprio(0); } while (0)
; #define PG8_WAIT_V(n) asm volatile("s_waitcnt vmcnt(" #n ")" ::: "memory")
; #define PG8_WAIT_L(n) asm volatile("s_waitcnt lgkmcnt(" #n ")" ::: "memory")
; #define PG8_BAR __builtin_amdgcn_s_barrier()
; #define PG8_SCHED __builtin_amdgcn_sched_barrier(0)
; template <class Epi, class Sched, bool ALIGN_EPI = false, bool SP2 = false>
; __device__ __forceinline__ void gemm_phase(PG8_LAS unsigned char* lds, const Gemm g, const Sched& S, const Epi& E) {
;     ...
;         for (int t = 0; t < nt; t += 2) {
;             const bool last = (t == nt - 2);
;             const char* a1 = cA + (size_t)(t + 1) * kstep;
;             const char* a2 = last ? nA : cA + (size_t)(t + 2) * kstep; const char* b2 = last ? nB : cB + (size_t)(t + 2) * kstep;
;             const char* a3 = a2 + kstep; const char* b3 = b2 + kstep;
;             if (last && has_next) S.a_ready(nxt);
;             if constexpr (SP2) {
;             PG8_LDB(B0, 0, 0); PG8_LDB(B1, 0, 1); PG8_SCHED; PG8_LDA(At, 0, 0); PG8_STAGE(PG8_SA(1, 1), a1 + hstep, voffA);
;     ...
;             PG8_LDA(At, 1, 1); PG8_STAGE(PG8_SB(1, 0), b3, voffB); PG8_STAGE(PG8_SB(1, 1), b3 + hstep, voffB); PG8_STAGE(PG8_SA(1, 0), a3, voffA);
;             PG8_WAIT_V(8); PG8_WAIT_L(0); PG8_BAR; PG8_MMA(1, 0, At, B0); PG8_MMA(1, 1, At, B1); PG8_BAR; PG8_SCHED;
	s_add_i32 s48, s83, s55
	v_lshl_add_u64 v[156:157], v[156:157], 0, s[10:11]
	s_mov_b32 m0, s48
	ds_read_b128 v[206:209], v173 offset:49152
	ds_read_b128 v[210:213], v173 offset:50176
	ds_read_b128 v[214:217], v173 offset:51200
	ds_read_b128 v[218:221], v173 offset:52224
	ds_read_b128 v[222:225], v173 offset:53248
	ds_read_b128 v[226:229], v173 offset:54272
	ds_read_b128 v[230:233], v173 offset:55296
	ds_read_b128 v[234:237], v173 offset:56320
	global_load_lds_dwordx4 v[156:157], off
	s_add_i32 m0, s48, 0x2000
	s_add_u32 s46, s46, 0x100080
	v_lshl_add_u64 v[156:157], v[238:239], 0, s[10:11]
	s_addc_u32 s47, s47, 0
	s_add_i32 s48, s84, s55
	global_load_lds_dwordx4 v[156:157], off
	v_lshl_add_u64 v[156:157], s[46:47], 0, v[132:133]
	s_mov_b32 m0, s48
	s_nop 0
	global_load_lds_dwordx4 v[156:157], off
	v_lshl_add_u64 v[156:157], s[46:47], 0, v[136:137]
	s_add_i32 m0, s48, 0x2000
	s_nop 0
	global_load_lds_dwordx4 v[156:157], off
	v_lshl_add_u64 v[156:157], v[240:241], 0, s[10:11]
	s_mov_b32 m0, s63
	s_nop 0
	global_load_lds_dwordx4 v[156:157], off
	v_lshl_add_u64 v[156:157], v[242:243], 0, s[10:11]
	s_mov_b32 m0, s70
	s_nop 0
	global_load_lds_dwordx4 v[156:157], off
	s_waitcnt vmcnt(8)
	s_waitcnt lgkmcnt(0)
	s_nop 0
	s_setprio 1
	s_barrier
	v_mfma_f32_16x16x32_bf16 v[62:65], v[152:155], v[206:209], v[62:65]
	v_mfma_f32_16x16x32_bf16 v[58:61], v[180:183], v[206:209], v[58:61]
	v_mfma_f32_16x16x32_bf16 v[46:49], v[152:155], v[214:217], v[46:49]
	v_mfma_f32_16x16x32_bf16 v[42:45], v[180:183], v[214:217], v[42:45]
	v_mfma_f32_16x16x32_bf16 v[30:33], v[152:155], v[222:225], v[30:33]
	v_mfma_f32_16x16x32_bf16 v[26:29], v[180:183], v[222:225], v[26:29]
	v_mfma_f32_16x16x32_bf16 v[14:17], v[152:155], v[230:233], v[14:17]
	v_mfma_f32_16x16x32_bf16 v[10:13], v[180:183], v[230:233], v[10:13]
	v_mfma_f32_16x16x32_bf16 v[62:65], v[176:179], v[210:213], v[62:65]
	v_mfma_f32_16x16x32_bf16 v[58:61], v[184:187], v[210:213], v[58:61]
	v_mfma_f32_16x16x32_bf16 v[46:49], v[176:179], v[218:221], v[46:49]
	v_mfma_f32_16x16x32_bf16 v[42:45], v[184:187], v[218:221], v[42:45]
	v_mfma_f32_16x16x32_bf16 v[30:33], v[176:179], v[226:229], v[30:33]
	v_mfma_f32_16x16x32_bf16 v[26:29], v[184:187], v[226:229], v[26:29]
	v_mfma_f32_16x16x32_bf16 v[14:17], v[176:179], v[234:237], v[14:17]
	v_mfma_f32_16x16x32_bf16 v[10:13], v[184:187], v[234:237], v[10:13]
	s_setprio 0
	s_setprio 1
	v_mfma_f32_16x16x32_bf16 v[54:57], v[188:191], v[206:209], v[54:57]
	v_mfma_f32_16x16x32_bf16 v[50:53], v[198:201], v[206:209], v[50:53]
	v_mfma_f32_16x16x32_bf16 v[38:41], v[188:191], v[214:217], v[38:41]
	v_mfma_f32_16x16x32_bf16 v[34:37], v[198:201], v[214:217], v[34:37]
	v_mfma_f32_16x16x32_bf16 v[22:25], v[188:191], v[222:225], v[22:25]
	v_mfma_f32_16x16x32_bf16 v[18:21], v[198:201], v[222:225], v[18:21]
	v_mfma_f32_16x16x32_bf16 v[6:9], v[188:191], v[230:233], v[6:9]
	v_mfma_f32_16x16x32_bf16 v[2:5], v[198:201], v[230:233], v[2:5]
	v_mfma_f32_16x16x32_bf16 v[54:57], v[192:195], v[210:213], v[54:57]
	v_mfma_f32_16x16x32_bf16 v[50:53], v[202:205], v[210:213], v[50:53]
	v_mfma_f32_16x16x32_bf16 v[38:41], v[192:195], v[218:221], v[38:41]
	v_mfma_f32_16x16x32_bf16 v[34:37], v[202:205], v[218:221], v[34:37]
	v_mfma_f32_16x16x32_bf16 v[22:25], v[192:195], v[226:229], v[22:25]
	v_mfma_f32_16x16x32_bf16 v[18:21], v[202:205], v[226:229], v[18:21]
	v_mfma_f32_16x16x32_bf16 v[6:9], v[192:195], v[234:237], v[6:9]
	v_mfma_f32_16x16x32_bf16 v[2:5], v[202:205], v[234:237], v[2:5]
	s_setprio 0
	s_barrier
	s_add_i32 s82, s82, 2
	s_add_u32 s2, s2, 0x100
	s_addc_u32 s3, s3, 0
	s_add_u32 s80, s80, 0x100
	s_addc_u32 s81, s81, 0
	s_cmp_gt_u32 s82, 61
	.p2align	3
.LBB0_132:
	ds_read_b128 v[152:155], v171
	ds_read_b128 v[176:179], v171 offset:1024
	ds_read_b128 v[180:183], v171 offset:2048
	ds_read_b128 v[184:187], v171 offset:3072
	ds_read_b128 v[188:191], v172
	ds_read_b128 v[192:195], v172 offset:1024
	ds_read_b128 v[198:201], v172 offset:2048
	ds_read_b128 v[202:205], v172 offset:3072
	s_add_u32 s46, s2, 0xfff00080
	s_addc_u32 s47, s3, -1
	s_cmp_eq_u32 s82, 60
	s_cselect_b32 s49, s35, s47
	s_cselect_b32 s48, s43, s46
	s_cselect_b32 s47, s17, s81
	s_cselect_b32 s46, s79, s80
	v_lshl_add_u64 v[156:157], s[2:3], 0, v[144:145]
	s_add_i32 m0, s45, 0xc000
	ds_read_b128 v[206:209], v173
	ds_read_b128 v[210:213], v173 offset:1024
	ds_read_b128 v[214:217], v173 offset:2048
	ds_read_b128 v[218:221], v173 offset:3072
	ds_read_b128 v[222:225], v173 offset:4096
	ds_read_b128 v[226:229], v173 offset:5120
	ds_read_b128 v[230:233], v173 offset:6144
	ds_read_b128 v[234:237], v173 offset:7168
	global_load_lds_dwordx4 v[156:157], off
	v_lshl_add_u64 v[156:157], s[2:3], 0, v[146:147]
	s_add_i32 m0, s45, 0xe000
	s_nop 0
	global_load_lds_dwordx4 v[156:157], off
	s_waitcnt vmcnt(8)
	s_waitcnt lgkmcnt(0)
	s_nop 0
	s_setprio 1
	s_barrier
; #define PG8_STAGE(bufoff, gbase, voff) do { _Pragma("unroll") for (int _i = 0; _i < 2; ++_i) \
;         __builtin_amdgcn_global_load_lds((const unsigned*)((const char*)(gbase) + (voff)[_i]), (PG8_LAS unsigned*)(lds + (bufoff) + ldsw + _i * 8192), 16, 0, 0); } while (0)
; #define PG8_LDA(dst, b, h) do { _Pragma("unroll") for (int m = 0; m < 4; ++m) _Pragma("unroll") for (int k = 0; k < 2; ++k) dst[m][k] = *(const PG8_LAS bf16x8*)(lds + PG8_SA(b, h) + aoff + m * 2048 + k * 1024); } while (0)
; #define PG8_MMA(ai, bj, At, Bt) do { __builtin_amdgcn_s_setprio(1); _Pragma("unroll") for (int m = 0; m < 4; ++m) _Pragma("unroll") for (int n = 0; n < 2; ++n) _Pragma("unroll") for (int k = 0; k < 2; ++k) \
;         acc[ai][bj][m][n] = __builtin_amdgcn_mfma_f32_16x16x32_bf16(Bt[n][k], At[m][k], acc[ai][bj][m][n], 0, 0, 0); __builtin_amdgcn_s_setprio(0); } while (0)
; #define PG8_WAIT_V(n) asm volatile("s_waitcnt vmcnt(" #n ")" ::: "memory")
; #define PG8_WAIT_L(n) asm volatile("s_waitcnt lgkmcnt(" #n ")" ::: "memory")
; #define PG8_BAR __builtin_amdgcn_s_barrier()
; #define PG8_SCHED __builtin_amdgcn_sched_barrier(0)
; template <class Epi, class Sched, bool ALIGN_EPI = false, bool SP2 = false>
; __device__ __forceinline__ void gemm_phase(PG8_LAS unsigned char* lds, const Gemm g, const Sched& S, const Epi& E) {
;     ...
;             PG8_WAIT_V(8); PG8_WAIT_L(0); PG8_BAR; PG8_MMA(0, 0, At, B0); PG8_MMA(0, 1, At, B1); PG8_BAR; PG8_SCHED;
;             PG8_LDA(At, 0, 1); PG8_STAGE(PG8_SB(0, 0), b2, voffB); PG8_STAGE(PG8_SB(0, 1), b2 + hstep, voffB); PG8_STAGE(PG8_SA(0, 0), a2, voffA);
;             PG8_WAIT_V(8); PG8_WAIT_L(0); PG8_BAR; PG8_MMA(1, 0, At, B0); PG8_MMA(1, 1, At, B1); PG8_BAR; PG8_SCHED;
	v_mfma_f32_16x16x32_bf16 v[126:129], v[152:155], v[206:209], v[126:129]
	v_mfma_f32_16x16x32_bf16 v[122:125], v[180:183], v[206:209], v[122:125]
	v_mfma_f32_16x16x32_bf16 v[110:113], v[152:155], v[214:217], v[110:113]
	v_mfma_f32_16x16x32_bf16 v[106:109], v[180:183], v[214:217], v[106:109]
	v_mfma_f32_16x16x32_bf16 v[94:97], v[152:155], v[222:225], v[94:97]
	v_mfma_f32_16x16x32_bf16 v[90:93], v[180:183], v[222:225], v[90:93]
	v_mfma_f32_16x16x32_bf16 v[78:81], v[152:155], v[230:233], v[78:81]
	v_mfma_f32_16x16x32_bf16 v[74:77], v[180:183], v[230:233], v[74:77]
	v_mfma_f32_16x16x32_bf16 v[126:129], v[176:179], v[210:213], v[126:129]
	v_mfma_f32_16x16x32_bf16 v[122:125], v[184:187], v[210:213], v[122:125]
	v_mfma_f32_16x16x32_bf16 v[110:113], v[176:179], v[218:221], v[110:113]
	v_mfma_f32_16x16x32_bf16 v[106:109], v[184:187], v[218:221], v[106:109]
	v_mfma_f32_16x16x32_bf16 v[94:97], v[176:179], v[226:229], v[94:97]
	v_mfma_f32_16x16x32_bf16 v[90:93], v[184:187], v[226:229], v[90:93]
	v_mfma_f32_16x16x32_bf16 v[78:81], v[176:179], v[234:237], v[78:81]
	v_mfma_f32_16x16x32_bf16 v[74:77], v[184:187], v[234:237], v[74:77]
	s_setprio 0
	s_setprio 1
	v_mfma_f32_16x16x32_bf16 v[118:121], v[188:191], v[206:209], v[118:121]
	v_mfma_f32_16x16x32_bf16 v[114:117], v[198:201], v[206:209], v[114:117]
	v_mfma_f32_16x16x32_bf16 v[102:105], v[188:191], v[214:217], v[102:105]
	v_mfma_f32_16x16x32_bf16 v[98:101], v[198:201], v[214:217], v[98:101]
	v_mfma_f32_16x16x32_bf16 v[86:89], v[188:191], v[222:225], v[86:89]
	v_mfma_f32_16x16x32_bf16 v[82:85], v[198:201], v[222:225], v[82:85]
	v_mfma_f32_16x16x32_bf16 v[70:73], v[188:191], v[230:233], v[70:73]
	v_mfma_f32_16x16x32_bf16 v[66:69], v[198:201], v[230:233], v[66:69]
	v_mfma_f32_16x16x32_bf16 v[118:121], v[192:195], v[210:213], v[118:121]
	v_mfma_f32_16x16x32_bf16 v[114:117], v[202:205], v[210:213], v[114:117]
	v_mfma_f32_16x16x32_bf16 v[102:105], v[192:195], v[218:221], v[102:105]
	v_mfma_f32_16x16x32_bf16 v[98:101], v[202:205], v[218:221], v[98:101]
	v_mfma_f32_16x16x32_bf16 v[86:89], v[192:195], v[226:229], v[86:89]
	v_mfma_f32_16x16x32_bf16 v[82:85], v[202:205], v[226:229], v[82:85]
	v_mfma_f32_16x16x32_bf16 v[70:73], v[192:195], v[234:237], v[70:73]
	v_mfma_f32_16x16x32_bf16 v[66:69], v[202:205], v[234:237], v[66:69]
	s_setprio 0
	s_barrier
	s_add_i32 s83, s74, s55
	v_lshl_add_u64 v[156:157], s[46:47], 0, v[132:133]
	s_mov_b32 m0, s83
	ds_read_b128 v[206:209], v173 offset:16384
	ds_read_b128 v[210:213], v173 offset:17408
	ds_read_b128 v[214:217], v173 offset:18432
	ds_read_b128 v[218:221], v173 offset:19456
	ds_read_b128 v[222:225], v173 offset:20480
	ds_read_b128 v[226:229], v173 offset:21504
	ds_read_b128 v[230:233], v173 offset:22528
	ds_read_b128 v[234:237], v173 offset:23552
	global_load_lds_dwordx4 v[156:157], off
	s_add_i32 m0, s83, 0x2000
	s_add_u32 s84, s46, 0x100000
	v_lshl_add_u64 v[238:239], s[46:47], 0, v[136:137]
	s_addc_u32 s85, s47, 0
	s_add_i32 s83, s75, s55
	global_load_lds_dwordx4 v[238:239], off
	v_lshl_add_u64 v[240:241], s[84:85], 0, v[132:133]
	s_mov_b32 m0, s83
	v_lshl_add_u64 v[242:243], s[48:49], 0, v[134:135]
	global_load_lds_dwordx4 v[240:241], off
	v_lshl_add_u64 v[240:241], s[84:85], 0, v[136:137]
	s_add_i32 m0, s83, 0x2000
	s_nop 0
	global_load_lds_dwordx4 v[240:241], off
	v_lshl_add_u64 v[240:241], s[48:49], 0, v[130:131]
	s_mov_b32 m0, s45
	s_nop 0
	global_load_lds_dwordx4 v[240:241], off
	s_mov_b32 m0, s56
	s_nop 0
	global_load_lds_dwordx4 v[242:243], off
	s_waitcnt vmcnt(8)
	s_waitcnt lgkmcnt(0)
	s_nop 0
	s_setprio 1
	s_barrier
	v_mfma_f32_16x16x32_bf16 v[62:65], v[152:155], v[206:209], v[62:65]
	v_mfma_f32_16x16x32_bf16 v[58:61], v[180:183], v[206:209], v[58:61]
	v_mfma_f32_16x16x32_bf16 v[46:49], v[152:155], v[214:217], v[46:49]
	v_mfma_f32_16x16x32_bf16 v[42:45], v[180:183], v[214:217], v[42:45]
	v_mfma_f32_16x16x32_bf16 v[30:33], v[152:155], v[222:225], v[30:33]
	v_mfma_f32_16x16x32_bf16 v[26:29], v[180:183], v[222:225], v[26:29]
	v_mfma_f32_16x16x32_bf16 v[14:17], v[152:155], v[230:233], v[14:17]
	v_mfma_f32_16x16x32_bf16 v[10:13], v[180:183], v[230:233], v[10:13]
	v_mfma_f32_16x16x32_bf16 v[62:65], v[176:179], v[210:213], v[62:65]
	v_mfma_f32_16x16x32_bf16 v[58:61], v[184:187], v[210:213], v[58:61]
	v_mfma_f32_16x16x32_bf16 v[46:49], v[176:179], v[218:221], v[46:49]
	v_mfma_f32_16x16x32_bf16 v[42:45], v[184:187], v[218:221], v[42:45]
	v_mfma_f32_16x16x32_bf16 v[30:33], v[176:179], v[226:229], v[30:33]
	v_mfma_f32_16x16x32_bf16 v[26:29], v[184:187], v[226:229], v[26:29]
	v_mfma_f32_16x16x32_bf16 v[14:17], v[176:179], v[234:237], v[14:17]
	v_mfma_f32_16x16x32_bf16 v[10:13], v[184:187], v[234:237], v[10:13]
	s_setprio 0
	s_setprio 1
	v_mfma_f32_16x16x32_bf16 v[54:57], v[188:191], v[206:209], v[54:57]
	v_mfma_f32_16x16x32_bf16 v[50:53], v[198:201], v[206:209], v[50:53]
	v_mfma_f32_16x16x32_bf16 v[38:41], v[188:191], v[214:217], v[38:41]
	v_mfma_f32_16x16x32_bf16 v[34:37], v[198:201], v[214:217], v[34:37]
	v_mfma_f32_16x16x32_bf16 v[22:25], v[188:191], v[222:225], v[22:25]
	v_mfma_f32_16x16x32_bf16 v[18:21], v[198:201], v[222:225], v[18:21]
	v_mfma_f32_16x16x32_bf16 v[6:9], v[188:191], v[230:233], v[6:9]
	v_mfma_f32_16x16x32_bf16 v[2:5], v[198:201], v[230:233], v[2:5]
	v_mfma_f32_16x16x32_bf16 v[54:57], v[192:195], v[210:213], v[54:57]
	v_mfma_f32_16x16x32_bf16 v[50:53], v[202:205], v[210:213], v[50:53]
	v_mfma_f32_16x16x32_bf16 v[38:41], v[192:195], v[218:221], v[38:41]
	v_mfma_f32_16x16x32_bf16 v[34:37], v[202:205], v[218:221], v[34:37]
	v_mfma_f32_16x16x32_bf16 v[22:25], v[192:195], v[226:229], v[22:25]
	v_mfma_f32_16x16x32_bf16 v[18:21], v[202:205], v[226:229], v[18:21]
	v_mfma_f32_16x16x32_bf16 v[6:9], v[192:195], v[234:237], v[6:9]
	v_mfma_f32_16x16x32_bf16 v[2:5], v[202:205], v[234:237], v[2:5]
	s_setprio 0
	s_barrier
; #define PG8_STAGE(bufoff, gbase, voff) do { _Pragma("unroll") for (int _i = 0; _i < 2; ++_i) \
;         __builtin_amdgcn_global_load_lds((const unsigned*)((const char*)(gbase) + (voff)[_i]), (PG8_LAS unsigned*)(lds + (bufoff) + ldsw + _i * 8192), 16, 0, 0); } while (0)
; #define PG8_LDA(dst, b, h) do { _Pragma("unroll") for (int m = 0; m < 4; ++m) _Pragma("unroll") for (int k = 0; k < 2; ++k) dst[m][k] = *(const PG8_LAS bf16x8*)(lds + PG8_SA(b, h) + aoff + m * 2048 + k * 1024); } while (0)
; #define PG8_LDB(dst, b, h) do { _Pragma("unroll") for (int n = 0; n < 2; ++n) _Pragma("unroll") for (int k = 0; k < 2; ++k) dst[n][k] = *(const PG8_LAS bf16x8*)(lds + PG8_SB(b, h) + boff + n * 2048 + k * 1024); } while (0)
; #define PG8_MMA(ai, bj, At, Bt) do { __builtin_amdgcn_s_setprio(1); _Pragma("unroll") for (int m = 0; m < 4; ++m) _Pragma("unroll") for (int n = 0; n < 2; ++n) _Pragma("unroll") for (int k = 0; k < 2; ++k) \
;         acc[ai][bj][m][n] = __builtin_amdgcn_mfma_f32_16x16x32_bf16(Bt[n][k], At[m][k], acc[ai][bj][m][n], 0, 0, 0); __builtin_amdgcn_s_setprio(0); } while (0)
; #define PG8_WAIT_V(n) asm volatile("s_waitcnt vmcnt(" #n ")" ::: "memory")
; #define PG8_WAIT_L(n) asm volatile("s_waitcnt lgkmcnt(" #n ")" ::: "memory")
; #define PG8_BAR __builtin_amdgcn_s_barrier()
; #define PG8_SCHED __builtin_amdgcn_sched_barrier(0)
; template <class Epi, class Sched, bool ALIGN_EPI = false, bool SP2 = false>
; __device__ __forceinline__ void gemm_phase(PG8_LAS unsigned char* lds, const Gemm g, const Sched& S, const Epi& E) {
;     ...
;             PG8_LDB(B0, 1, 0); PG8_LDB(B1, 1, 1); PG8_SCHED; PG8_LDA(At, 1, 0); PG8_STAGE(PG8_SA(0, 1), a2 + hstep, voffA);
;             PG8_WAIT_V(8); PG8_WAIT_L(0); PG8_BAR; PG8_MMA(0, 0, At, B0); PG8_MMA(0, 1, At, B1); PG8_BAR; PG8_SCHED;
	s_add_i32 s83, 0, 0x18000
	v_add_u32_e32 v149, s83, v167
	s_add_i32 s84, 0, 0x1c000
	ds_read_b128 v[152:155], v149
	ds_read_b128 v[176:179], v149 offset:1024
	ds_read_b128 v[180:183], v149 offset:2048
	ds_read_b128 v[184:187], v149 offset:3072
	v_add_u32_e32 v149, s84, v167
	ds_read_b128 v[188:191], v149
	ds_read_b128 v[192:195], v149 offset:1024
	ds_read_b128 v[198:201], v149 offset:2048
	ds_read_b128 v[202:205], v149 offset:3072
	s_add_u32 s48, s48, 0x100000
	s_addc_u32 s49, s49, 0
	s_mov_b32 m0, s57
	v_lshl_add_u64 v[244:245], s[48:49], 0, v[130:131]
	ds_read_b128 v[206:209], v173 offset:32768
	ds_read_b128 v[210:213], v173 offset:33792
	ds_read_b128 v[214:217], v173 offset:34816
	ds_read_b128 v[218:221], v173 offset:35840
	ds_read_b128 v[222:225], v173 offset:36864
	ds_read_b128 v[226:229], v173 offset:37888
	ds_read_b128 v[230:233], v173 offset:38912
	ds_read_b128 v[234:237], v173 offset:39936
	global_load_lds_dwordx4 v[244:245], off
	v_lshl_add_u64 v[244:245], s[48:49], 0, v[134:135]
	s_mov_b32 m0, s58
	s_nop 0
	global_load_lds_dwordx4 v[244:245], off
	s_waitcnt vmcnt(8)
	s_waitcnt lgkmcnt(0)
	s_nop 0
	s_setprio 1
	s_barrier
	v_mfma_f32_16x16x32_bf16 v[126:129], v[152:155], v[206:209], v[126:129]
	v_mfma_f32_16x16x32_bf16 v[122:125], v[180:183], v[206:209], v[122:125]
	v_mfma_f32_16x16x32_bf16 v[110:113], v[152:155], v[214:217], v[110:113]
	v_mfma_f32_16x16x32_bf16 v[106:109], v[180:183], v[214:217], v[106:109]
	v_mfma_f32_16x16x32_bf16 v[94:97], v[152:155], v[222:225], v[94:97]
	v_mfma_f32_16x16x32_bf16 v[90:93], v[180:183], v[222:225], v[90:93]
	v_mfma_f32_16x16x32_bf16 v[78:81], v[152:155], v[230:233], v[78:81]
	v_mfma_f32_16x16x32_bf16 v[74:77], v[180:183], v[230:233], v[74:77]
	v_mfma_f32_16x16x32_bf16 v[126:129], v[176:179], v[210:213], v[126:129]
	v_mfma_f32_16x16x32_bf16 v[122:125], v[184:187], v[210:213], v[122:125]
	v_mfma_f32_16x16x32_bf16 v[110:113], v[176:179], v[218:221], v[110:113]
	v_mfma_f32_16x16x32_bf16 v[106:109], v[184:187], v[218:221], v[106:109]
	v_mfma_f32_16x16x32_bf16 v[94:97], v[176:179], v[226:229], v[94:97]
	v_mfma_f32_16x16x32_bf16 v[90:93], v[184:187], v[226:229], v[90:93]
	v_mfma_f32_16x16x32_bf16 v[78:81], v[176:179], v[234:237], v[78:81]
	v_mfma_f32_16x16x32_bf16 v[74:77], v[184:187], v[234:237], v[74:77]
	s_setprio 0
	s_setprio 1
	v_mfma_f32_16x16x32_bf16 v[118:121], v[188:191], v[206:209], v[118:121]
	v_mfma_f32_16x16x32_bf16 v[114:117], v[198:201], v[206:209], v[114:117]
	v_mfma_f32_16x16x32_bf16 v[102:105], v[188:191], v[214:217], v[102:105]
	v_mfma_f32_16x16x32_bf16 v[98:101], v[198:201], v[214:217], v[98:101]
	v_mfma_f32_16x16x32_bf16 v[86:89], v[188:191], v[222:225], v[86:89]
	v_mfma_f32_16x16x32_bf16 v[82:85], v[198:201], v[222:225], v[82:85]
	v_mfma_f32_16x16x32_bf16 v[70:73], v[188:191], v[230:233], v[70:73]
	v_mfma_f32_16x16x32_bf16 v[66:69], v[198:201], v[230:233], v[66:69]
	v_mfma_f32_16x16x32_bf16 v[118:121], v[192:195], v[210:213], v[118:121]
	v_mfma_f32_16x16x32_bf16 v[114:117], v[202:205], v[210:213], v[114:117]
	v_mfma_f32_16x16x32_bf16 v[102:105], v[192:195], v[218:221], v[102:105]
	v_mfma_f32_16x16x32_bf16 v[98:101], v[202:205], v[218:221], v[98:101]
	v_mfma_f32_16x16x32_bf16 v[86:89], v[192:195], v[226:229], v[86:89]
	v_mfma_f32_16x16x32_bf16 v[82:85], v[202:205], v[226:229], v[82:85]
	v_mfma_f32_16x16x32_bf16 v[70:73], v[192:195], v[234:237], v[70:73]
	v_mfma_f32_16x16x32_bf16 v[66:69], v[202:205], v[234:237], v[66:69]
	s_setprio 0
	s_barrier
; #define PG8_STAGE(bufoff, gbase, voff) do { _Pragma("unroll") for (int _i = 0; _i < 2; ++_i) \
;         __builtin_amdgcn_global_load_lds((const unsigned*)((const char*)(gbase) + (voff)[_i]), (PG8_LAS unsigned*)(lds + (bufoff) + ldsw + _i * 8192), 16, 0, 0); } while (0)
; #define PG8_LDA(dst, b, h) do { _Pragma("unroll") for (int m = 0; m < 4; ++m) _Pragma("unroll") for (int k = 0; k < 2; ++k) dst[m][k] = *(const PG8_LAS bf16x8*)(lds + PG8_SA(b, h) + aoff + m * 2048 + k * 1024); } while (0)
; #define PG8_MMA(ai, bj, At, Bt) do { __builtin_amdgcn_s_setprio(1); _Pragma("unroll") for (int m = 0; m < 4; ++m) _Pragma("unroll") for (int n = 0; n < 2; ++n) _Pragma("unroll") for (int k = 0; k < 2; ++k) \
;         acc[ai][bj][m][n] = __builtin_amdgcn_mfma_f32_16x16x32_bf16(Bt[n][k], At[m][k], acc[ai][bj][m][n], 0, 0, 0); __builtin_amdgcn_s_setprio(0); } while (0)
; #define PG8_WAIT_V(n) asm volatile("s_waitcnt vmcnt(" #n ")" ::: "memory")
; #define PG8_WAIT_L(n) asm volatile("s_waitcnt lgkmcnt(" #n ")" ::: "memory")
; #define PG8_BAR __builtin_amdgcn_s_barrier()
; #define PG8_SCHED __builtin_amdgcn_sched_barrier(0)
; template <class Epi, class Sched, bool ALIGN_EPI = false, bool SP2 = false>
; __device__ __forceinline__ void gemm_phase(PG8_LAS unsigned char* lds, const Gemm g, const Sched& S, const Epi& E) {
;     ...
;             PG8_LDA(At, 1, 1); PG8_STAGE(PG8_SB(1, 0), b3, voffB); PG8_STAGE(PG8_SB(1, 1), b3 + hstep, voffB); PG8_STAGE(PG8_SA(1, 0), a3, voffA);
;             PG8_WAIT_V(8); PG8_WAIT_L(0); PG8_BAR; PG8_MMA(1, 0, At, B0); PG8_MMA(1, 1, At, B1); PG8_BAR; PG8_SCHED;
;     ...
;         if constexpr (ALIGN_EPI) { if (wr == 0) PG8_BAR; }
	s_add_i32 s48, s83, s55
	v_lshl_add_u64 v[156:157], v[156:157], 0, s[10:11]
	s_mov_b32 m0, s48
	ds_read_b128 v[206:209], v173 offset:49152
	ds_read_b128 v[210:213], v173 offset:50176
	ds_read_b128 v[214:217], v173 offset:51200
	ds_read_b128 v[218:221], v173 offset:52224
	ds_read_b128 v[222:225], v173 offset:53248
	ds_read_b128 v[226:229], v173 offset:54272
	ds_read_b128 v[230:233], v173 offset:55296
	ds_read_b128 v[234:237], v173 offset:56320
	global_load_lds_dwordx4 v[156:157], off
	s_add_i32 m0, s48, 0x2000
	s_add_u32 s46, s46, 0x100080
	v_lshl_add_u64 v[156:157], v[238:239], 0, s[10:11]
	s_addc_u32 s47, s47, 0
	s_add_i32 s48, s84, s55
	global_load_lds_dwordx4 v[156:157], off
	v_lshl_add_u64 v[156:157], s[46:47], 0, v[132:133]
	s_mov_b32 m0, s48
	s_nop 0
	global_load_lds_dwordx4 v[156:157], off
	v_lshl_add_u64 v[156:157], s[46:47], 0, v[136:137]
	s_add_i32 m0, s48, 0x2000
	s_nop 0
	global_load_lds_dwordx4 v[156:157], off
	v_lshl_add_u64 v[156:157], v[240:241], 0, s[10:11]
	s_mov_b32 m0, s63
	s_nop 0
	global_load_lds_dwordx4 v[156:157], off
	v_lshl_add_u64 v[156:157], v[242:243], 0, s[10:11]
	s_mov_b32 m0, s70
	s_nop 0
	global_load_lds_dwordx4 v[156:157], off
	s_waitcnt vmcnt(8)
	s_waitcnt lgkmcnt(0)
	s_nop 0
	s_setprio 1
	s_barrier
	v_mfma_f32_16x16x32_bf16 v[62:65], v[152:155], v[206:209], v[62:65]
	v_mfma_f32_16x16x32_bf16 v[58:61], v[180:183], v[206:209], v[58:61]
	v_mfma_f32_16x16x32_bf16 v[46:49], v[152:155], v[214:217], v[46:49]
	v_mfma_f32_16x16x32_bf16 v[42:45], v[180:183], v[214:217], v[42:45]
	v_mfma_f32_16x16x32_bf16 v[30:33], v[152:155], v[222:225], v[30:33]
	v_mfma_f32_16x16x32_bf16 v[26:29], v[180:183], v[222:225], v[26:29]
	v_mfma_f32_16x16x32_bf16 v[14:17], v[152:155], v[230:233], v[14:17]
	v_mfma_f32_16x16x32_bf16 v[10:13], v[180:183], v[230:233], v[10:13]
	v_mfma_f32_16x16x32_bf16 v[62:65], v[176:179], v[210:213], v[62:65]
	v_mfma_f32_16x16x32_bf16 v[58:61], v[184:187], v[210:213], v[58:61]
	v_mfma_f32_16x16x32_bf16 v[46:49], v[176:179], v[218:221], v[46:49]
	v_mfma_f32_16x16x32_bf16 v[42:45], v[184:187], v[218:221], v[42:45]
	v_mfma_f32_16x16x32_bf16 v[30:33], v[176:179], v[226:229], v[30:33]
	v_mfma_f32_16x16x32_bf16 v[26:29], v[184:187], v[226:229], v[26:29]
	v_mfma_f32_16x16x32_bf16 v[14:17], v[176:179], v[234:237], v[14:17]
	v_mfma_f32_16x16x32_bf16 v[10:13], v[184:187], v[234:237], v[10:13]
	s_setprio 0
	s_setprio 1
	v_mfma_f32_16x16x32_bf16 v[54:57], v[188:191], v[206:209], v[54:57]
	v_mfma_f32_16x16x32_bf16 v[50:53], v[198:201], v[206:209], v[50:53]
	v_mfma_f32_16x16x32_bf16 v[38:41], v[188:191], v[214:217], v[38:41]
	v_mfma_f32_16x16x32_bf16 v[34:37], v[198:201], v[214:217], v[34:37]
	v_mfma_f32_16x16x32_bf16 v[22:25], v[188:191], v[222:225], v[22:25]
	v_mfma_f32_16x16x32_bf16 v[18:21], v[198:201], v[222:225], v[18:21]
	v_mfma_f32_16x16x32_bf16 v[6:9], v[188:191], v[230:233], v[6:9]
	v_mfma_f32_16x16x32_bf16 v[2:5], v[198:201], v[230:233], v[2:5]
	v_mfma_f32_16x16x32_bf16 v[54:57], v[192:195], v[210:213], v[54:57]
	v_mfma_f32_16x16x32_bf16 v[50:53], v[202:205], v[210:213], v[50:53]
	v_mfma_f32_16x16x32_bf16 v[38:41], v[192:195], v[218:221], v[38:41]
	v_mfma_f32_16x16x32_bf16 v[34:37], v[202:205], v[218:221], v[34:37]
	v_mfma_f32_16x16x32_bf16 v[22:25], v[192:195], v[226:229], v[22:25]
	v_mfma_f32_16x16x32_bf16 v[18:21], v[202:205], v[226:229], v[18:21]
	v_mfma_f32_16x16x32_bf16 v[6:9], v[192:195], v[234:237], v[6:9]
	v_mfma_f32_16x16x32_bf16 v[2:5], v[202:205], v[234:237], v[2:5]
	s_setprio 0
	s_barrier
	s_add_i32 s82, s82, 2
	s_add_u32 s2, s2, 0x100
	s_addc_u32 s3, s3, 0
	s_add_u32 s80, s80, 0x100
	s_addc_u32 s81, s81, 0
	s_cmp_gt_u32 s82, 61
	s_cbranch_scc0 .LBB0_132
	s_and_b64 vcc, exec, s[12:13]
	s_cbranch_vccz .LBB0_135
	s_barrier

; #define PG8_STAGE(bufoff, gbase, voff) do { _Pragma("unroll") for (int _i = 0; _i < 2; ++_i) \
;         __builtin_amdgcn_global_load_lds((const unsigned*)((const char*)(gbase) + (voff)[_i]), (PG8_LAS unsigned*)(lds + (bufoff) + ldsw + _i * 8192), 16, 0, 0); } while (0)
; #define PG8_LDA(dst, b, h) do { _Pragma("unroll") for (int m = 0; m < 4; ++m) _Pragma("unroll") for (int k = 0; k < 2; ++k) dst[m][k] = *(const PG8_LAS bf16x8*)(lds + PG8_SA(b, h) + aoff + m * 2048 + k * 1024); } while (0)
; #define PG8_LDB(dst, b, h) do { _Pragma("unroll") for (int n = 0; n < 2; ++n) _Pragma("unroll") for (int k = 0; k < 2; ++k) dst[n][k] = *(const PG8_LAS bf16x8*)(lds + PG8_SB(b, h) + boff + n * 2048 + k * 1024); } while (0)
; #define PG8_WAIT_V(n) asm volatile("s_waitcnt vmcnt(" #n ")" ::: "memory")
; #define PG8_WAIT_L(n) asm volatile("s_waitcnt lgkmcnt(" #n ")" ::: "memory")
; #define PG8_BAR __builtin_amdgcn_s_barrier()
; #define PG8_SCHED __builtin_amdgcn_sched_barrier(0)
; template <class Epi, class Sched, bool ALIGN_EPI = false, bool SP2 = false>
; __device__ __forceinline__ void gemm_phase(PG8_LAS unsigned char* lds, const Gemm g, const Sched& S, const Epi& E) {
;     ...
;         const char* nA = has_next ? (const char*)g.A + (size_t)nxt.pm * tstep : cA; const char* nB = has_next ? (const char*)g.Bt + (size_t)nxt.pn * tstep : cB;
;         for (int t = 0; t < nt; t += 2) {
;             const bool last = (t == nt - 2);
;             const char* a1 = cA + (size_t)(t + 1) * kstep;
;             const char* a2 = last ? nA : cA + (size_t)(t + 2) * kstep; const char* b2 = last ? nB : cB + (size_t)(t + 2) * kstep;
;             const char* a3 = a2 + kstep; const char* b3 = b2 + kstep;
;             if (last && has_next) S.a_ready(nxt);
;             if constexpr (SP2) {
;             PG8_LDB(B0, 0, 0); PG8_LDB(B1, 0, 1); PG8_SCHED; PG8_LDA(At, 0, 0); PG8_STAGE(PG8_SA(1, 1), a1 + hstep, voffA);
;             PG8_WAIT_V(8); PG8_WAIT_L(0); PG8_BAR; PG8_MMA(0, 0, At, B0); PG8_MMA(0, 1, At, B1); PG8_BAR; PG8_SCHED;
;             PG8_LDA(At, 0, 1); PG8_STAGE(PG8_SB(0, 0), b2, voffB); PG8_STAGE(PG8_SB(0, 1), b2 + hstep, voffB); PG8_STAGE(PG8_SA(0, 0), a2, voffA);
;             PG8_WAIT_V(8); PG8_WAIT_L(0); PG8_BAR; PG8_MMA(1, 0, At, B0); PG8_MMA(1, 1, At, B1); PG8_BAR; PG8_SCHED;
.LBB0_216:
	s_ashr_i32 s35, s34, 31
	s_lshl_b64 s[38:39], s[34:35], 21
	s_add_u32 s38, s51, s38
	s_addc_u32 s39, s52, s39
	s_and_b64 s[40:41], s[36:37], exec
	s_cselect_b32 s3, s39, s45
	s_cselect_b32 s35, s38, s44
	s_ashr_i32 s17, s16, 31
	s_lshl_b64 s[40:41], s[16:17], 21
	s_add_u32 s40, s53, s40
	s_addc_u32 s41, s54, s41
	s_and_b64 s[48:49], s[36:37], exec
	s_cselect_b32 s17, s41, s47
	s_cselect_b32 s43, s40, s46
	s_add_u32 s44, s44, 0x100080
	s_addc_u32 s45, s45, 0
	s_add_u32 s78, s46, 0x100
	s_addc_u32 s79, s47, 0
	s_mov_b32 s80, -2
	.p2align	3
	ds_read_b128 v[152:155], v159
	ds_read_b128 v[168:171], v159 offset:1024
	ds_read_b128 v[172:175], v159 offset:2048
	ds_read_b128 v[176:179], v159 offset:3072
	ds_read_b128 v[180:183], v160
	ds_read_b128 v[184:187], v160 offset:1024
	ds_read_b128 v[188:191], v160 offset:2048
	ds_read_b128 v[192:195], v160 offset:3072
	s_add_u32 s46, s44, 0xfff00080
	s_addc_u32 s47, s45, -1
	s_cmp_eq_u32 s80, 60
	s_cselect_b32 s49, s3, s47
	s_cselect_b32 s48, s35, s46
	s_cselect_b32 s47, s17, s79
	s_cselect_b32 s46, s43, s78
	v_lshl_add_u64 v[156:157], s[44:45], 0, v[144:145]
	s_add_i32 m0, s56, 0xc000
	ds_read_b128 v[198:201], v161
	ds_read_b128 v[202:205], v161 offset:1024
	ds_read_b128 v[206:209], v161 offset:2048
	ds_read_b128 v[210:213], v161 offset:3072
	ds_read_b128 v[214:217], v161 offset:4096
	ds_read_b128 v[218:221], v161 offset:5120
	ds_read_b128 v[222:225], v161 offset:6144
	ds_read_b128 v[226:229], v161 offset:7168
	global_load_lds_dwordx4 v[156:157], off
	v_lshl_add_u64 v[156:157], s[44:45], 0, v[146:147]
	s_add_i32 m0, s56, 0xe000
	s_nop 0
	global_load_lds_dwordx4 v[156:157], off
	s_waitcnt vmcnt(8)
	s_waitcnt lgkmcnt(0)
	s_nop 0
	s_setprio 1
	s_barrier
	v_mfma_f32_16x16x32_bf16 v[126:129], v[152:155], v[198:201], 0
	v_mfma_f32_16x16x32_bf16 v[122:125], v[172:175], v[198:201], 0
	v_mfma_f32_16x16x32_bf16 v[110:113], v[152:155], v[206:209], 0
	v_mfma_f32_16x16x32_bf16 v[106:109], v[172:175], v[206:209], 0
	v_mfma_f32_16x16x32_bf16 v[94:97], v[152:155], v[214:217], 0
	v_mfma_f32_16x16x32_bf16 v[90:93], v[172:175], v[214:217], 0
	v_mfma_f32_16x16x32_bf16 v[78:81], v[152:155], v[222:225], 0
	v_mfma_f32_16x16x32_bf16 v[74:77], v[172:175], v[222:225], 0
	v_mfma_f32_16x16x32_bf16 v[126:129], v[168:171], v[202:205], v[126:129]
	v_mfma_f32_16x16x32_bf16 v[122:125], v[176:179], v[202:205], v[122:125]
	v_mfma_f32_16x16x32_bf16 v[110:113], v[168:171], v[210:213], v[110:113]
	v_mfma_f32_16x16x32_bf16 v[106:109], v[176:179], v[210:213], v[106:109]
	v_mfma_f32_16x16x32_bf16 v[94:97], v[168:171], v[218:221], v[94:97]
	v_mfma_f32_16x16x32_bf16 v[90:93], v[176:179], v[218:221], v[90:93]
	v_mfma_f32_16x16x32_bf16 v[78:81], v[168:171], v[226:229], v[78:81]
	v_mfma_f32_16x16x32_bf16 v[74:77], v[176:179], v[226:229], v[74:77]
	s_setprio 0
	s_setprio 1
	v_mfma_f32_16x16x32_bf16 v[118:121], v[180:183], v[198:201], 0
	v_mfma_f32_16x16x32_bf16 v[114:117], v[188:191], v[198:201], 0
	v_mfma_f32_16x16x32_bf16 v[102:105], v[180:183], v[206:209], 0
	v_mfma_f32_16x16x32_bf16 v[98:101], v[188:191], v[206:209], 0
	v_mfma_f32_16x16x32_bf16 v[86:89], v[180:183], v[214:217], 0
	v_mfma_f32_16x16x32_bf16 v[82:85], v[188:191], v[214:217], 0
	v_mfma_f32_16x16x32_bf16 v[70:73], v[180:183], v[222:225], 0
	v_mfma_f32_16x16x32_bf16 v[66:69], v[188:191], v[222:225], 0
	v_mfma_f32_16x16x32_bf16 v[118:121], v[184:187], v[202:205], v[118:121]
	v_mfma_f32_16x16x32_bf16 v[114:117], v[192:195], v[202:205], v[114:117]
	v_mfma_f32_16x16x32_bf16 v[102:105], v[184:187], v[210:213], v[102:105]
	v_mfma_f32_16x16x32_bf16 v[98:101], v[192:195], v[210:213], v[98:101]
	v_mfma_f32_16x16x32_bf16 v[86:89], v[184:187], v[218:221], v[86:89]
	v_mfma_f32_16x16x32_bf16 v[82:85], v[192:195], v[218:221], v[82:85]
	v_mfma_f32_16x16x32_bf16 v[70:73], v[184:187], v[226:229], v[70:73]
	v_mfma_f32_16x16x32_bf16 v[66:69], v[192:195], v[226:229], v[66:69]
	s_setprio 0
	s_barrier
	s_add_i32 s81, s73, s55
	v_lshl_add_u64 v[156:157], s[46:47], 0, v[132:133]
	s_mov_b32 m0, s81
	ds_read_b128 v[198:201], v161 offset:16384
	ds_read_b128 v[202:205], v161 offset:17408
	ds_read_b128 v[206:209], v161 offset:18432
	ds_read_b128 v[210:213], v161 offset:19456
	ds_read_b128 v[214:217], v161 offset:20480
	ds_read_b128 v[218:221], v161 offset:21504
	ds_read_b128 v[222:225], v161 offset:22528
	ds_read_b128 v[226:229], v161 offset:23552
	global_load_lds_dwordx4 v[156:157], off
	s_add_i32 m0, s81, 0x2000
	s_add_u32 s82, s46, 0x100000
	v_lshl_add_u64 v[230:231], s[46:47], 0, v[136:137]
	s_addc_u32 s83, s47, 0
	s_add_i32 s81, s74, s55
	global_load_lds_dwordx4 v[230:231], off
	v_lshl_add_u64 v[232:233], s[82:83], 0, v[132:133]
	s_mov_b32 m0, s81
	v_lshl_add_u64 v[234:235], s[48:49], 0, v[134:135]
	global_load_lds_dwordx4 v[232:233], off
	v_lshl_add_u64 v[232:233], s[82:83], 0, v[136:137]
	s_add_i32 m0, s81, 0x2000
	s_nop 0
	global_load_lds_dwordx4 v[232:233], off
	v_lshl_add_u64 v[232:233], s[48:49], 0, v[130:131]
	s_mov_b32 m0, s56
	s_nop 0
	global_load_lds_dwordx4 v[232:233], off
	s_mov_b32 m0, s57
	s_nop 0
	global_load_lds_dwordx4 v[234:235], off
	s_waitcnt vmcnt(8)
	s_waitcnt lgkmcnt(0)
	s_nop 0
	s_setprio 1
	s_barrier
; #define PG8_STAGE(bufoff, gbase, voff) do { _Pragma("unroll") for (int _i = 0; _i < 2; ++_i) \
;         __builtin_amdgcn_global_load_lds((const unsigned*)((const char*)(gbase) + (voff)[_i]), (PG8_LAS unsigned*)(lds + (bufoff) + ldsw + _i * 8192), 16, 0, 0); } while (0)
; #define PG8_LDA(dst, b, h) do { _Pragma("unroll") for (int m = 0; m < 4; ++m) _Pragma("unroll") for (int k = 0; k < 2; ++k) dst[m][k] = *(const PG8_LAS bf16x8*)(lds + PG8_SA(b, h) + aoff + m * 2048 + k * 1024); } while (0)
; #define PG8_LDB(dst, b, h) do { _Pragma("unroll") for (int n = 0; n < 2; ++n) _Pragma("unroll") for (int k = 0; k < 2; ++k) dst[n][k] = *(const PG8_LAS bf16x8*)(lds + PG8_SB(b, h) + boff + n * 2048 + k * 1024); } while (0)
; #define PG8_MMA(ai, bj, At, Bt) do { __builtin_amdgcn_s_setprio(1); _Pragma("unroll") for (int m = 0; m < 4; ++m) _Pragma("unroll") for (int n = 0; n < 2; ++n) _Pragma("unroll") for (int k = 0; k < 2; ++k) \
;         acc[ai][bj][m][n] = __builtin_amdgcn_mfma_f32_16x16x32_bf16(Bt[n][k], At[m][k], acc[ai][bj][m][n], 0, 0, 0); __builtin_amdgcn_s_setprio(0); } while (0)
; #define PG8_WAIT_V(n) asm volatile("s_waitcnt vmcnt(" #n ")" ::: "memory")
; #define PG8_WAIT_L(n) asm volatile("s_waitcnt lgkmcnt(" #n ")" ::: "memory")
; #define PG8_BAR __builtin_amdgcn_s_barrier()
; #define PG8_SCHED __builtin_amdgcn_sched_barrier(0)
; template <class Epi, class Sched, bool ALIGN_EPI = false, bool SP2 = false>
; __device__ __forceinline__ void gemm_phase(PG8_LAS unsigned char* lds, const Gemm g, const Sched& S, const Epi& E) {
;     ...
;             PG8_WAIT_V(8); PG8_WAIT_L(0); PG8_BAR; PG8_MMA(1, 0, At, B0); PG8_MMA(1, 1, At, B1); PG8_BAR; PG8_SCHED;
;             PG8_LDB(B0, 1, 0); PG8_LDB(B1, 1, 1); PG8_SCHED; PG8_LDA(At, 1, 0); PG8_STAGE(PG8_SA(0, 1), a2 + hstep, voffA);
;             PG8_WAIT_V(8); PG8_WAIT_L(0); PG8_BAR; PG8_MMA(0, 0, At, B0); PG8_MMA(0, 1, At, B1); PG8_BAR; PG8_SCHED;
	v_mfma_f32_16x16x32_bf16 v[62:65], v[152:155], v[198:201], 0
	v_mfma_f32_16x16x32_bf16 v[58:61], v[172:175], v[198:201], 0
	v_mfma_f32_16x16x32_bf16 v[46:49], v[152:155], v[206:209], 0
	v_mfma_f32_16x16x32_bf16 v[42:45], v[172:175], v[206:209], 0
	v_mfma_f32_16x16x32_bf16 v[30:33], v[152:155], v[214:217], 0
	v_mfma_f32_16x16x32_bf16 v[26:29], v[172:175], v[214:217], 0
	v_mfma_f32_16x16x32_bf16 v[14:17], v[152:155], v[222:225], 0
	v_mfma_f32_16x16x32_bf16 v[10:13], v[172:175], v[222:225], 0
	v_mfma_f32_16x16x32_bf16 v[62:65], v[168:171], v[202:205], v[62:65]
	v_mfma_f32_16x16x32_bf16 v[58:61], v[176:179], v[202:205], v[58:61]
	v_mfma_f32_16x16x32_bf16 v[46:49], v[168:171], v[210:213], v[46:49]
	v_mfma_f32_16x16x32_bf16 v[42:45], v[176:179], v[210:213], v[42:45]
	v_mfma_f32_16x16x32_bf16 v[30:33], v[168:171], v[218:221], v[30:33]
	v_mfma_f32_16x16x32_bf16 v[26:29], v[176:179], v[218:221], v[26:29]
	v_mfma_f32_16x16x32_bf16 v[14:17], v[168:171], v[226:229], v[14:17]
	v_mfma_f32_16x16x32_bf16 v[10:13], v[176:179], v[226:229], v[10:13]
	s_setprio 0
	s_setprio 1
	v_mfma_f32_16x16x32_bf16 v[54:57], v[180:183], v[198:201], 0
	v_mfma_f32_16x16x32_bf16 v[50:53], v[188:191], v[198:201], 0
	v_mfma_f32_16x16x32_bf16 v[38:41], v[180:183], v[206:209], 0
	v_mfma_f32_16x16x32_bf16 v[34:37], v[188:191], v[206:209], 0
	v_mfma_f32_16x16x32_bf16 v[22:25], v[180:183], v[214:217], 0
	v_mfma_f32_16x16x32_bf16 v[18:21], v[188:191], v[214:217], 0
	v_mfma_f32_16x16x32_bf16 v[6:9], v[180:183], v[222:225], 0
	v_mfma_f32_16x16x32_bf16 v[2:5], v[188:191], v[222:225], 0
	v_mfma_f32_16x16x32_bf16 v[54:57], v[184:187], v[202:205], v[54:57]
	v_mfma_f32_16x16x32_bf16 v[50:53], v[192:195], v[202:205], v[50:53]
	v_mfma_f32_16x16x32_bf16 v[38:41], v[184:187], v[210:213], v[38:41]
	v_mfma_f32_16x16x32_bf16 v[34:37], v[192:195], v[210:213], v[34:37]
	v_mfma_f32_16x16x32_bf16 v[22:25], v[184:187], v[218:221], v[22:25]
	v_mfma_f32_16x16x32_bf16 v[18:21], v[192:195], v[218:221], v[18:21]
	v_mfma_f32_16x16x32_bf16 v[6:9], v[184:187], v[226:229], v[6:9]
	v_mfma_f32_16x16x32_bf16 v[2:5], v[192:195], v[226:229], v[2:5]
	s_setprio 0
	s_barrier
	s_add_i32 s81, 0, 0x18000
	v_add_u32_e32 v149, s81, v164
	s_add_i32 s82, 0, 0x1c000
	ds_read_b128 v[152:155], v149
	ds_read_b128 v[168:171], v149 offset:1024
	ds_read_b128 v[172:175], v149 offset:2048
	ds_read_b128 v[176:179], v149 offset:3072
	v_add_u32_e32 v149, s82, v164
	ds_read_b128 v[180:183], v149
	ds_read_b128 v[184:187], v149 offset:1024
	ds_read_b128 v[188:191], v149 offset:2048
	ds_read_b128 v[192:195], v149 offset:3072
	s_add_u32 s48, s48, 0x100000
	s_addc_u32 s49, s49, 0
	s_mov_b32 m0, s58
	v_lshl_add_u64 v[236:237], s[48:49], 0, v[130:131]
	ds_read_b128 v[198:201], v161 offset:32768
	ds_read_b128 v[202:205], v161 offset:33792
	ds_read_b128 v[206:209], v161 offset:34816
	ds_read_b128 v[210:213], v161 offset:35840
	ds_read_b128 v[214:217], v161 offset:36864
	ds_read_b128 v[218:221], v161 offset:37888
	ds_read_b128 v[222:225], v161 offset:38912
	ds_read_b128 v[226:229], v161 offset:39936
	global_load_lds_dwordx4 v[236:237], off
	v_lshl_add_u64 v[236:237], s[48:49], 0, v[134:135]
	s_mov_b32 m0, s59
	s_nop 0
	global_load_lds_dwordx4 v[236:237], off
	s_waitcnt vmcnt(8)
	s_waitcnt lgkmcnt(0)
	s_nop 0
	s_setprio 1
	s_barrier
	v_mfma_f32_16x16x32_bf16 v[126:129], v[152:155], v[198:201], v[126:129]
	v_mfma_f32_16x16x32_bf16 v[122:125], v[172:175], v[198:201], v[122:125]
	v_mfma_f32_16x16x32_bf16 v[110:113], v[152:155], v[206:209], v[110:113]
	v_mfma_f32_16x16x32_bf16 v[106:109], v[172:175], v[206:209], v[106:109]
	v_mfma_f32_16x16x32_bf16 v[94:97], v[152:155], v[214:217], v[94:97]
	v_mfma_f32_16x16x32_bf16 v[90:93], v[172:175], v[214:217], v[90:93]
	v_mfma_f32_16x16x32_bf16 v[78:81], v[152:155], v[222:225], v[78:81]
	v_mfma_f32_16x16x32_bf16 v[74:77], v[172:175], v[222:225], v[74:77]
	v_mfma_f32_16x16x32_bf16 v[126:129], v[168:171], v[202:205], v[126:129]
	v_mfma_f32_16x16x32_bf16 v[122:125], v[176:179], v[202:205], v[122:125]
	v_mfma_f32_16x16x32_bf16 v[110:113], v[168:171], v[210:213], v[110:113]
	v_mfma_f32_16x16x32_bf16 v[106:109], v[176:179], v[210:213], v[106:109]
	v_mfma_f32_16x16x32_bf16 v[94:97], v[168:171], v[218:221], v[94:97]
	v_mfma_f32_16x16x32_bf16 v[90:93], v[176:179], v[218:221], v[90:93]
	v_mfma_f32_16x16x32_bf16 v[78:81], v[168:171], v[226:229], v[78:81]
	v_mfma_f32_16x16x32_bf16 v[74:77], v[176:179], v[226:229], v[74:77]
	s_setprio 0
	s_setprio 1
	v_mfma_f32_16x16x32_bf16 v[118:121], v[180:183], v[198:201], v[118:121]
	v_mfma_f32_16x16x32_bf16 v[114:117], v[188:191], v[198:201], v[114:117]
	v_mfma_f32_16x16x32_bf16 v[102:105], v[180:183], v[206:209], v[102:105]
	v_mfma_f32_16x16x32_bf16 v[98:101], v[188:191], v[206:209], v[98:101]
	v_mfma_f32_16x16x32_bf16 v[86:89], v[180:183], v[214:217], v[86:89]
	v_mfma_f32_16x16x32_bf16 v[82:85], v[188:191], v[214:217], v[82:85]
	v_mfma_f32_16x16x32_bf16 v[70:73], v[180:183], v[222:225], v[70:73]
	v_mfma_f32_16x16x32_bf16 v[66:69], v[188:191], v[222:225], v[66:69]
	v_mfma_f32_16x16x32_bf16 v[118:121], v[184:187], v[202:205], v[118:121]
	v_mfma_f32_16x16x32_bf16 v[114:117], v[192:195], v[202:205], v[114:117]
	v_mfma_f32_16x16x32_bf16 v[102:105], v[184:187], v[210:213], v[102:105]
	v_mfma_f32_16x16x32_bf16 v[98:101], v[192:195], v[210:213], v[98:101]
	v_mfma_f32_16x16x32_bf16 v[86:89], v[184:187], v[218:221], v[86:89]
	v_mfma_f32_16x16x32_bf16 v[82:85], v[192:195], v[218:221], v[82:85]
	v_mfma_f32_16x16x32_bf16 v[70:73], v[184:187], v[226:229], v[70:73]
	v_mfma_f32_16x16x32_bf16 v[66:69], v[192:195], v[226:229], v[66:69]
	s_setprio 0
	s_barrier
; #define PG8_STAGE(bufoff, gbase, voff) do { _Pragma("unroll") for (int _i = 0; _i < 2; ++_i) \
;         __builtin_amdgcn_global_load_lds((const unsigned*)((const char*)(gbase) + (voff)[_i]), (PG8_LAS unsigned*)(lds + (bufoff) + ldsw + _i * 8192), 16, 0, 0); } while (0)
; #define PG8_LDA(dst, b, h) do { _Pragma("unroll") for (int m = 0; m < 4; ++m) _Pragma("unroll") for (int k = 0; k < 2; ++k) dst[m][k] = *(const PG8_LAS bf16x8*)(lds + PG8_SA(b, h) + aoff + m * 2048 + k * 1024); } while (0)
; #define PG8_LDB(dst, b, h) do { _Pragma("unroll") for (int n = 0; n < 2; ++n) _Pragma("unroll") for (int k = 0; k < 2; ++k) dst[n][k] = *(const PG8_LAS bf16x8*)(lds + PG8_SB(b, h) + boff + n * 2048 + k * 1024); } while (0)
; #define PG8_MMA(ai, bj, At, Bt) do { __builtin_amdgcn_s_setprio(1); _Pragma("unroll") for (int m = 0; m < 4; ++m) _Pragma("unroll") for (int n = 0; n < 2; ++n) _Pragma("unroll") for (int k = 0; k < 2; ++k) \
;         acc[ai][bj][m][n] = __builtin_amdgcn_mfma_f32_16x16x32_bf16(Bt[n][k], At[m][k], acc[ai][bj][m][n], 0, 0, 0); __builtin_amdgcn_s_setprio(0); } while (0)
; #define PG8_WAIT_V(n) asm volatile("s_waitcnt vmcnt(" #n ")" ::: "memory")
; #define PG8_WAIT_L(n) asm volatile("s_waitcnt lgkmcnt(" #n ")" ::: "memory")
; #define PG8_BAR __builtin_amdgcn_s_barrier()
; #define PG8_SCHED __builtin_amdgcn_sched_barrier(0)
; template <class Epi, class Sched, bool ALIGN_EPI = false, bool SP2 = false>
; __device__ __forceinline__ void gemm_phase(PG8_LAS unsigned char* lds, const Gemm g, const Sched& S, const Epi& E) {
;     ...
;         for (int t = 0; t < nt; t += 2) {
;             const bool last = (t == nt - 2);
;             const char* a1 = cA + (size_t)(t + 1) * kstep;
;             const char* a2 = last ? nA : cA + (size_t)(t + 2) * kstep; const char* b2 = last ? nB : cB + (size_t)(t + 2) * kstep;
;             const char* a3 = a2 + kstep; const char* b3 = b2 + kstep;
;             if (last && has_next) S.a_ready(nxt);
;             if constexpr (SP2) {
;             PG8_LDB(B0, 0, 0); PG8_LDB(B1, 0, 1); PG8_SCHED; PG8_LDA(At, 0, 0); PG8_STAGE(PG8_SA(1, 1), a1 + hstep, voffA);
;     ...
;             PG8_LDA(At, 1, 1); PG8_STAGE(PG8_SB(1, 0), b3, voffB); PG8_STAGE(PG8_SB(1, 1), b3 + hstep, voffB); PG8_STAGE(PG8_SA(1, 0), a3, voffA);
;             PG8_WAIT_V(8); PG8_WAIT_L(0); PG8_BAR; PG8_MMA(1, 0, At, B0); PG8_MMA(1, 1, At, B1); PG8_BAR; PG8_SCHED;
	s_add_i32 s48, s81, s55
	v_lshl_add_u64 v[156:157], v[156:157], 0, s[10:11]
	s_mov_b32 m0, s48
	ds_read_b128 v[198:201], v161 offset:49152
	ds_read_b128 v[202:205], v161 offset:50176
	ds_read_b128 v[206:209], v161 offset:51200
	ds_read_b128 v[210:213], v161 offset:52224
	ds_read_b128 v[214:217], v161 offset:53248
	ds_read_b128 v[218:221], v161 offset:54272
	ds_read_b128 v[222:225], v161 offset:55296
	ds_read_b128 v[226:229], v161 offset:56320
	global_load_lds_dwordx4 v[156:157], off
	s_add_i32 m0, s48, 0x2000
	s_add_u32 s46, s46, 0x100080
	v_lshl_add_u64 v[156:157], v[230:231], 0, s[10:11]
	s_addc_u32 s47, s47, 0
	s_add_i32 s48, s82, s55
	global_load_lds_dwordx4 v[156:157], off
	v_lshl_add_u64 v[156:157], s[46:47], 0, v[132:133]
	s_mov_b32 m0, s48
	s_nop 0
	global_load_lds_dwordx4 v[156:157], off
	v_lshl_add_u64 v[156:157], s[46:47], 0, v[136:137]
	s_add_i32 m0, s48, 0x2000
	s_nop 0
	global_load_lds_dwordx4 v[156:157], off
	v_lshl_add_u64 v[156:157], v[232:233], 0, s[10:11]
	s_mov_b32 m0, s70
	s_nop 0
	global_load_lds_dwordx4 v[156:157], off
	v_lshl_add_u64 v[156:157], v[234:235], 0, s[10:11]
	s_mov_b32 m0, s71
	s_nop 0
	global_load_lds_dwordx4 v[156:157], off
	s_waitcnt vmcnt(8)
	s_waitcnt lgkmcnt(0)
	s_nop 0
	s_setprio 1
	s_barrier
	v_mfma_f32_16x16x32_bf16 v[62:65], v[152:155], v[198:201], v[62:65]
	v_mfma_f32_16x16x32_bf16 v[58:61], v[172:175], v[198:201], v[58:61]
	v_mfma_f32_16x16x32_bf16 v[46:49], v[152:155], v[206:209], v[46:49]
	v_mfma_f32_16x16x32_bf16 v[42:45], v[172:175], v[206:209], v[42:45]
	v_mfma_f32_16x16x32_bf16 v[30:33], v[152:155], v[214:217], v[30:33]
	v_mfma_f32_16x16x32_bf16 v[26:29], v[172:175], v[214:217], v[26:29]
	v_mfma_f32_16x16x32_bf16 v[14:17], v[152:155], v[222:225], v[14:17]
	v_mfma_f32_16x16x32_bf16 v[10:13], v[172:175], v[222:225], v[10:13]
	v_mfma_f32_16x16x32_bf16 v[62:65], v[168:171], v[202:205], v[62:65]
	v_mfma_f32_16x16x32_bf16 v[58:61], v[176:179], v[202:205], v[58:61]
	v_mfma_f32_16x16x32_bf16 v[46:49], v[168:171], v[210:213], v[46:49]
	v_mfma_f32_16x16x32_bf16 v[42:45], v[176:179], v[210:213], v[42:45]
	v_mfma_f32_16x16x32_bf16 v[30:33], v[168:171], v[218:221], v[30:33]
	v_mfma_f32_16x16x32_bf16 v[26:29], v[176:179], v[218:221], v[26:29]
	v_mfma_f32_16x16x32_bf16 v[14:17], v[168:171], v[226:229], v[14:17]
	v_mfma_f32_16x16x32_bf16 v[10:13], v[176:179], v[226:229], v[10:13]
	s_setprio 0
	s_setprio 1
	v_mfma_f32_16x16x32_bf16 v[54:57], v[180:183], v[198:201], v[54:57]
	v_mfma_f32_16x16x32_bf16 v[50:53], v[188:191], v[198:201], v[50:53]
	v_mfma_f32_16x16x32_bf16 v[38:41], v[180:183], v[206:209], v[38:41]
	v_mfma_f32_16x16x32_bf16 v[34:37], v[188:191], v[206:209], v[34:37]
	v_mfma_f32_16x16x32_bf16 v[22:25], v[180:183], v[214:217], v[22:25]
	v_mfma_f32_16x16x32_bf16 v[18:21], v[188:191], v[214:217], v[18:21]
	v_mfma_f32_16x16x32_bf16 v[6:9], v[180:183], v[222:225], v[6:9]
	v_mfma_f32_16x16x32_bf16 v[2:5], v[188:191], v[222:225], v[2:5]
	v_mfma_f32_16x16x32_bf16 v[54:57], v[184:187], v[202:205], v[54:57]
	v_mfma_f32_16x16x32_bf16 v[50:53], v[192:195], v[202:205], v[50:53]
	v_mfma_f32_16x16x32_bf16 v[38:41], v[184:187], v[210:213], v[38:41]
	v_mfma_f32_16x16x32_bf16 v[34:37], v[192:195], v[210:213], v[34:37]
	v_mfma_f32_16x16x32_bf16 v[22:25], v[184:187], v[218:221], v[22:25]
	v_mfma_f32_16x16x32_bf16 v[18:21], v[192:195], v[218:221], v[18:21]
	v_mfma_f32_16x16x32_bf16 v[6:9], v[184:187], v[226:229], v[6:9]
	v_mfma_f32_16x16x32_bf16 v[2:5], v[192:195], v[226:229], v[2:5]
	s_setprio 0
	s_barrier
	s_add_i32 s80, s80, 2
	s_add_u32 s44, s44, 0x100
	s_addc_u32 s45, s45, 0
	s_add_u32 s78, s78, 0x100
	s_addc_u32 s79, s79, 0
	s_cmp_gt_u32 s80, 61
	.p2align	3
.LBB0_217:
	ds_read_b128 v[152:155], v159
	ds_read_b128 v[168:171], v159 offset:1024
	ds_read_b128 v[172:175], v159 offset:2048
	ds_read_b128 v[176:179], v159 offset:3072
	ds_read_b128 v[180:183], v160
	ds_read_b128 v[184:187], v160 offset:1024
	ds_read_b128 v[188:191], v160 offset:2048
	ds_read_b128 v[192:195], v160 offset:3072
	s_add_u32 s46, s44, 0xfff00080
	s_addc_u32 s47, s45, -1
	s_cmp_eq_u32 s80, 60
	s_cselect_b32 s49, s3, s47
	s_cselect_b32 s48, s35, s46
	s_cselect_b32 s47, s17, s79
	s_cselect_b32 s46, s43, s78
	v_lshl_add_u64 v[156:157], s[44:45], 0, v[144:145]
	s_add_i32 m0, s56, 0xc000
	ds_read_b128 v[198:201], v161
	ds_read_b128 v[202:205], v161 offset:1024
	ds_read_b128 v[206:209], v161 offset:2048
	ds_read_b128 v[210:213], v161 offset:3072
	ds_read_b128 v[214:217], v161 offset:4096
	ds_read_b128 v[218:221], v161 offset:5120
	ds_read_b128 v[222:225], v161 offset:6144
	ds_read_b128 v[226:229], v161 offset:7168
	global_load_lds_dwordx4 v[156:157], off
	v_lshl_add_u64 v[156:157], s[44:45], 0, v[146:147]
	s_add_i32 m0, s56, 0xe000
	s_nop 0
	global_load_lds_dwordx4 v[156:157], off
	s_waitcnt vmcnt(8)
	s_waitcnt lgkmcnt(0)
	s_nop 0
	s_setprio 1
	s_barrier
; #define PG8_STAGE(bufoff, gbase, voff) do { _Pragma("unroll") for (int _i = 0; _i < 2; ++_i) \
;         __builtin_amdgcn_global_load_lds((const unsigned*)((const char*)(gbase) + (voff)[_i]), (PG8_LAS unsigned*)(lds + (bufoff) + ldsw + _i * 8192), 16, 0, 0); } while (0)
; #define PG8_LDA(dst, b, h) do { _Pragma("unroll") for (int m = 0; m < 4; ++m) _Pragma("unroll") for (int k = 0; k < 2; ++k) dst[m][k] = *(const PG8_LAS bf16x8*)(lds + PG8_SA(b, h) + aoff + m * 2048 + k * 1024); } while (0)
; #define PG8_MMA(ai, bj, At, Bt) do { __builtin_amdgcn_s_setprio(1); _Pragma("unroll") for (int m = 0; m < 4; ++m) _Pragma("unroll") for (int n = 0; n < 2; ++n) _Pragma("unroll") for (int k = 0; k < 2; ++k) \
;         acc[ai][bj][m][n] = __builtin_amdgcn_mfma_f32_16x16x32_bf16(Bt[n][k], At[m][k], acc[ai][bj][m][n], 0, 0, 0); __builtin_amdgcn_s_setprio(0); } while (0)
; #define PG8_WAIT_V(n) asm volatile("s_waitcnt vmcnt(" #n ")" ::: "memory")
; #define PG8_WAIT_L(n) asm volatile("s_waitcnt lgkmcnt(" #n ")" ::: "memory")
; #define PG8_BAR __builtin_amdgcn_s_barrier()
; #define PG8_SCHED __builtin_amdgcn_sched_barrier(0)
; template <class Epi, class Sched, bool ALIGN_EPI = false, bool SP2 = false>
; __device__ __forceinline__ void gemm_phase(PG8_LAS unsigned char* lds, const Gemm g, const Sched& S, const Epi& E) {
;     ...
;             PG8_WAIT_V(8); PG8_WAIT_L(0); PG8_BAR; PG8_MMA(0, 0, At, B0); PG8_MMA(0, 1, At, B1); PG8_BAR; PG8_SCHED;
;             PG8_LDA(At, 0, 1); PG8_STAGE(PG8_SB(0, 0), b2, voffB); PG8_STAGE(PG8_SB(0, 1), b2 + hstep, voffB); PG8_STAGE(PG8_SA(0, 0), a2, voffA);
;             PG8_WAIT_V(8); PG8_WAIT_L(0); PG8_BAR; PG8_MMA(1, 0, At, B0); PG8_MMA(1, 1, At, B1); PG8_BAR; PG8_SCHED;
	v_mfma_f32_16x16x32_bf16 v[126:129], v[152:155], v[198:201], v[126:129]
	v_mfma_f32_16x16x32_bf16 v[122:125], v[172:175], v[198:201], v[122:125]
	v_mfma_f32_16x16x32_bf16 v[110:113], v[152:155], v[206:209], v[110:113]
	v_mfma_f32_16x16x32_bf16 v[106:109], v[172:175], v[206:209], v[106:109]
	v_mfma_f32_16x16x32_bf16 v[94:97], v[152:155], v[214:217], v[94:97]
	v_mfma_f32_16x16x32_bf16 v[90:93], v[172:175], v[214:217], v[90:93]
	v_mfma_f32_16x16x32_bf16 v[78:81], v[152:155], v[222:225], v[78:81]
	v_mfma_f32_16x16x32_bf16 v[74:77], v[172:175], v[222:225], v[74:77]
	v_mfma_f32_16x16x32_bf16 v[126:129], v[168:171], v[202:205], v[126:129]
	v_mfma_f32_16x16x32_bf16 v[122:125], v[176:179], v[202:205], v[122:125]
	v_mfma_f32_16x16x32_bf16 v[110:113], v[168:171], v[210:213], v[110:113]
	v_mfma_f32_16x16x32_bf16 v[106:109], v[176:179], v[210:213], v[106:109]
	v_mfma_f32_16x16x32_bf16 v[94:97], v[168:171], v[218:221], v[94:97]
	v_mfma_f32_16x16x32_bf16 v[90:93], v[176:179], v[218:221], v[90:93]
	v_mfma_f32_16x16x32_bf16 v[78:81], v[168:171], v[226:229], v[78:81]
	v_mfma_f32_16x16x32_bf16 v[74:77], v[176:179], v[226:229], v[74:77]
	s_setprio 0
	s_setprio 1
	v_mfma_f32_16x16x32_bf16 v[118:121], v[180:183], v[198:201], v[118:121]
	v_mfma_f32_16x16x32_bf16 v[114:117], v[188:191], v[198:201], v[114:117]
	v_mfma_f32_16x16x32_bf16 v[102:105], v[180:183], v[206:209], v[102:105]
	v_mfma_f32_16x16x32_bf16 v[98:101], v[188:191], v[206:209], v[98:101]
	v_mfma_f32_16x16x32_bf16 v[86:89], v[180:183], v[214:217], v[86:89]
	v_mfma_f32_16x16x32_bf16 v[82:85], v[188:191], v[214:217], v[82:85]
	v_mfma_f32_16x16x32_bf16 v[70:73], v[180:183], v[222:225], v[70:73]
	v_mfma_f32_16x16x32_bf16 v[66:69], v[188:191], v[222:225], v[66:69]
	v_mfma_f32_16x16x32_bf16 v[118:121], v[184:187], v[202:205], v[118:121]
	v_mfma_f32_16x16x32_bf16 v[114:117], v[192:195], v[202:205], v[114:117]
	v_mfma_f32_16x16x32_bf16 v[102:105], v[184:187], v[210:213], v[102:105]
	v_mfma_f32_16x16x32_bf16 v[98:101], v[192:195], v[210:213], v[98:101]
	v_mfma_f32_16x16x32_bf16 v[86:89], v[184:187], v[218:221], v[86:89]
	v_mfma_f32_16x16x32_bf16 v[82:85], v[192:195], v[218:221], v[82:85]
	v_mfma_f32_16x16x32_bf16 v[70:73], v[184:187], v[226:229], v[70:73]
	v_mfma_f32_16x16x32_bf16 v[66:69], v[192:195], v[226:229], v[66:69]
	s_setprio 0
	s_barrier
	s_add_i32 s81, s73, s55
	v_lshl_add_u64 v[156:157], s[46:47], 0, v[132:133]
	s_mov_b32 m0, s81
	ds_read_b128 v[198:201], v161 offset:16384
	ds_read_b128 v[202:205], v161 offset:17408
	ds_read_b128 v[206:209], v161 offset:18432
	ds_read_b128 v[210:213], v161 offset:19456
	ds_read_b128 v[214:217], v161 offset:20480
	ds_read_b128 v[218:221], v161 offset:21504
	ds_read_b128 v[222:225], v161 offset:22528
	ds_read_b128 v[226:229], v161 offset:23552
	global_load_lds_dwordx4 v[156:157], off
	s_add_i32 m0, s81, 0x2000
	s_add_u32 s82, s46, 0x100000
	v_lshl_add_u64 v[230:231], s[46:47], 0, v[136:137]
	s_addc_u32 s83, s47, 0
	s_add_i32 s81, s74, s55
	global_load_lds_dwordx4 v[230:231], off
	v_lshl_add_u64 v[232:233], s[82:83], 0, v[132:133]
	s_mov_b32 m0, s81
	v_lshl_add_u64 v[234:235], s[48:49], 0, v[134:135]
	global_load_lds_dwordx4 v[232:233], off
	v_lshl_add_u64 v[232:233], s[82:83], 0, v[136:137]
	s_add_i32 m0, s81, 0x2000
	s_nop 0
	global_load_lds_dwordx4 v[232:233], off
	v_lshl_add_u64 v[232:233], s[48:49], 0, v[130:131]
	s_mov_b32 m0, s56
	s_nop 0
	global_load_lds_dwordx4 v[232:233], off
	s_mov_b32 m0, s57
	s_nop 0
	global_load_lds_dwordx4 v[234:235], off
	s_waitcnt vmcnt(8)
	s_waitcnt lgkmcnt(0)
	s_nop 0
	s_setprio 1
	s_barrier
	v_mfma_f32_16x16x32_bf16 v[62:65], v[152:155], v[198:201], v[62:65]
	v_mfma_f32_16x16x32_bf16 v[58:61], v[172:175], v[198:201], v[58:61]
	v_mfma_f32_16x16x32_bf16 v[46:49], v[152:155], v[206:209], v[46:49]
	v_mfma_f32_16x16x32_bf16 v[42:45], v[172:175], v[206:209], v[42:45]
	v_mfma_f32_16x16x32_bf16 v[30:33], v[152:155], v[214:217], v[30:33]
	v_mfma_f32_16x16x32_bf16 v[26:29], v[172:175], v[214:217], v[26:29]
	v_mfma_f32_16x16x32_bf16 v[14:17], v[152:155], v[222:225], v[14:17]
	v_mfma_f32_16x16x32_bf16 v[10:13], v[172:175], v[222:225], v[10:13]
	v_mfma_f32_16x16x32_bf16 v[62:65], v[168:171], v[202:205], v[62:65]
	v_mfma_f32_16x16x32_bf16 v[58:61], v[176:179], v[202:205], v[58:61]
	v_mfma_f32_16x16x32_bf16 v[46:49], v[168:171], v[210:213], v[46:49]
	v_mfma_f32_16x16x32_bf16 v[42:45], v[176:179], v[210:213], v[42:45]
	v_mfma_f32_16x16x32_bf16 v[30:33], v[168:171], v[218:221], v[30:33]
	v_mfma_f32_16x16x32_bf16 v[26:29], v[176:179], v[218:221], v[26:29]
	v_mfma_f32_16x16x32_bf16 v[14:17], v[168:171], v[226:229], v[14:17]
	v_mfma_f32_16x16x32_bf16 v[10:13], v[176:179], v[226:229], v[10:13]
	s_setprio 0
	s_setprio 1
	v_mfma_f32_16x16x32_bf16 v[54:57], v[180:183], v[198:201], v[54:57]
	v_mfma_f32_16x16x32_bf16 v[50:53], v[188:191], v[198:201], v[50:53]
	v_mfma_f32_16x16x32_bf16 v[38:41], v[180:183], v[206:209], v[38:41]
	v_mfma_f32_16x16x32_bf16 v[34:37], v[188:191], v[206:209], v[34:37]
	v_mfma_f32_16x16x32_bf16 v[22:25], v[180:183], v[214:217], v[22:25]
	v_mfma_f32_16x16x32_bf16 v[18:21], v[188:191], v[214:217], v[18:21]
	v_mfma_f32_16x16x32_bf16 v[6:9], v[180:183], v[222:225], v[6:9]
	v_mfma_f32_16x16x32_bf16 v[2:5], v[188:191], v[222:225], v[2:5]
	v_mfma_f32_16x16x32_bf16 v[54:57], v[184:187], v[202:205], v[54:57]
	v_mfma_f32_16x16x32_bf16 v[50:53], v[192:195], v[202:205], v[50:53]
	v_mfma_f32_16x16x32_bf16 v[38:41], v[184:187], v[210:213], v[38:41]
	v_mfma_f32_16x16x32_bf16 v[34:37], v[192:195], v[210:213], v[34:37]
	v_mfma_f32_16x16x32_bf16 v[22:25], v[184:187], v[218:221], v[22:25]
	v_mfma_f32_16x16x32_bf16 v[18:21], v[192:195], v[218:221], v[18:21]
	v_mfma_f32_16x16x32_bf16 v[6:9], v[184:187], v[226:229], v[6:9]
	v_mfma_f32_16x16x32_bf16 v[2:5], v[192:195], v[226:229], v[2:5]
	s_setprio 0
	s_barrier
; #define PG8_STAGE(bufoff, gbase, voff) do { _Pragma("unroll") for (int _i = 0; _i < 2; ++_i) \
;         __builtin_amdgcn_global_load_lds((const unsigned*)((const char*)(gbase) + (voff)[_i]), (PG8_LAS unsigned*)(lds + (bufoff) + ldsw + _i * 8192), 16, 0, 0); } while (0)
; #define PG8_LDA(dst, b, h) do { _Pragma("unroll") for (int m = 0; m < 4; ++m) _Pragma("unroll") for (int k = 0; k < 2; ++k) dst[m][k] = *(const PG8_LAS bf16x8*)(lds + PG8_SA(b, h) + aoff + m * 2048 + k * 1024); } while (0)
; #define PG8_LDB(dst, b, h) do { _Pragma("unroll") for (int n = 0; n < 2; ++n) _Pragma("unroll") for (int k = 0; k < 2; ++k) dst[n][k] = *(const PG8_LAS bf16x8*)(lds + PG8_SB(b, h) + boff + n * 2048 + k * 1024); } while (0)
; #define PG8_MMA(ai, bj, At, Bt) do { __builtin_amdgcn_s_setprio(1); _Pragma("unroll") for (int m = 0; m < 4; ++m) _Pragma("unroll") for (int n = 0; n < 2; ++n) _Pragma("unroll") for (int k = 0; k < 2; ++k) \
;         acc[ai][bj][m][n] = __builtin_amdgcn_mfma_f32_16x16x32_bf16(Bt[n][k], At[m][k], acc[ai][bj][m][n], 0, 0, 0); __builtin_amdgcn_s_setprio(0); } while (0)
; #define PG8_WAIT_V(n) asm volatile("s_waitcnt vmcnt(" #n ")" ::: "memory")
; #define PG8_WAIT_L(n) asm volatile("s_waitcnt lgkmcnt(" #n ")" ::: "memory")
; #define PG8_BAR __builtin_amdgcn_s_barrier()
; #define PG8_SCHED __builtin_amdgcn_sched_barrier(0)
; template <class Epi, class Sched, bool ALIGN_EPI = false, bool SP2 = false>
; __device__ __forceinline__ void gemm_phase(PG8_LAS unsigned char* lds, const Gemm g, const Sched& S, const Epi& E) {
;     ...
;             PG8_LDB(B0, 1, 0); PG8_LDB(B1, 1, 1); PG8_SCHED; PG8_LDA(At, 1, 0); PG8_STAGE(PG8_SA(0, 1), a2 + hstep, voffA);
;             PG8_WAIT_V(8); PG8_WAIT_L(0); PG8_BAR; PG8_MMA(0, 0, At, B0); PG8_MMA(0, 1, At, B1); PG8_BAR; PG8_SCHED;
	s_add_i32 s81, 0, 0x18000
	v_add_u32_e32 v149, s81, v164
	s_add_i32 s82, 0, 0x1c000
	ds_read_b128 v[152:155], v149
	ds_read_b128 v[168:171], v149 offset:1024
	ds_read_b128 v[172:175], v149 offset:2048
	ds_read_b128 v[176:179], v149 offset:3072
	v_add_u32_e32 v149, s82, v164
	ds_read_b128 v[180:183], v149
	ds_read_b128 v[184:187], v149 offset:1024
	ds_read_b128 v[188:191], v149 offset:2048
	ds_read_b128 v[192:195], v149 offset:3072
	s_add_u32 s48, s48, 0x100000
	s_addc_u32 s49, s49, 0
	s_mov_b32 m0, s58
	v_lshl_add_u64 v[236:237], s[48:49], 0, v[130:131]
	ds_read_b128 v[198:201], v161 offset:32768
	ds_read_b128 v[202:205], v161 offset:33792
	ds_read_b128 v[206:209], v161 offset:34816
	ds_read_b128 v[210:213], v161 offset:35840
	ds_read_b128 v[214:217], v161 offset:36864
	ds_read_b128 v[218:221], v161 offset:37888
	ds_read_b128 v[222:225], v161 offset:38912
	ds_read_b128 v[226:229], v161 offset:39936
	global_load_lds_dwordx4 v[236:237], off
	v_lshl_add_u64 v[236:237], s[48:49], 0, v[134:135]
	s_mov_b32 m0, s59
	s_nop 0
	global_load_lds_dwordx4 v[236:237], off
	s_waitcnt vmcnt(8)
	s_waitcnt lgkmcnt(0)
	s_nop 0
	s_setprio 1
	s_barrier
	v_mfma_f32_16x16x32_bf16 v[126:129], v[152:155], v[198:201], v[126:129]
	v_mfma_f32_16x16x32_bf16 v[122:125], v[172:175], v[198:201], v[122:125]
	v_mfma_f32_16x16x32_bf16 v[110:113], v[152:155], v[206:209], v[110:113]
	v_mfma_f32_16x16x32_bf16 v[106:109], v[172:175], v[206:209], v[106:109]
	v_mfma_f32_16x16x32_bf16 v[94:97], v[152:155], v[214:217], v[94:97]
	v_mfma_f32_16x16x32_bf16 v[90:93], v[172:175], v[214:217], v[90:93]
	v_mfma_f32_16x16x32_bf16 v[78:81], v[152:155], v[222:225], v[78:81]
	v_mfma_f32_16x16x32_bf16 v[74:77], v[172:175], v[222:225], v[74:77]
	v_mfma_f32_16x16x32_bf16 v[126:129], v[168:171], v[202:205], v[126:129]
	v_mfma_f32_16x16x32_bf16 v[122:125], v[176:179], v[202:205], v[122:125]
	v_mfma_f32_16x16x32_bf16 v[110:113], v[168:171], v[210:213], v[110:113]
	v_mfma_f32_16x16x32_bf16 v[106:109], v[176:179], v[210:213], v[106:109]
	v_mfma_f32_16x16x32_bf16 v[94:97], v[168:171], v[218:221], v[94:97]
	v_mfma_f32_16x16x32_bf16 v[90:93], v[176:179], v[218:221], v[90:93]
	v_mfma_f32_16x16x32_bf16 v[78:81], v[168:171], v[226:229], v[78:81]
	v_mfma_f32_16x16x32_bf16 v[74:77], v[176:179], v[226:229], v[74:77]
	s_setprio 0
	s_setprio 1
	v_mfma_f32_16x16x32_bf16 v[118:121], v[180:183], v[198:201], v[118:121]
	v_mfma_f32_16x16x32_bf16 v[114:117], v[188:191], v[198:201], v[114:117]
	v_mfma_f32_16x16x32_bf16 v[102:105], v[180:183], v[206:209], v[102:105]
	v_mfma_f32_16x16x32_bf16 v[98:101], v[188:191], v[206:209], v[98:101]
	v_mfma_f32_16x16x32_bf16 v[86:89], v[180:183], v[214:217], v[86:89]
	v_mfma_f32_16x16x32_bf16 v[82:85], v[188:191], v[214:217], v[82:85]
	v_mfma_f32_16x16x32_bf16 v[70:73], v[180:183], v[222:225], v[70:73]
	v_mfma_f32_16x16x32_bf16 v[66:69], v[188:191], v[222:225], v[66:69]
	v_mfma_f32_16x16x32_bf16 v[118:121], v[184:187], v[202:205], v[118:121]
	v_mfma_f32_16x16x32_bf16 v[114:117], v[192:195], v[202:205], v[114:117]
	v_mfma_f32_16x16x32_bf16 v[102:105], v[184:187], v[210:213], v[102:105]
	v_mfma_f32_16x16x32_bf16 v[98:101], v[192:195], v[210:213], v[98:101]
	v_mfma_f32_16x16x32_bf16 v[86:89], v[184:187], v[218:221], v[86:89]
	v_mfma_f32_16x16x32_bf16 v[82:85], v[192:195], v[218:221], v[82:85]
	v_mfma_f32_16x16x32_bf16 v[70:73], v[184:187], v[226:229], v[70:73]
	v_mfma_f32_16x16x32_bf16 v[66:69], v[192:195], v[226:229], v[66:69]
	s_setprio 0
	s_barrier
; #define PG8_STAGE(bufoff, gbase, voff) do { _Pragma("unroll") for (int _i = 0; _i < 2; ++_i) \
;         __builtin_amdgcn_global_load_lds((const unsigned*)((const char*)(gbase) + (voff)[_i]), (PG8_LAS unsigned*)(lds + (bufoff) + ldsw + _i * 8192), 16, 0, 0); } while (0)
; #define PG8_LDA(dst, b, h) do { _Pragma("unroll") for (int m = 0; m < 4; ++m) _Pragma("unroll") for (int k = 0; k < 2; ++k) dst[m][k] = *(const PG8_LAS bf16x8*)(lds + PG8_SA(b, h) + aoff + m * 2048 + k * 1024); } while (0)
; #define PG8_MMA(ai, bj, At, Bt) do { __builtin_amdgcn_s_setprio(1); _Pragma("unroll") for (int m = 0; m < 4; ++m) _Pragma("unroll") for (int n = 0; n < 2; ++n) _Pragma("unroll") for (int k = 0; k < 2; ++k) \
;         acc[ai][bj][m][n] = __builtin_amdgcn_mfma_f32_16x16x32_bf16(Bt[n][k], At[m][k], acc[ai][bj][m][n], 0, 0, 0); __builtin_amdgcn_s_setprio(0); } while (0)
; #define PG8_WAIT_V(n) asm volatile("s_waitcnt vmcnt(" #n ")" ::: "memory")
; #define PG8_WAIT_L(n) asm volatile("s_waitcnt lgkmcnt(" #n ")" ::: "memory")
; #define PG8_BAR __builtin_amdgcn_s_barrier()
; #define PG8_SCHED __builtin_amdgcn_sched_barrier(0)
; template <class Epi, class Sched, bool ALIGN_EPI = false, bool SP2 = false>
; __device__ __forceinline__ void gemm_phase(PG8_LAS unsigned char* lds, const Gemm g, const Sched& S, const Epi& E) {
;     ...
;             PG8_LDA(At, 1, 1); PG8_STAGE(PG8_SB(1, 0), b3, voffB); PG8_STAGE(PG8_SB(1, 1), b3 + hstep, voffB); PG8_STAGE(PG8_SA(1, 0), a3, voffA);
;             PG8_WAIT_V(8); PG8_WAIT_L(0); PG8_BAR; PG8_MMA(1, 0, At, B0); PG8_MMA(1, 1, At, B1); PG8_BAR; PG8_SCHED;
;     ...
;         if constexpr (ALIGN_EPI) { if (wr == 0) PG8_BAR; }
	s_add_i32 s48, s81, s55
	v_lshl_add_u64 v[156:157], v[156:157], 0, s[10:11]
	s_mov_b32 m0, s48
	ds_read_b128 v[198:201], v161 offset:49152
	ds_read_b128 v[202:205], v161 offset:50176
	ds_read_b128 v[206:209], v161 offset:51200
	ds_read_b128 v[210:213], v161 offset:52224
	ds_read_b128 v[214:217], v161 offset:53248
	ds_read_b128 v[218:221], v161 offset:54272
	ds_read_b128 v[222:225], v161 offset:55296
	ds_read_b128 v[226:229], v161 offset:56320
	global_load_lds_dwordx4 v[156:157], off
	s_add_i32 m0, s48, 0x2000
	s_add_u32 s46, s46, 0x100080
	v_lshl_add_u64 v[156:157], v[230:231], 0, s[10:11]
	s_addc_u32 s47, s47, 0
	s_add_i32 s48, s82, s55
	global_load_lds_dwordx4 v[156:157], off
	v_lshl_add_u64 v[156:157], s[46:47], 0, v[132:133]
	s_mov_b32 m0, s48
	s_nop 0
	global_load_lds_dwordx4 v[156:157], off
	v_lshl_add_u64 v[156:157], s[46:47], 0, v[136:137]
	s_add_i32 m0, s48, 0x2000
	s_nop 0
	global_load_lds_dwordx4 v[156:157], off
	v_lshl_add_u64 v[156:157], v[232:233], 0, s[10:11]
	s_mov_b32 m0, s70
	s_nop 0
	global_load_lds_dwordx4 v[156:157], off
	v_lshl_add_u64 v[156:157], v[234:235], 0, s[10:11]
	s_mov_b32 m0, s71
	s_nop 0
	global_load_lds_dwordx4 v[156:157], off
	s_waitcnt vmcnt(8)
	s_waitcnt lgkmcnt(0)
	s_nop 0
	s_setprio 1
	s_barrier
	v_mfma_f32_16x16x32_bf16 v[62:65], v[152:155], v[198:201], v[62:65]
	v_mfma_f32_16x16x32_bf16 v[58:61], v[172:175], v[198:201], v[58:61]
	v_mfma_f32_16x16x32_bf16 v[46:49], v[152:155], v[206:209], v[46:49]
	v_mfma_f32_16x16x32_bf16 v[42:45], v[172:175], v[206:209], v[42:45]
	v_mfma_f32_16x16x32_bf16 v[30:33], v[152:155], v[214:217], v[30:33]
	v_mfma_f32_16x16x32_bf16 v[26:29], v[172:175], v[214:217], v[26:29]
	v_mfma_f32_16x16x32_bf16 v[14:17], v[152:155], v[222:225], v[14:17]
	v_mfma_f32_16x16x32_bf16 v[10:13], v[172:175], v[222:225], v[10:13]
	v_mfma_f32_16x16x32_bf16 v[62:65], v[168:171], v[202:205], v[62:65]
	v_mfma_f32_16x16x32_bf16 v[58:61], v[176:179], v[202:205], v[58:61]
	v_mfma_f32_16x16x32_bf16 v[46:49], v[168:171], v[210:213], v[46:49]
	v_mfma_f32_16x16x32_bf16 v[42:45], v[176:179], v[210:213], v[42:45]
	v_mfma_f32_16x16x32_bf16 v[30:33], v[168:171], v[218:221], v[30:33]
	v_mfma_f32_16x16x32_bf16 v[26:29], v[176:179], v[218:221], v[26:29]
	v_mfma_f32_16x16x32_bf16 v[14:17], v[168:171], v[226:229], v[14:17]
	v_mfma_f32_16x16x32_bf16 v[10:13], v[176:179], v[226:229], v[10:13]
	s_setprio 0
	s_setprio 1
	v_mfma_f32_16x16x32_bf16 v[54:57], v[180:183], v[198:201], v[54:57]
	v_mfma_f32_16x16x32_bf16 v[50:53], v[188:191], v[198:201], v[50:53]
	v_mfma_f32_16x16x32_bf16 v[38:41], v[180:183], v[206:209], v[38:41]
	v_mfma_f32_16x16x32_bf16 v[34:37], v[188:191], v[206:209], v[34:37]
	v_mfma_f32_16x16x32_bf16 v[22:25], v[180:183], v[214:217], v[22:25]
	v_mfma_f32_16x16x32_bf16 v[18:21], v[188:191], v[214:217], v[18:21]
	v_mfma_f32_16x16x32_bf16 v[6:9], v[180:183], v[222:225], v[6:9]
	v_mfma_f32_16x16x32_bf16 v[2:5], v[188:191], v[222:225], v[2:5]
	v_mfma_f32_16x16x32_bf16 v[54:57], v[184:187], v[202:205], v[54:57]
	v_mfma_f32_16x16x32_bf16 v[50:53], v[192:195], v[202:205], v[50:53]
	v_mfma_f32_16x16x32_bf16 v[38:41], v[184:187], v[210:213], v[38:41]
	v_mfma_f32_16x16x32_bf16 v[34:37], v[192:195], v[210:213], v[34:37]
	v_mfma_f32_16x16x32_bf16 v[22:25], v[184:187], v[218:221], v[22:25]
	v_mfma_f32_16x16x32_bf16 v[18:21], v[192:195], v[218:221], v[18:21]
	v_mfma_f32_16x16x32_bf16 v[6:9], v[184:187], v[226:229], v[6:9]
	v_mfma_f32_16x16x32_bf16 v[2:5], v[192:195], v[226:229], v[2:5]
	s_setprio 0
	s_barrier
	s_add_i32 s80, s80, 2
	s_add_u32 s44, s44, 0x100
	s_addc_u32 s45, s45, 0
	s_add_u32 s78, s78, 0x100
	s_addc_u32 s79, s79, 0
	s_cmp_gt_u32 s80, 61
	s_cbranch_scc0 .LBB0_217
	s_and_b64 vcc, exec, s[12:13]
	s_cbranch_vccz .LBB0_220
	s_barrier

; #define PG8_STAGE(bufoff, gbase, voff) do { _Pragma("unroll") for (int _i = 0; _i < 2; ++_i) \
;         __builtin_amdgcn_global_load_lds((const unsigned*)((const char*)(gbase) + (voff)[_i]), (PG8_LAS unsigned*)(lds + (bufoff) + ldsw + _i * 8192), 16, 0, 0); } while (0)
; #define PG8_LDA(dst, b, h) do { _Pragma("unroll") for (int m = 0; m < 4; ++m) _Pragma("unroll") for (int k = 0; k < 2; ++k) dst[m][k] = *(const PG8_LAS bf16x8*)(lds + PG8_SA(b, h) + aoff + m * 2048 + k * 1024); } while (0)
; #define PG8_LDB(dst, b, h) do { _Pragma("unroll") for (int n = 0; n < 2; ++n) _Pragma("unroll") for (int k = 0; k < 2; ++k) dst[n][k] = *(const PG8_LAS bf16x8*)(lds + PG8_SB(b, h) + boff + n * 2048 + k * 1024); } while (0)
; #define PG8_WAIT_V(n) asm volatile("s_waitcnt vmcnt(" #n ")" ::: "memory")
; #define PG8_WAIT_L(n) asm volatile("s_waitcnt lgkmcnt(" #n ")" ::: "memory")
; #define PG8_BAR __builtin_amdgcn_s_barrier()
; #define PG8_SCHED __builtin_amdgcn_sched_barrier(0)
; template <class Epi, class Sched, bool ALIGN_EPI = false, bool SP2 = false>
; __device__ __forceinline__ void gemm_phase(PG8_LAS unsigned char* lds, const Gemm g, const Sched& S, const Epi& E) {
;     ...
;         const char* nA = has_next ? (const char*)g.A + (size_t)nxt.pm * tstep : cA; const char* nB = has_next ? (const char*)g.Bt + (size_t)nxt.pn * tstep : cB;
;         for (int t = 0; t < nt; t += 2) {
;             const bool last = (t == nt - 2);
;             const char* a1 = cA + (size_t)(t + 1) * kstep;
;             const char* a2 = last ? nA : cA + (size_t)(t + 2) * kstep; const char* b2 = last ? nB : cB + (size_t)(t + 2) * kstep;
;             const char* a3 = a2 + kstep; const char* b3 = b2 + kstep;
;             if (last && has_next) S.a_ready(nxt);
;             if constexpr (SP2) {
;             PG8_LDB(B0, 0, 0); PG8_LDB(B1, 0, 1); PG8_SCHED; PG8_LDA(At, 0, 0); PG8_STAGE(PG8_SA(1, 1), a1 + hstep, voffA);
;             PG8_WAIT_V(8); PG8_WAIT_L(0); PG8_BAR; PG8_MMA(0, 0, At, B0); PG8_MMA(0, 1, At, B1); PG8_BAR; PG8_SCHED;
;             PG8_LDA(At, 0, 1); PG8_STAGE(PG8_SB(0, 0), b2, voffB); PG8_STAGE(PG8_SB(0, 1), b2 + hstep, voffB); PG8_STAGE(PG8_SA(0, 0), a2, voffA);
;             PG8_WAIT_V(8); PG8_WAIT_L(0); PG8_BAR; PG8_MMA(1, 0, At, B0); PG8_MMA(1, 1, At, B1); PG8_BAR; PG8_SCHED;
.LBB0_709:
	s_ashr_i32 s43, s42, 31
	s_lshl_b64 s[44:45], s[42:43], 21
	s_add_u32 s44, s19, s44
	s_addc_u32 s45, s21, s45
	s_and_b64 s[46:47], s[4:5], exec
	s_cselect_b32 s43, s45, s49
	s_cselect_b32 s72, s44, s48
	s_ashr_i32 s41, s40, 31
	s_lshl_b64 s[46:47], s[40:41], 21
	s_add_u32 s46, s54, s46
	s_addc_u32 s47, s55, s47
	s_and_b64 s[52:53], s[4:5], exec
	s_cselect_b32 s41, s47, s51
	s_cselect_b32 s73, s46, s50
	s_add_u32 s48, s48, 0x100080
	s_addc_u32 s49, s49, 0
	s_add_u32 s74, s50, 0x100
	s_addc_u32 s75, s51, 0
	s_mov_b32 s76, -2
	s_waitcnt lgkmcnt(0)
	.p2align	3
	ds_read_b128 v[146:149], v160
	ds_read_b128 v[164:167], v160 offset:1024
	ds_read_b128 v[168:171], v160 offset:2048
	ds_read_b128 v[172:175], v160 offset:3072
	ds_read_b128 v[176:179], v161
	ds_read_b128 v[180:183], v161 offset:1024
	ds_read_b128 v[184:187], v161 offset:2048
	ds_read_b128 v[188:191], v161 offset:3072
	s_add_u32 s50, s48, 0xfff00080
	s_addc_u32 s51, s49, -1
	s_cmp_eq_u32 s76, 60
	s_cselect_b32 s53, s43, s51
	s_cselect_b32 s52, s72, s50
	s_cselect_b32 s51, s41, s75
	s_cselect_b32 s50, s73, s74
	v_lshl_add_u64 v[226:227], s[48:49], 0, v[138:139]
	s_add_i32 m0, s9, 0xc000
	ds_read_b128 v[192:195], v162
	ds_read_b128 v[198:201], v162 offset:1024
	ds_read_b128 v[202:205], v162 offset:2048
	ds_read_b128 v[206:209], v162 offset:3072
	ds_read_b128 v[210:213], v162 offset:4096
	ds_read_b128 v[214:217], v162 offset:5120
	ds_read_b128 v[218:221], v162 offset:6144
	ds_read_b128 v[222:225], v162 offset:7168
	global_load_lds_dwordx4 v[226:227], off
	v_lshl_add_u64 v[226:227], s[48:49], 0, v[140:141]
	s_add_i32 m0, s9, 0xe000
	s_nop 0
	global_load_lds_dwordx4 v[226:227], off
	s_waitcnt vmcnt(8)
	s_waitcnt lgkmcnt(0)
	s_nop 0
	s_setprio 1
	s_barrier
	v_mfma_f32_16x16x32_bf16 v[126:129], v[146:149], v[192:195], 0
	v_mfma_f32_16x16x32_bf16 v[122:125], v[168:171], v[192:195], 0
	v_mfma_f32_16x16x32_bf16 v[110:113], v[146:149], v[202:205], 0
	v_mfma_f32_16x16x32_bf16 v[106:109], v[168:171], v[202:205], 0
	v_mfma_f32_16x16x32_bf16 v[94:97], v[146:149], v[210:213], 0
	v_mfma_f32_16x16x32_bf16 v[90:93], v[168:171], v[210:213], 0
	v_mfma_f32_16x16x32_bf16 v[78:81], v[146:149], v[218:221], 0
	v_mfma_f32_16x16x32_bf16 v[74:77], v[168:171], v[218:221], 0
	v_mfma_f32_16x16x32_bf16 v[126:129], v[164:167], v[198:201], v[126:129]
	v_mfma_f32_16x16x32_bf16 v[122:125], v[172:175], v[198:201], v[122:125]
	v_mfma_f32_16x16x32_bf16 v[110:113], v[164:167], v[206:209], v[110:113]
	v_mfma_f32_16x16x32_bf16 v[106:109], v[172:175], v[206:209], v[106:109]
	v_mfma_f32_16x16x32_bf16 v[94:97], v[164:167], v[214:217], v[94:97]
	v_mfma_f32_16x16x32_bf16 v[90:93], v[172:175], v[214:217], v[90:93]
	v_mfma_f32_16x16x32_bf16 v[78:81], v[164:167], v[222:225], v[78:81]
	v_mfma_f32_16x16x32_bf16 v[74:77], v[172:175], v[222:225], v[74:77]
	s_setprio 0
	s_setprio 1
	v_mfma_f32_16x16x32_bf16 v[118:121], v[176:179], v[192:195], 0
	v_mfma_f32_16x16x32_bf16 v[114:117], v[184:187], v[192:195], 0
	v_mfma_f32_16x16x32_bf16 v[102:105], v[176:179], v[202:205], 0
	v_mfma_f32_16x16x32_bf16 v[98:101], v[184:187], v[202:205], 0
	v_mfma_f32_16x16x32_bf16 v[86:89], v[176:179], v[210:213], 0
	v_mfma_f32_16x16x32_bf16 v[82:85], v[184:187], v[210:213], 0
	v_mfma_f32_16x16x32_bf16 v[70:73], v[176:179], v[218:221], 0
	v_mfma_f32_16x16x32_bf16 v[66:69], v[184:187], v[218:221], 0
	v_mfma_f32_16x16x32_bf16 v[118:121], v[180:183], v[198:201], v[118:121]
	v_mfma_f32_16x16x32_bf16 v[114:117], v[188:191], v[198:201], v[114:117]
	v_mfma_f32_16x16x32_bf16 v[102:105], v[180:183], v[206:209], v[102:105]
	v_mfma_f32_16x16x32_bf16 v[98:101], v[188:191], v[206:209], v[98:101]
	v_mfma_f32_16x16x32_bf16 v[86:89], v[180:183], v[214:217], v[86:89]
	v_mfma_f32_16x16x32_bf16 v[82:85], v[188:191], v[214:217], v[82:85]
	v_mfma_f32_16x16x32_bf16 v[70:73], v[180:183], v[222:225], v[70:73]
	v_mfma_f32_16x16x32_bf16 v[66:69], v[188:191], v[222:225], v[66:69]
	s_setprio 0
	s_barrier
	s_add_i32 s77, s69, s56
	v_lshl_add_u64 v[226:227], s[50:51], 0, v[132:133]
	s_mov_b32 m0, s77
	ds_read_b128 v[192:195], v162 offset:16384
	ds_read_b128 v[198:201], v162 offset:17408
	ds_read_b128 v[202:205], v162 offset:18432
	ds_read_b128 v[206:209], v162 offset:19456
	ds_read_b128 v[210:213], v162 offset:20480
	ds_read_b128 v[214:217], v162 offset:21504
	ds_read_b128 v[218:221], v162 offset:22528
	ds_read_b128 v[222:225], v162 offset:23552
	global_load_lds_dwordx4 v[226:227], off
	s_add_i32 m0, s77, 0x2000
	s_add_u32 s78, s50, 0x100000
	v_lshl_add_u64 v[228:229], s[50:51], 0, v[136:137]
	s_addc_u32 s79, s51, 0
	s_add_i32 s77, s70, s56
	global_load_lds_dwordx4 v[228:229], off
	v_lshl_add_u64 v[230:231], s[78:79], 0, v[132:133]
	s_mov_b32 m0, s77
	v_lshl_add_u64 v[232:233], s[52:53], 0, v[134:135]
	global_load_lds_dwordx4 v[230:231], off
	v_lshl_add_u64 v[230:231], s[78:79], 0, v[136:137]
	s_add_i32 m0, s77, 0x2000
	s_nop 0
	global_load_lds_dwordx4 v[230:231], off
	v_lshl_add_u64 v[230:231], s[52:53], 0, v[130:131]
	s_mov_b32 m0, s9
	s_nop 0
	global_load_lds_dwordx4 v[230:231], off
	s_mov_b32 m0, s57
	s_nop 0
	global_load_lds_dwordx4 v[232:233], off
	s_waitcnt vmcnt(8)
	s_waitcnt lgkmcnt(0)
	s_nop 0
	s_setprio 1
	s_barrier
; #define PG8_STAGE(bufoff, gbase, voff) do { _Pragma("unroll") for (int _i = 0; _i < 2; ++_i) \
;         __builtin_amdgcn_global_load_lds((const unsigned*)((const char*)(gbase) + (voff)[_i]), (PG8_LAS unsigned*)(lds + (bufoff) + ldsw + _i * 8192), 16, 0, 0); } while (0)
; #define PG8_LDA(dst, b, h) do { _Pragma("unroll") for (int m = 0; m < 4; ++m) _Pragma("unroll") for (int k = 0; k < 2; ++k) dst[m][k] = *(const PG8_LAS bf16x8*)(lds + PG8_SA(b, h) + aoff + m * 2048 + k * 1024); } while (0)
; #define PG8_LDB(dst, b, h) do { _Pragma("unroll") for (int n = 0; n < 2; ++n) _Pragma("unroll") for (int k = 0; k < 2; ++k) dst[n][k] = *(const PG8_LAS bf16x8*)(lds + PG8_SB(b, h) + boff + n * 2048 + k * 1024); } while (0)
; #define PG8_MMA(ai, bj, At, Bt) do { __builtin_amdgcn_s_setprio(1); _Pragma("unroll") for (int m = 0; m < 4; ++m) _Pragma("unroll") for (int n = 0; n < 2; ++n) _Pragma("unroll") for (int k = 0; k < 2; ++k) \
;         acc[ai][bj][m][n] = __builtin_amdgcn_mfma_f32_16x16x32_bf16(Bt[n][k], At[m][k], acc[ai][bj][m][n], 0, 0, 0); __builtin_amdgcn_s_setprio(0); } while (0)
; #define PG8_WAIT_V(n) asm volatile("s_waitcnt vmcnt(" #n ")" ::: "memory")
; #define PG8_WAIT_L(n) asm volatile("s_waitcnt lgkmcnt(" #n ")" ::: "memory")
; #define PG8_BAR __builtin_amdgcn_s_barrier()
; #define PG8_SCHED __builtin_amdgcn_sched_barrier(0)
; template <class Epi, class Sched, bool ALIGN_EPI = false, bool SP2 = false>
; __device__ __forceinline__ void gemm_phase(PG8_LAS unsigned char* lds, const Gemm g, const Sched& S, const Epi& E) {
;     ...
;             PG8_WAIT_V(8); PG8_WAIT_L(0); PG8_BAR; PG8_MMA(1, 0, At, B0); PG8_MMA(1, 1, At, B1); PG8_BAR; PG8_SCHED;
;             PG8_LDB(B0, 1, 0); PG8_LDB(B1, 1, 1); PG8_SCHED; PG8_LDA(At, 1, 0); PG8_STAGE(PG8_SA(0, 1), a2 + hstep, voffA);
;             PG8_WAIT_V(8); PG8_WAIT_L(0); PG8_BAR; PG8_MMA(0, 0, At, B0); PG8_MMA(0, 1, At, B1); PG8_BAR; PG8_SCHED;
	v_mfma_f32_16x16x32_bf16 v[62:65], v[146:149], v[192:195], 0
	v_mfma_f32_16x16x32_bf16 v[58:61], v[168:171], v[192:195], 0
	v_mfma_f32_16x16x32_bf16 v[46:49], v[146:149], v[202:205], 0
	v_mfma_f32_16x16x32_bf16 v[42:45], v[168:171], v[202:205], 0
	v_mfma_f32_16x16x32_bf16 v[30:33], v[146:149], v[210:213], 0
	v_mfma_f32_16x16x32_bf16 v[26:29], v[168:171], v[210:213], 0
	v_mfma_f32_16x16x32_bf16 v[14:17], v[146:149], v[218:221], 0
	v_mfma_f32_16x16x32_bf16 v[10:13], v[168:171], v[218:221], 0
	v_mfma_f32_16x16x32_bf16 v[62:65], v[164:167], v[198:201], v[62:65]
	v_mfma_f32_16x16x32_bf16 v[58:61], v[172:175], v[198:201], v[58:61]
	v_mfma_f32_16x16x32_bf16 v[46:49], v[164:167], v[206:209], v[46:49]
	v_mfma_f32_16x16x32_bf16 v[42:45], v[172:175], v[206:209], v[42:45]
	v_mfma_f32_16x16x32_bf16 v[30:33], v[164:167], v[214:217], v[30:33]
	v_mfma_f32_16x16x32_bf16 v[26:29], v[172:175], v[214:217], v[26:29]
	v_mfma_f32_16x16x32_bf16 v[14:17], v[164:167], v[222:225], v[14:17]
	v_mfma_f32_16x16x32_bf16 v[10:13], v[172:175], v[222:225], v[10:13]
	s_setprio 0
	s_setprio 1
	v_mfma_f32_16x16x32_bf16 v[54:57], v[176:179], v[192:195], 0
	v_mfma_f32_16x16x32_bf16 v[50:53], v[184:187], v[192:195], 0
	v_mfma_f32_16x16x32_bf16 v[38:41], v[176:179], v[202:205], 0
	v_mfma_f32_16x16x32_bf16 v[34:37], v[184:187], v[202:205], 0
	v_mfma_f32_16x16x32_bf16 v[22:25], v[176:179], v[210:213], 0
	v_mfma_f32_16x16x32_bf16 v[18:21], v[184:187], v[210:213], 0
	v_mfma_f32_16x16x32_bf16 v[6:9], v[176:179], v[218:221], 0
	v_mfma_f32_16x16x32_bf16 v[2:5], v[184:187], v[218:221], 0
	v_mfma_f32_16x16x32_bf16 v[54:57], v[180:183], v[198:201], v[54:57]
	v_mfma_f32_16x16x32_bf16 v[50:53], v[188:191], v[198:201], v[50:53]
	v_mfma_f32_16x16x32_bf16 v[38:41], v[180:183], v[206:209], v[38:41]
	v_mfma_f32_16x16x32_bf16 v[34:37], v[188:191], v[206:209], v[34:37]
	v_mfma_f32_16x16x32_bf16 v[22:25], v[180:183], v[214:217], v[22:25]
	v_mfma_f32_16x16x32_bf16 v[18:21], v[188:191], v[214:217], v[18:21]
	v_mfma_f32_16x16x32_bf16 v[6:9], v[180:183], v[222:225], v[6:9]
	v_mfma_f32_16x16x32_bf16 v[2:5], v[188:191], v[222:225], v[2:5]
	s_setprio 0
	s_barrier
	s_add_i32 s77, 0, 0x18000
	s_add_i32 s78, 0, 0x1c000
	v_add_u32_e32 v172, s77, v151
	v_add_u32_e32 v188, s78, v151
	ds_read_b128 v[146:149], v172
	ds_read_b128 v[164:167], v172 offset:1024
	ds_read_b128 v[168:171], v172 offset:2048
	ds_read_b128 v[172:175], v172 offset:3072
	ds_read_b128 v[176:179], v188
	ds_read_b128 v[180:183], v188 offset:1024
	ds_read_b128 v[184:187], v188 offset:2048
	ds_read_b128 v[188:191], v188 offset:3072
	s_add_u32 s52, s52, 0x100000
	s_addc_u32 s53, s53, 0
	s_mov_b32 m0, s58
	v_lshl_add_u64 v[234:235], s[52:53], 0, v[130:131]
	ds_read_b128 v[192:195], v162 offset:32768
	ds_read_b128 v[198:201], v162 offset:33792
	ds_read_b128 v[202:205], v162 offset:34816
	ds_read_b128 v[206:209], v162 offset:35840
	ds_read_b128 v[210:213], v162 offset:36864
	ds_read_b128 v[214:217], v162 offset:37888
	ds_read_b128 v[218:221], v162 offset:38912
	ds_read_b128 v[222:225], v162 offset:39936
	global_load_lds_dwordx4 v[234:235], off
	v_lshl_add_u64 v[234:235], s[52:53], 0, v[134:135]
	s_mov_b32 m0, s59
	s_nop 0
	global_load_lds_dwordx4 v[234:235], off
	s_waitcnt vmcnt(8)
	s_waitcnt lgkmcnt(0)
	s_nop 0
	s_setprio 1
	s_barrier
	v_mfma_f32_16x16x32_bf16 v[126:129], v[146:149], v[192:195], v[126:129]
	v_mfma_f32_16x16x32_bf16 v[122:125], v[168:171], v[192:195], v[122:125]
	v_mfma_f32_16x16x32_bf16 v[110:113], v[146:149], v[202:205], v[110:113]
	v_mfma_f32_16x16x32_bf16 v[106:109], v[168:171], v[202:205], v[106:109]
	v_mfma_f32_16x16x32_bf16 v[94:97], v[146:149], v[210:213], v[94:97]
	v_mfma_f32_16x16x32_bf16 v[90:93], v[168:171], v[210:213], v[90:93]
	v_mfma_f32_16x16x32_bf16 v[78:81], v[146:149], v[218:221], v[78:81]
	v_mfma_f32_16x16x32_bf16 v[74:77], v[168:171], v[218:221], v[74:77]
	v_mfma_f32_16x16x32_bf16 v[126:129], v[164:167], v[198:201], v[126:129]
	v_mfma_f32_16x16x32_bf16 v[122:125], v[172:175], v[198:201], v[122:125]
	v_mfma_f32_16x16x32_bf16 v[110:113], v[164:167], v[206:209], v[110:113]
	v_mfma_f32_16x16x32_bf16 v[106:109], v[172:175], v[206:209], v[106:109]
	v_mfma_f32_16x16x32_bf16 v[94:97], v[164:167], v[214:217], v[94:97]
	v_mfma_f32_16x16x32_bf16 v[90:93], v[172:175], v[214:217], v[90:93]
	v_mfma_f32_16x16x32_bf16 v[78:81], v[164:167], v[222:225], v[78:81]
	v_mfma_f32_16x16x32_bf16 v[74:77], v[172:175], v[222:225], v[74:77]
	s_setprio 0
	s_setprio 1
	v_mfma_f32_16x16x32_bf16 v[118:121], v[176:179], v[192:195], v[118:121]
	v_mfma_f32_16x16x32_bf16 v[114:117], v[184:187], v[192:195], v[114:117]
	v_mfma_f32_16x16x32_bf16 v[102:105], v[176:179], v[202:205], v[102:105]
	v_mfma_f32_16x16x32_bf16 v[98:101], v[184:187], v[202:205], v[98:101]
	v_mfma_f32_16x16x32_bf16 v[86:89], v[176:179], v[210:213], v[86:89]
	v_mfma_f32_16x16x32_bf16 v[82:85], v[184:187], v[210:213], v[82:85]
	v_mfma_f32_16x16x32_bf16 v[70:73], v[176:179], v[218:221], v[70:73]
	v_mfma_f32_16x16x32_bf16 v[66:69], v[184:187], v[218:221], v[66:69]
	v_mfma_f32_16x16x32_bf16 v[118:121], v[180:183], v[198:201], v[118:121]
	v_mfma_f32_16x16x32_bf16 v[114:117], v[188:191], v[198:201], v[114:117]
	v_mfma_f32_16x16x32_bf16 v[102:105], v[180:183], v[206:209], v[102:105]
	v_mfma_f32_16x16x32_bf16 v[98:101], v[188:191], v[206:209], v[98:101]
	v_mfma_f32_16x16x32_bf16 v[86:89], v[180:183], v[214:217], v[86:89]
	v_mfma_f32_16x16x32_bf16 v[82:85], v[188:191], v[214:217], v[82:85]
	v_mfma_f32_16x16x32_bf16 v[70:73], v[180:183], v[222:225], v[70:73]
	v_mfma_f32_16x16x32_bf16 v[66:69], v[188:191], v[222:225], v[66:69]
	s_setprio 0
	s_barrier
; #define PG8_STAGE(bufoff, gbase, voff) do { _Pragma("unroll") for (int _i = 0; _i < 2; ++_i) \
;         __builtin_amdgcn_global_load_lds((const unsigned*)((const char*)(gbase) + (voff)[_i]), (PG8_LAS unsigned*)(lds + (bufoff) + ldsw + _i * 8192), 16, 0, 0); } while (0)
; #define PG8_LDA(dst, b, h) do { _Pragma("unroll") for (int m = 0; m < 4; ++m) _Pragma("unroll") for (int k = 0; k < 2; ++k) dst[m][k] = *(const PG8_LAS bf16x8*)(lds + PG8_SA(b, h) + aoff + m * 2048 + k * 1024); } while (0)
; #define PG8_LDB(dst, b, h) do { _Pragma("unroll") for (int n = 0; n < 2; ++n) _Pragma("unroll") for (int k = 0; k < 2; ++k) dst[n][k] = *(const PG8_LAS bf16x8*)(lds + PG8_SB(b, h) + boff + n * 2048 + k * 1024); } while (0)
; #define PG8_MMA(ai, bj, At, Bt) do { __builtin_amdgcn_s_setprio(1); _Pragma("unroll") for (int m = 0; m < 4; ++m) _Pragma("unroll") for (int n = 0; n < 2; ++n) _Pragma("unroll") for (int k = 0; k < 2; ++k) \
;         acc[ai][bj][m][n] = __builtin_amdgcn_mfma_f32_16x16x32_bf16(Bt[n][k], At[m][k], acc[ai][bj][m][n], 0, 0, 0); __builtin_amdgcn_s_setprio(0); } while (0)
; #define PG8_WAIT_V(n) asm volatile("s_waitcnt vmcnt(" #n ")" ::: "memory")
; #define PG8_WAIT_L(n) asm volatile("s_waitcnt lgkmcnt(" #n ")" ::: "memory")
; #define PG8_BAR __builtin_amdgcn_s_barrier()
; #define PG8_SCHED __builtin_amdgcn_sched_barrier(0)
; template <class Epi, class Sched, bool ALIGN_EPI = false, bool SP2 = false>
; __device__ __forceinline__ void gemm_phase(PG8_LAS unsigned char* lds, const Gemm g, const Sched& S, const Epi& E) {
;     ...
;         for (int t = 0; t < nt; t += 2) {
;             const bool last = (t == nt - 2);
;             const char* a1 = cA + (size_t)(t + 1) * kstep;
;             const char* a2 = last ? nA : cA + (size_t)(t + 2) * kstep; const char* b2 = last ? nB : cB + (size_t)(t + 2) * kstep;
;             const char* a3 = a2 + kstep; const char* b3 = b2 + kstep;
;             if (last && has_next) S.a_ready(nxt);
;             if constexpr (SP2) {
;             PG8_LDB(B0, 0, 0); PG8_LDB(B1, 0, 1); PG8_SCHED; PG8_LDA(At, 0, 0); PG8_STAGE(PG8_SA(1, 1), a1 + hstep, voffA);
;     ...
;             PG8_LDA(At, 1, 1); PG8_STAGE(PG8_SB(1, 0), b3, voffB); PG8_STAGE(PG8_SB(1, 1), b3 + hstep, voffB); PG8_STAGE(PG8_SA(1, 0), a3, voffA);
;             PG8_WAIT_V(8); PG8_WAIT_L(0); PG8_BAR; PG8_MMA(1, 0, At, B0); PG8_MMA(1, 1, At, B1); PG8_BAR; PG8_SCHED;
	s_add_i32 s52, s77, s56
	v_lshl_add_u64 v[226:227], v[226:227], 0, s[36:37]
	s_mov_b32 m0, s52
	ds_read_b128 v[192:195], v162 offset:49152
	ds_read_b128 v[198:201], v162 offset:50176
	ds_read_b128 v[202:205], v162 offset:51200
	ds_read_b128 v[206:209], v162 offset:52224
	ds_read_b128 v[210:213], v162 offset:53248
	ds_read_b128 v[214:217], v162 offset:54272
	ds_read_b128 v[218:221], v162 offset:55296
	ds_read_b128 v[222:225], v162 offset:56320
	global_load_lds_dwordx4 v[226:227], off
	s_add_i32 m0, s52, 0x2000
	s_add_u32 s50, s50, 0x100080
	v_lshl_add_u64 v[226:227], v[228:229], 0, s[36:37]
	s_addc_u32 s51, s51, 0
	s_add_i32 s52, s78, s56
	global_load_lds_dwordx4 v[226:227], off
	v_lshl_add_u64 v[226:227], s[50:51], 0, v[132:133]
	s_mov_b32 m0, s52
	s_nop 0
	global_load_lds_dwordx4 v[226:227], off
	v_lshl_add_u64 v[226:227], s[50:51], 0, v[136:137]
	s_add_i32 m0, s52, 0x2000
	s_nop 0
	global_load_lds_dwordx4 v[226:227], off
	v_lshl_add_u64 v[226:227], v[230:231], 0, s[36:37]
	s_mov_b32 m0, s61
	s_nop 0
	global_load_lds_dwordx4 v[226:227], off
	v_lshl_add_u64 v[226:227], v[232:233], 0, s[36:37]
	s_mov_b32 m0, s62
	s_nop 0
	global_load_lds_dwordx4 v[226:227], off
	s_waitcnt vmcnt(8)
	s_waitcnt lgkmcnt(0)
	s_nop 0
	s_setprio 1
	s_barrier
	v_mfma_f32_16x16x32_bf16 v[62:65], v[146:149], v[192:195], v[62:65]
	v_mfma_f32_16x16x32_bf16 v[58:61], v[168:171], v[192:195], v[58:61]
	v_mfma_f32_16x16x32_bf16 v[46:49], v[146:149], v[202:205], v[46:49]
	v_mfma_f32_16x16x32_bf16 v[42:45], v[168:171], v[202:205], v[42:45]
	v_mfma_f32_16x16x32_bf16 v[30:33], v[146:149], v[210:213], v[30:33]
	v_mfma_f32_16x16x32_bf16 v[26:29], v[168:171], v[210:213], v[26:29]
	v_mfma_f32_16x16x32_bf16 v[14:17], v[146:149], v[218:221], v[14:17]
	v_mfma_f32_16x16x32_bf16 v[10:13], v[168:171], v[218:221], v[10:13]
	v_mfma_f32_16x16x32_bf16 v[62:65], v[164:167], v[198:201], v[62:65]
	v_mfma_f32_16x16x32_bf16 v[58:61], v[172:175], v[198:201], v[58:61]
	v_mfma_f32_16x16x32_bf16 v[46:49], v[164:167], v[206:209], v[46:49]
	v_mfma_f32_16x16x32_bf16 v[42:45], v[172:175], v[206:209], v[42:45]
	v_mfma_f32_16x16x32_bf16 v[30:33], v[164:167], v[214:217], v[30:33]
	v_mfma_f32_16x16x32_bf16 v[26:29], v[172:175], v[214:217], v[26:29]
	v_mfma_f32_16x16x32_bf16 v[14:17], v[164:167], v[222:225], v[14:17]
	v_mfma_f32_16x16x32_bf16 v[10:13], v[172:175], v[222:225], v[10:13]
	s_setprio 0
	s_setprio 1
	v_mfma_f32_16x16x32_bf16 v[54:57], v[176:179], v[192:195], v[54:57]
	v_mfma_f32_16x16x32_bf16 v[50:53], v[184:187], v[192:195], v[50:53]
	v_mfma_f32_16x16x32_bf16 v[38:41], v[176:179], v[202:205], v[38:41]
	v_mfma_f32_16x16x32_bf16 v[34:37], v[184:187], v[202:205], v[34:37]
	v_mfma_f32_16x16x32_bf16 v[22:25], v[176:179], v[210:213], v[22:25]
	v_mfma_f32_16x16x32_bf16 v[18:21], v[184:187], v[210:213], v[18:21]
	v_mfma_f32_16x16x32_bf16 v[6:9], v[176:179], v[218:221], v[6:9]
	v_mfma_f32_16x16x32_bf16 v[2:5], v[184:187], v[218:221], v[2:5]
	v_mfma_f32_16x16x32_bf16 v[54:57], v[180:183], v[198:201], v[54:57]
	v_mfma_f32_16x16x32_bf16 v[50:53], v[188:191], v[198:201], v[50:53]
	v_mfma_f32_16x16x32_bf16 v[38:41], v[180:183], v[206:209], v[38:41]
	v_mfma_f32_16x16x32_bf16 v[34:37], v[188:191], v[206:209], v[34:37]
	v_mfma_f32_16x16x32_bf16 v[22:25], v[180:183], v[214:217], v[22:25]
	v_mfma_f32_16x16x32_bf16 v[18:21], v[188:191], v[214:217], v[18:21]
	v_mfma_f32_16x16x32_bf16 v[6:9], v[180:183], v[222:225], v[6:9]
	v_mfma_f32_16x16x32_bf16 v[2:5], v[188:191], v[222:225], v[2:5]
	s_setprio 0
	s_barrier
	s_add_i32 s76, s76, 2
	s_add_u32 s48, s48, 0x100
	s_addc_u32 s49, s49, 0
	s_add_u32 s74, s74, 0x100
	s_addc_u32 s75, s75, 0
	s_cmp_gt_u32 s76, 61
	.p2align	3
.LBB0_710:
	ds_read_b128 v[146:149], v160
	ds_read_b128 v[164:167], v160 offset:1024
	ds_read_b128 v[168:171], v160 offset:2048
	ds_read_b128 v[172:175], v160 offset:3072
	ds_read_b128 v[176:179], v161
	ds_read_b128 v[180:183], v161 offset:1024
	ds_read_b128 v[184:187], v161 offset:2048
	ds_read_b128 v[188:191], v161 offset:3072
	s_add_u32 s50, s48, 0xfff00080
	s_addc_u32 s51, s49, -1
	s_cmp_eq_u32 s76, 60
	s_cselect_b32 s53, s43, s51
	s_cselect_b32 s52, s72, s50
	s_cselect_b32 s51, s41, s75
	s_cselect_b32 s50, s73, s74
	v_lshl_add_u64 v[226:227], s[48:49], 0, v[138:139]
	s_add_i32 m0, s9, 0xc000
	ds_read_b128 v[192:195], v162
	ds_read_b128 v[198:201], v162 offset:1024
	ds_read_b128 v[202:205], v162 offset:2048
	ds_read_b128 v[206:209], v162 offset:3072
	ds_read_b128 v[210:213], v162 offset:4096
	ds_read_b128 v[214:217], v162 offset:5120
	ds_read_b128 v[218:221], v162 offset:6144
	ds_read_b128 v[222:225], v162 offset:7168
	global_load_lds_dwordx4 v[226:227], off
	v_lshl_add_u64 v[226:227], s[48:49], 0, v[140:141]
	s_add_i32 m0, s9, 0xe000
	s_nop 0
	global_load_lds_dwordx4 v[226:227], off
	s_waitcnt vmcnt(8)
	s_waitcnt lgkmcnt(0)
	s_nop 0
	s_setprio 1
	s_barrier
; #define PG8_STAGE(bufoff, gbase, voff) do { _Pragma("unroll") for (int _i = 0; _i < 2; ++_i) \
;         __builtin_amdgcn_global_load_lds((const unsigned*)((const char*)(gbase) + (voff)[_i]), (PG8_LAS unsigned*)(lds + (bufoff) + ldsw + _i * 8192), 16, 0, 0); } while (0)
; #define PG8_LDA(dst, b, h) do { _Pragma("unroll") for (int m = 0; m < 4; ++m) _Pragma("unroll") for (int k = 0; k < 2; ++k) dst[m][k] = *(const PG8_LAS bf16x8*)(lds + PG8_SA(b, h) + aoff + m * 2048 + k * 1024); } while (0)
; #define PG8_MMA(ai, bj, At, Bt) do { __builtin_amdgcn_s_setprio(1); _Pragma("unroll") for (int m = 0; m < 4; ++m) _Pragma("unroll") for (int n = 0; n < 2; ++n) _Pragma("unroll") for (int k = 0; k < 2; ++k) \
;         acc[ai][bj][m][n] = __builtin_amdgcn_mfma_f32_16x16x32_bf16(Bt[n][k], At[m][k], acc[ai][bj][m][n], 0, 0, 0); __builtin_amdgcn_s_setprio(0); } while (0)
; #define PG8_WAIT_V(n) asm volatile("s_waitcnt vmcnt(" #n ")" ::: "memory")
; #define PG8_WAIT_L(n) asm volatile("s_waitcnt lgkmcnt(" #n ")" ::: "memory")
; #define PG8_BAR __builtin_amdgcn_s_barrier()
; #define PG8_SCHED __builtin_amdgcn_sched_barrier(0)
; template <class Epi, class Sched, bool ALIGN_EPI = false, bool SP2 = false>
; __device__ __forceinline__ void gemm_phase(PG8_LAS unsigned char* lds, const Gemm g, const Sched& S, const Epi& E) {
;     ...
;             PG8_WAIT_V(8); PG8_WAIT_L(0); PG8_BAR; PG8_MMA(0, 0, At, B0); PG8_MMA(0, 1, At, B1); PG8_BAR; PG8_SCHED;
;             PG8_LDA(At, 0, 1); PG8_STAGE(PG8_SB(0, 0), b2, voffB); PG8_STAGE(PG8_SB(0, 1), b2 + hstep, voffB); PG8_STAGE(PG8_SA(0, 0), a2, voffA);
;             PG8_WAIT_V(8); PG8_WAIT_L(0); PG8_BAR; PG8_MMA(1, 0, At, B0); PG8_MMA(1, 1, At, B1); PG8_BAR; PG8_SCHED;
	v_mfma_f32_16x16x32_bf16 v[126:129], v[146:149], v[192:195], v[126:129]
	v_mfma_f32_16x16x32_bf16 v[122:125], v[168:171], v[192:195], v[122:125]
	v_mfma_f32_16x16x32_bf16 v[110:113], v[146:149], v[202:205], v[110:113]
	v_mfma_f32_16x16x32_bf16 v[106:109], v[168:171], v[202:205], v[106:109]
	v_mfma_f32_16x16x32_bf16 v[94:97], v[146:149], v[210:213], v[94:97]
	v_mfma_f32_16x16x32_bf16 v[90:93], v[168:171], v[210:213], v[90:93]
	v_mfma_f32_16x16x32_bf16 v[78:81], v[146:149], v[218:221], v[78:81]
	v_mfma_f32_16x16x32_bf16 v[74:77], v[168:171], v[218:221], v[74:77]
	v_mfma_f32_16x16x32_bf16 v[126:129], v[164:167], v[198:201], v[126:129]
	v_mfma_f32_16x16x32_bf16 v[122:125], v[172:175], v[198:201], v[122:125]
	v_mfma_f32_16x16x32_bf16 v[110:113], v[164:167], v[206:209], v[110:113]
	v_mfma_f32_16x16x32_bf16 v[106:109], v[172:175], v[206:209], v[106:109]
	v_mfma_f32_16x16x32_bf16 v[94:97], v[164:167], v[214:217], v[94:97]
	v_mfma_f32_16x16x32_bf16 v[90:93], v[172:175], v[214:217], v[90:93]
	v_mfma_f32_16x16x32_bf16 v[78:81], v[164:167], v[222:225], v[78:81]
	v_mfma_f32_16x16x32_bf16 v[74:77], v[172:175], v[222:225], v[74:77]
	s_setprio 0
	s_setprio 1
	v_mfma_f32_16x16x32_bf16 v[118:121], v[176:179], v[192:195], v[118:121]
	v_mfma_f32_16x16x32_bf16 v[114:117], v[184:187], v[192:195], v[114:117]
	v_mfma_f32_16x16x32_bf16 v[102:105], v[176:179], v[202:205], v[102:105]
	v_mfma_f32_16x16x32_bf16 v[98:101], v[184:187], v[202:205], v[98:101]
	v_mfma_f32_16x16x32_bf16 v[86:89], v[176:179], v[210:213], v[86:89]
	v_mfma_f32_16x16x32_bf16 v[82:85], v[184:187], v[210:213], v[82:85]
	v_mfma_f32_16x16x32_bf16 v[70:73], v[176:179], v[218:221], v[70:73]
	v_mfma_f32_16x16x32_bf16 v[66:69], v[184:187], v[218:221], v[66:69]
	v_mfma_f32_16x16x32_bf16 v[118:121], v[180:183], v[198:201], v[118:121]
	v_mfma_f32_16x16x32_bf16 v[114:117], v[188:191], v[198:201], v[114:117]
	v_mfma_f32_16x16x32_bf16 v[102:105], v[180:183], v[206:209], v[102:105]
	v_mfma_f32_16x16x32_bf16 v[98:101], v[188:191], v[206:209], v[98:101]
	v_mfma_f32_16x16x32_bf16 v[86:89], v[180:183], v[214:217], v[86:89]
	v_mfma_f32_16x16x32_bf16 v[82:85], v[188:191], v[214:217], v[82:85]
	v_mfma_f32_16x16x32_bf16 v[70:73], v[180:183], v[222:225], v[70:73]
	v_mfma_f32_16x16x32_bf16 v[66:69], v[188:191], v[222:225], v[66:69]
	s_setprio 0
	s_barrier
	s_add_i32 s77, s69, s56
	v_lshl_add_u64 v[226:227], s[50:51], 0, v[132:133]
	s_mov_b32 m0, s77
	ds_read_b128 v[192:195], v162 offset:16384
	ds_read_b128 v[198:201], v162 offset:17408
	ds_read_b128 v[202:205], v162 offset:18432
	ds_read_b128 v[206:209], v162 offset:19456
	ds_read_b128 v[210:213], v162 offset:20480
	ds_read_b128 v[214:217], v162 offset:21504
	ds_read_b128 v[218:221], v162 offset:22528
	ds_read_b128 v[222:225], v162 offset:23552
	global_load_lds_dwordx4 v[226:227], off
	s_add_i32 m0, s77, 0x2000
	s_add_u32 s78, s50, 0x100000
	v_lshl_add_u64 v[228:229], s[50:51], 0, v[136:137]
	s_addc_u32 s79, s51, 0
	s_add_i32 s77, s70, s56
	global_load_lds_dwordx4 v[228:229], off
	v_lshl_add_u64 v[230:231], s[78:79], 0, v[132:133]
	s_mov_b32 m0, s77
	v_lshl_add_u64 v[232:233], s[52:53], 0, v[134:135]
	global_load_lds_dwordx4 v[230:231], off
	v_lshl_add_u64 v[230:231], s[78:79], 0, v[136:137]
	s_add_i32 m0, s77, 0x2000
	s_nop 0
	global_load_lds_dwordx4 v[230:231], off
	v_lshl_add_u64 v[230:231], s[52:53], 0, v[130:131]
	s_mov_b32 m0, s9
	s_nop 0
	global_load_lds_dwordx4 v[230:231], off
	s_mov_b32 m0, s57
	s_nop 0
	global_load_lds_dwordx4 v[232:233], off
	s_waitcnt vmcnt(8)
	s_waitcnt lgkmcnt(0)
	s_nop 0
	s_setprio 1
	s_barrier
	v_mfma_f32_16x16x32_bf16 v[62:65], v[146:149], v[192:195], v[62:65]
	v_mfma_f32_16x16x32_bf16 v[58:61], v[168:171], v[192:195], v[58:61]
	v_mfma_f32_16x16x32_bf16 v[46:49], v[146:149], v[202:205], v[46:49]
	v_mfma_f32_16x16x32_bf16 v[42:45], v[168:171], v[202:205], v[42:45]
	v_mfma_f32_16x16x32_bf16 v[30:33], v[146:149], v[210:213], v[30:33]
	v_mfma_f32_16x16x32_bf16 v[26:29], v[168:171], v[210:213], v[26:29]
	v_mfma_f32_16x16x32_bf16 v[14:17], v[146:149], v[218:221], v[14:17]
	v_mfma_f32_16x16x32_bf16 v[10:13], v[168:171], v[218:221], v[10:13]
	v_mfma_f32_16x16x32_bf16 v[62:65], v[164:167], v[198:201], v[62:65]
	v_mfma_f32_16x16x32_bf16 v[58:61], v[172:175], v[198:201], v[58:61]
	v_mfma_f32_16x16x32_bf16 v[46:49], v[164:167], v[206:209], v[46:49]
	v_mfma_f32_16x16x32_bf16 v[42:45], v[172:175], v[206:209], v[42:45]
	v_mfma_f32_16x16x32_bf16 v[30:33], v[164:167], v[214:217], v[30:33]
	v_mfma_f32_16x16x32_bf16 v[26:29], v[172:175], v[214:217], v[26:29]
	v_mfma_f32_16x16x32_bf16 v[14:17], v[164:167], v[222:225], v[14:17]
	v_mfma_f32_16x16x32_bf16 v[10:13], v[172:175], v[222:225], v[10:13]
	s_setprio 0
	s_setprio 1
	v_mfma_f32_16x16x32_bf16 v[54:57], v[176:179], v[192:195], v[54:57]
	v_mfma_f32_16x16x32_bf16 v[50:53], v[184:187], v[192:195], v[50:53]
	v_mfma_f32_16x16x32_bf16 v[38:41], v[176:179], v[202:205], v[38:41]
	v_mfma_f32_16x16x32_bf16 v[34:37], v[184:187], v[202:205], v[34:37]
	v_mfma_f32_16x16x32_bf16 v[22:25], v[176:179], v[210:213], v[22:25]
	v_mfma_f32_16x16x32_bf16 v[18:21], v[184:187], v[210:213], v[18:21]
	v_mfma_f32_16x16x32_bf16 v[6:9], v[176:179], v[218:221], v[6:9]
	v_mfma_f32_16x16x32_bf16 v[2:5], v[184:187], v[218:221], v[2:5]
	v_mfma_f32_16x16x32_bf16 v[54:57], v[180:183], v[198:201], v[54:57]
	v_mfma_f32_16x16x32_bf16 v[50:53], v[188:191], v[198:201], v[50:53]
	v_mfma_f32_16x16x32_bf16 v[38:41], v[180:183], v[206:209], v[38:41]
	v_mfma_f32_16x16x32_bf16 v[34:37], v[188:191], v[206:209], v[34:37]
	v_mfma_f32_16x16x32_bf16 v[22:25], v[180:183], v[214:217], v[22:25]
	v_mfma_f32_16x16x32_bf16 v[18:21], v[188:191], v[214:217], v[18:21]
	v_mfma_f32_16x16x32_bf16 v[6:9], v[180:183], v[222:225], v[6:9]
	v_mfma_f32_16x16x32_bf16 v[2:5], v[188:191], v[222:225], v[2:5]
	s_setprio 0
	s_barrier
; #define PG8_STAGE(bufoff, gbase, voff) do { _Pragma("unroll") for (int _i = 0; _i < 2; ++_i) \
;         __builtin_amdgcn_global_load_lds((const unsigned*)((const char*)(gbase) + (voff)[_i]), (PG8_LAS unsigned*)(lds + (bufoff) + ldsw + _i * 8192), 16, 0, 0); } while (0)
; #define PG8_LDA(dst, b, h) do { _Pragma("unroll") for (int m = 0; m < 4; ++m) _Pragma("unroll") for (int k = 0; k < 2; ++k) dst[m][k] = *(const PG8_LAS bf16x8*)(lds + PG8_SA(b, h) + aoff + m * 2048 + k * 1024); } while (0)
; #define PG8_LDB(dst, b, h) do { _Pragma("unroll") for (int n = 0; n < 2; ++n) _Pragma("unroll") for (int k = 0; k < 2; ++k) dst[n][k] = *(const PG8_LAS bf16x8*)(lds + PG8_SB(b, h) + boff + n * 2048 + k * 1024); } while (0)
; #define PG8_MMA(ai, bj, At, Bt) do { __builtin_amdgcn_s_setprio(1); _Pragma("unroll") for (int m = 0; m < 4; ++m) _Pragma("unroll") for (int n = 0; n < 2; ++n) _Pragma("unroll") for (int k = 0; k < 2; ++k) \
;         acc[ai][bj][m][n] = __builtin_amdgcn_mfma_f32_16x16x32_bf16(Bt[n][k], At[m][k], acc[ai][bj][m][n], 0, 0, 0); __builtin_amdgcn_s_setprio(0); } while (0)
; #define PG8_WAIT_V(n) asm volatile("s_waitcnt vmcnt(" #n ")" ::: "memory")
; #define PG8_WAIT_L(n) asm volatile("s_waitcnt lgkmcnt(" #n ")" ::: "memory")
; #define PG8_BAR __builtin_amdgcn_s_barrier()
; #define PG8_SCHED __builtin_amdgcn_sched_barrier(0)
; template <class Epi, class Sched, bool ALIGN_EPI = false, bool SP2 = false>
; __device__ __forceinline__ void gemm_phase(PG8_LAS unsigned char* lds, const Gemm g, const Sched& S, const Epi& E) {
;     ...
;             PG8_LDB(B0, 1, 0); PG8_LDB(B1, 1, 1); PG8_SCHED; PG8_LDA(At, 1, 0); PG8_STAGE(PG8_SA(0, 1), a2 + hstep, voffA);
;             PG8_WAIT_V(8); PG8_WAIT_L(0); PG8_BAR; PG8_MMA(0, 0, At, B0); PG8_MMA(0, 1, At, B1); PG8_BAR; PG8_SCHED;
	s_add_i32 s77, 0, 0x18000
	s_add_i32 s78, 0, 0x1c000
	v_add_u32_e32 v172, s77, v151
	v_add_u32_e32 v188, s78, v151
	ds_read_b128 v[146:149], v172
	ds_read_b128 v[164:167], v172 offset:1024
	ds_read_b128 v[168:171], v172 offset:2048
	ds_read_b128 v[172:175], v172 offset:3072
	ds_read_b128 v[176:179], v188
	ds_read_b128 v[180:183], v188 offset:1024
	ds_read_b128 v[184:187], v188 offset:2048
	ds_read_b128 v[188:191], v188 offset:3072
	s_add_u32 s52, s52, 0x100000
	s_addc_u32 s53, s53, 0
	s_mov_b32 m0, s58
	v_lshl_add_u64 v[234:235], s[52:53], 0, v[130:131]
	ds_read_b128 v[192:195], v162 offset:32768
	ds_read_b128 v[198:201], v162 offset:33792
	ds_read_b128 v[202:205], v162 offset:34816
	ds_read_b128 v[206:209], v162 offset:35840
	ds_read_b128 v[210:213], v162 offset:36864
	ds_read_b128 v[214:217], v162 offset:37888
	ds_read_b128 v[218:221], v162 offset:38912
	ds_read_b128 v[222:225], v162 offset:39936
	global_load_lds_dwordx4 v[234:235], off
	v_lshl_add_u64 v[234:235], s[52:53], 0, v[134:135]
	s_mov_b32 m0, s59
	s_nop 0
	global_load_lds_dwordx4 v[234:235], off
	s_waitcnt vmcnt(8)
	s_waitcnt lgkmcnt(0)
	s_nop 0
	s_setprio 1
	s_barrier
	v_mfma_f32_16x16x32_bf16 v[126:129], v[146:149], v[192:195], v[126:129]
	v_mfma_f32_16x16x32_bf16 v[122:125], v[168:171], v[192:195], v[122:125]
	v_mfma_f32_16x16x32_bf16 v[110:113], v[146:149], v[202:205], v[110:113]
	v_mfma_f32_16x16x32_bf16 v[106:109], v[168:171], v[202:205], v[106:109]
	v_mfma_f32_16x16x32_bf16 v[94:97], v[146:149], v[210:213], v[94:97]
	v_mfma_f32_16x16x32_bf16 v[90:93], v[168:171], v[210:213], v[90:93]
	v_mfma_f32_16x16x32_bf16 v[78:81], v[146:149], v[218:221], v[78:81]
	v_mfma_f32_16x16x32_bf16 v[74:77], v[168:171], v[218:221], v[74:77]
	v_mfma_f32_16x16x32_bf16 v[126:129], v[164:167], v[198:201], v[126:129]
	v_mfma_f32_16x16x32_bf16 v[122:125], v[172:175], v[198:201], v[122:125]
	v_mfma_f32_16x16x32_bf16 v[110:113], v[164:167], v[206:209], v[110:113]
	v_mfma_f32_16x16x32_bf16 v[106:109], v[172:175], v[206:209], v[106:109]
	v_mfma_f32_16x16x32_bf16 v[94:97], v[164:167], v[214:217], v[94:97]
	v_mfma_f32_16x16x32_bf16 v[90:93], v[172:175], v[214:217], v[90:93]
	v_mfma_f32_16x16x32_bf16 v[78:81], v[164:167], v[222:225], v[78:81]
	v_mfma_f32_16x16x32_bf16 v[74:77], v[172:175], v[222:225], v[74:77]
	s_setprio 0
	s_setprio 1
	v_mfma_f32_16x16x32_bf16 v[118:121], v[176:179], v[192:195], v[118:121]
	v_mfma_f32_16x16x32_bf16 v[114:117], v[184:187], v[192:195], v[114:117]
	v_mfma_f32_16x16x32_bf16 v[102:105], v[176:179], v[202:205], v[102:105]
	v_mfma_f32_16x16x32_bf16 v[98:101], v[184:187], v[202:205], v[98:101]
	v_mfma_f32_16x16x32_bf16 v[86:89], v[176:179], v[210:213], v[86:89]
	v_mfma_f32_16x16x32_bf16 v[82:85], v[184:187], v[210:213], v[82:85]
	v_mfma_f32_16x16x32_bf16 v[70:73], v[176:179], v[218:221], v[70:73]
	v_mfma_f32_16x16x32_bf16 v[66:69], v[184:187], v[218:221], v[66:69]
	v_mfma_f32_16x16x32_bf16 v[118:121], v[180:183], v[198:201], v[118:121]
	v_mfma_f32_16x16x32_bf16 v[114:117], v[188:191], v[198:201], v[114:117]
	v_mfma_f32_16x16x32_bf16 v[102:105], v[180:183], v[206:209], v[102:105]
	v_mfma_f32_16x16x32_bf16 v[98:101], v[188:191], v[206:209], v[98:101]
	v_mfma_f32_16x16x32_bf16 v[86:89], v[180:183], v[214:217], v[86:89]
	v_mfma_f32_16x16x32_bf16 v[82:85], v[188:191], v[214:217], v[82:85]
	v_mfma_f32_16x16x32_bf16 v[70:73], v[180:183], v[222:225], v[70:73]
	v_mfma_f32_16x16x32_bf16 v[66:69], v[188:191], v[222:225], v[66:69]
	s_setprio 0
	s_barrier
; #define PG8_STAGE(bufoff, gbase, voff) do { _Pragma("unroll") for (int _i = 0; _i < 2; ++_i) \
;         __builtin_amdgcn_global_load_lds((const unsigned*)((const char*)(gbase) + (voff)[_i]), (PG8_LAS unsigned*)(lds + (bufoff) + ldsw + _i * 8192), 16, 0, 0); } while (0)
; #define PG8_LDA(dst, b, h) do { _Pragma("unroll") for (int m = 0; m < 4; ++m) _Pragma("unroll") for (int k = 0; k < 2; ++k) dst[m][k] = *(const PG8_LAS bf16x8*)(lds + PG8_SA(b, h) + aoff + m * 2048 + k * 1024); } while (0)
; #define PG8_MMA(ai, bj, At, Bt) do { __builtin_amdgcn_s_setprio(1); _Pragma("unroll") for (int m = 0; m < 4; ++m) _Pragma("unroll") for (int n = 0; n < 2; ++n) _Pragma("unroll") for (int k = 0; k < 2; ++k) \
;         acc[ai][bj][m][n] = __builtin_amdgcn_mfma_f32_16x16x32_bf16(Bt[n][k], At[m][k], acc[ai][bj][m][n], 0, 0, 0); __builtin_amdgcn_s_setprio(0); } while (0)
; #define PG8_WAIT_V(n) asm volatile("s_waitcnt vmcnt(" #n ")" ::: "memory")
; #define PG8_WAIT_L(n) asm volatile("s_waitcnt lgkmcnt(" #n ")" ::: "memory")
; #define PG8_BAR __builtin_amdgcn_s_barrier()
; #define PG8_SCHED __builtin_amdgcn_sched_barrier(0)
; template <class Epi, class Sched, bool ALIGN_EPI = false, bool SP2 = false>
; __device__ __forceinline__ void gemm_phase(PG8_LAS unsigned char* lds, const Gemm g, const Sched& S, const Epi& E) {
;     ...
;             PG8_LDA(At, 1, 1); PG8_STAGE(PG8_SB(1, 0), b3, voffB); PG8_STAGE(PG8_SB(1, 1), b3 + hstep, voffB); PG8_STAGE(PG8_SA(1, 0), a3, voffA);
;             PG8_WAIT_V(8); PG8_WAIT_L(0); PG8_BAR; PG8_MMA(1, 0, At, B0); PG8_MMA(1, 1, At, B1); PG8_BAR; PG8_SCHED;
;     ...
;         if constexpr (ALIGN_EPI) { if (wr == 0) PG8_BAR; }
	s_add_i32 s52, s77, s56
	v_lshl_add_u64 v[226:227], v[226:227], 0, s[36:37]
	s_mov_b32 m0, s52
	ds_read_b128 v[192:195], v162 offset:49152
	ds_read_b128 v[198:201], v162 offset:50176
	ds_read_b128 v[202:205], v162 offset:51200
	ds_read_b128 v[206:209], v162 offset:52224
	ds_read_b128 v[210:213], v162 offset:53248
	ds_read_b128 v[214:217], v162 offset:54272
	ds_read_b128 v[218:221], v162 offset:55296
	ds_read_b128 v[222:225], v162 offset:56320
	global_load_lds_dwordx4 v[226:227], off
	s_add_i32 m0, s52, 0x2000
	s_add_u32 s50, s50, 0x100080
	v_lshl_add_u64 v[226:227], v[228:229], 0, s[36:37]
	s_addc_u32 s51, s51, 0
	s_add_i32 s52, s78, s56
	global_load_lds_dwordx4 v[226:227], off
	v_lshl_add_u64 v[226:227], s[50:51], 0, v[132:133]
	s_mov_b32 m0, s52
	s_nop 0
	global_load_lds_dwordx4 v[226:227], off
	v_lshl_add_u64 v[226:227], s[50:51], 0, v[136:137]
	s_add_i32 m0, s52, 0x2000
	s_nop 0
	global_load_lds_dwordx4 v[226:227], off
	v_lshl_add_u64 v[226:227], v[230:231], 0, s[36:37]
	s_mov_b32 m0, s61
	s_nop 0
	global_load_lds_dwordx4 v[226:227], off
	v_lshl_add_u64 v[226:227], v[232:233], 0, s[36:37]
	s_mov_b32 m0, s62
	s_nop 0
	global_load_lds_dwordx4 v[226:227], off
	s_waitcnt vmcnt(8)
	s_waitcnt lgkmcnt(0)
	s_nop 0
	s_setprio 1
	s_barrier
	v_mfma_f32_16x16x32_bf16 v[62:65], v[146:149], v[192:195], v[62:65]
	v_mfma_f32_16x16x32_bf16 v[58:61], v[168:171], v[192:195], v[58:61]
	v_mfma_f32_16x16x32_bf16 v[46:49], v[146:149], v[202:205], v[46:49]
	v_mfma_f32_16x16x32_bf16 v[42:45], v[168:171], v[202:205], v[42:45]
	v_mfma_f32_16x16x32_bf16 v[30:33], v[146:149], v[210:213], v[30:33]
	v_mfma_f32_16x16x32_bf16 v[26:29], v[168:171], v[210:213], v[26:29]
	v_mfma_f32_16x16x32_bf16 v[14:17], v[146:149], v[218:221], v[14:17]
	v_mfma_f32_16x16x32_bf16 v[10:13], v[168:171], v[218:221], v[10:13]
	v_mfma_f32_16x16x32_bf16 v[62:65], v[164:167], v[198:201], v[62:65]
	v_mfma_f32_16x16x32_bf16 v[58:61], v[172:175], v[198:201], v[58:61]
	v_mfma_f32_16x16x32_bf16 v[46:49], v[164:167], v[206:209], v[46:49]
	v_mfma_f32_16x16x32_bf16 v[42:45], v[172:175], v[206:209], v[42:45]
	v_mfma_f32_16x16x32_bf16 v[30:33], v[164:167], v[214:217], v[30:33]
	v_mfma_f32_16x16x32_bf16 v[26:29], v[172:175], v[214:217], v[26:29]
	v_mfma_f32_16x16x32_bf16 v[14:17], v[164:167], v[222:225], v[14:17]
	v_mfma_f32_16x16x32_bf16 v[10:13], v[172:175], v[222:225], v[10:13]
	s_setprio 0
	s_setprio 1
	v_mfma_f32_16x16x32_bf16 v[54:57], v[176:179], v[192:195], v[54:57]
	v_mfma_f32_16x16x32_bf16 v[50:53], v[184:187], v[192:195], v[50:53]
	v_mfma_f32_16x16x32_bf16 v[38:41], v[176:179], v[202:205], v[38:41]
	v_mfma_f32_16x16x32_bf16 v[34:37], v[184:187], v[202:205], v[34:37]
	v_mfma_f32_16x16x32_bf16 v[22:25], v[176:179], v[210:213], v[22:25]
	v_mfma_f32_16x16x32_bf16 v[18:21], v[184:187], v[210:213], v[18:21]
	v_mfma_f32_16x16x32_bf16 v[6:9], v[176:179], v[218:221], v[6:9]
	v_mfma_f32_16x16x32_bf16 v[2:5], v[184:187], v[218:221], v[2:5]
	v_mfma_f32_16x16x32_bf16 v[54:57], v[180:183], v[198:201], v[54:57]
	v_mfma_f32_16x16x32_bf16 v[50:53], v[188:191], v[198:201], v[50:53]
	v_mfma_f32_16x16x32_bf16 v[38:41], v[180:183], v[206:209], v[38:41]
	v_mfma_f32_16x16x32_bf16 v[34:37], v[188:191], v[206:209], v[34:37]
	v_mfma_f32_16x16x32_bf16 v[22:25], v[180:183], v[214:217], v[22:25]
	v_mfma_f32_16x16x32_bf16 v[18:21], v[188:191], v[214:217], v[18:21]
	v_mfma_f32_16x16x32_bf16 v[6:9], v[180:183], v[222:225], v[6:9]
	v_mfma_f32_16x16x32_bf16 v[2:5], v[188:191], v[222:225], v[2:5]
	s_setprio 0
	s_barrier
	s_add_i32 s76, s76, 2
	s_add_u32 s48, s48, 0x100
	s_addc_u32 s49, s49, 0
	s_add_u32 s74, s74, 0x100
	s_addc_u32 s75, s75, 0
	s_cmp_gt_u32 s76, 61
	s_cbranch_scc0 .LBB0_710
	s_and_b64 vcc, exec, s[38:39]
	s_cbranch_vccz .LBB0_713
	s_barrier

; #define PG8_STAGE(bufoff, gbase, voff) do { _Pragma("unroll") for (int _i = 0; _i < 2; ++_i) \
;         __builtin_amdgcn_global_load_lds((const unsigned*)((const char*)(gbase) + (voff)[_i]), (PG8_LAS unsigned*)(lds + (bufoff) + ldsw + _i * 8192), 16, 0, 0); } while (0)
; #define PG8_LDA(dst, b, h) do { _Pragma("unroll") for (int m = 0; m < 4; ++m) _Pragma("unroll") for (int k = 0; k < 2; ++k) dst[m][k] = *(const PG8_LAS bf16x8*)(lds + PG8_SA(b, h) + aoff + m * 2048 + k * 1024); } while (0)
; #define PG8_LDB(dst, b, h) do { _Pragma("unroll") for (int n = 0; n < 2; ++n) _Pragma("unroll") for (int k = 0; k < 2; ++k) dst[n][k] = *(const PG8_LAS bf16x8*)(lds + PG8_SB(b, h) + boff + n * 2048 + k * 1024); } while (0)
; #define PG8_WAIT_V(n) asm volatile("s_waitcnt vmcnt(" #n ")" ::: "memory")
; #define PG8_WAIT_L(n) asm volatile("s_waitcnt lgkmcnt(" #n ")" ::: "memory")
; #define PG8_BAR __builtin_amdgcn_s_barrier()
; #define PG8_SCHED __builtin_amdgcn_sched_barrier(0)
; template <class Epi, class Sched, bool ALIGN_EPI = false, bool SP2 = false>
; __device__ __forceinline__ void gemm_phase(PG8_LAS unsigned char* lds, const Gemm g, const Sched& S, const Epi& E) {
;     ...
;         const char* nA = has_next ? (const char*)g.A + (size_t)nxt.pm * tstep : cA; const char* nB = has_next ? (const char*)g.Bt + (size_t)nxt.pn * tstep : cB;
;         for (int t = 0; t < nt; t += 2) {
;             const bool last = (t == nt - 2);
;             const char* a1 = cA + (size_t)(t + 1) * kstep;
;             const char* a2 = last ? nA : cA + (size_t)(t + 2) * kstep; const char* b2 = last ? nB : cB + (size_t)(t + 2) * kstep;
;             const char* a3 = a2 + kstep; const char* b3 = b2 + kstep;
;             if (last && has_next) S.a_ready(nxt);
;             if constexpr (SP2) {
;             PG8_LDB(B0, 0, 0); PG8_LDB(B1, 0, 1); PG8_SCHED; PG8_LDA(At, 0, 0); PG8_STAGE(PG8_SA(1, 1), a1 + hstep, voffA);
;             PG8_WAIT_V(8); PG8_WAIT_L(0); PG8_BAR; PG8_MMA(0, 0, At, B0); PG8_MMA(0, 1, At, B1); PG8_BAR; PG8_SCHED;
;             PG8_LDA(At, 0, 1); PG8_STAGE(PG8_SB(0, 0), b2, voffB); PG8_STAGE(PG8_SB(0, 1), b2 + hstep, voffB); PG8_STAGE(PG8_SA(0, 0), a2, voffA);
;             PG8_WAIT_V(8); PG8_WAIT_L(0); PG8_BAR; PG8_MMA(1, 0, At, B0); PG8_MMA(1, 1, At, B1); PG8_BAR; PG8_SCHED;
.LBB0_880:
	s_ashr_i32 s37, s36, 31
	s_lshl_b64 s[38:39], s[36:37], 21
	s_add_u32 s38, s19, s38
	s_addc_u32 s39, s21, s39
	s_and_b64 s[40:41], s[2:3], exec
	s_cselect_b32 s37, s39, s45
	s_cselect_b32 s70, s38, s44
	s_ashr_i32 s35, s34, 31
	s_lshl_b64 s[40:41], s[34:35], 21
	s_add_u32 s40, s50, s40
	s_addc_u32 s41, s51, s41
	s_and_b64 s[48:49], s[2:3], exec
	s_cselect_b32 s35, s41, s47
	s_cselect_b32 s71, s40, s46
	s_add_u32 s44, s44, 0x100080
	s_addc_u32 s45, s45, 0
	s_add_u32 s72, s46, 0x100
	s_addc_u32 s73, s47, 0
	s_mov_b32 s74, -2
	.p2align	3
	ds_read_b128 v[156:159], v152
	ds_read_b128 v[160:163], v152 offset:1024
	ds_read_b128 v[164:167], v152 offset:2048
	ds_read_b128 v[168:171], v152 offset:3072
	ds_read_b128 v[172:175], v153
	ds_read_b128 v[176:179], v153 offset:1024
	ds_read_b128 v[180:183], v153 offset:2048
	ds_read_b128 v[184:187], v153 offset:3072
	s_add_u32 s46, s44, 0xfff00080
	s_addc_u32 s47, s45, -1
	s_cmp_eq_u32 s74, 60
	s_cselect_b32 s49, s37, s47
	s_cselect_b32 s48, s70, s46
	s_cselect_b32 s47, s35, s73
	s_cselect_b32 s46, s71, s72
	v_lshl_add_u64 v[146:147], s[44:45], 0, v[138:139]
	s_add_i32 m0, s43, 0xc000
	ds_read_b128 v[188:191], v154
	ds_read_b128 v[192:195], v154 offset:1024
	ds_read_b128 v[198:201], v154 offset:2048
	ds_read_b128 v[202:205], v154 offset:3072
	ds_read_b128 v[206:209], v154 offset:4096
	ds_read_b128 v[210:213], v154 offset:5120
	ds_read_b128 v[214:217], v154 offset:6144
	ds_read_b128 v[218:221], v154 offset:7168
	global_load_lds_dwordx4 v[146:147], off
	v_lshl_add_u64 v[146:147], s[44:45], 0, v[140:141]
	s_add_i32 m0, s43, 0xe000
	s_nop 0
	global_load_lds_dwordx4 v[146:147], off
	s_waitcnt vmcnt(8)
	s_waitcnt lgkmcnt(0)
	s_nop 0
	s_setprio 1
	s_barrier
	v_mfma_f32_16x16x32_bf16 v[122:125], v[156:159], v[188:191], 0
	v_mfma_f32_16x16x32_bf16 v[114:117], v[164:167], v[188:191], 0
	v_mfma_f32_16x16x32_bf16 v[106:109], v[156:159], v[198:201], 0
	v_mfma_f32_16x16x32_bf16 v[98:101], v[164:167], v[198:201], 0
	v_mfma_f32_16x16x32_bf16 v[90:93], v[156:159], v[206:209], 0
	v_mfma_f32_16x16x32_bf16 v[82:85], v[164:167], v[206:209], 0
	v_mfma_f32_16x16x32_bf16 v[74:77], v[156:159], v[214:217], 0
	v_mfma_f32_16x16x32_bf16 v[66:69], v[164:167], v[214:217], 0
	v_mfma_f32_16x16x32_bf16 v[122:125], v[160:163], v[192:195], v[122:125]
	v_mfma_f32_16x16x32_bf16 v[114:117], v[168:171], v[192:195], v[114:117]
	v_mfma_f32_16x16x32_bf16 v[106:109], v[160:163], v[202:205], v[106:109]
	v_mfma_f32_16x16x32_bf16 v[98:101], v[168:171], v[202:205], v[98:101]
	v_mfma_f32_16x16x32_bf16 v[90:93], v[160:163], v[210:213], v[90:93]
	v_mfma_f32_16x16x32_bf16 v[82:85], v[168:171], v[210:213], v[82:85]
	v_mfma_f32_16x16x32_bf16 v[74:77], v[160:163], v[218:221], v[74:77]
	v_mfma_f32_16x16x32_bf16 v[66:69], v[168:171], v[218:221], v[66:69]
	s_setprio 0
	s_setprio 1
	v_mfma_f32_16x16x32_bf16 v[126:129], v[172:175], v[188:191], 0
	v_mfma_f32_16x16x32_bf16 v[118:121], v[180:183], v[188:191], 0
	v_mfma_f32_16x16x32_bf16 v[110:113], v[172:175], v[198:201], 0
	v_mfma_f32_16x16x32_bf16 v[102:105], v[180:183], v[198:201], 0
	v_mfma_f32_16x16x32_bf16 v[94:97], v[172:175], v[206:209], 0
	v_mfma_f32_16x16x32_bf16 v[86:89], v[180:183], v[206:209], 0
	v_mfma_f32_16x16x32_bf16 v[78:81], v[172:175], v[214:217], 0
	v_mfma_f32_16x16x32_bf16 v[70:73], v[180:183], v[214:217], 0
	v_mfma_f32_16x16x32_bf16 v[126:129], v[176:179], v[192:195], v[126:129]
	v_mfma_f32_16x16x32_bf16 v[118:121], v[184:187], v[192:195], v[118:121]
	v_mfma_f32_16x16x32_bf16 v[110:113], v[176:179], v[202:205], v[110:113]
	v_mfma_f32_16x16x32_bf16 v[102:105], v[184:187], v[202:205], v[102:105]
	v_mfma_f32_16x16x32_bf16 v[94:97], v[176:179], v[210:213], v[94:97]
	v_mfma_f32_16x16x32_bf16 v[86:89], v[184:187], v[210:213], v[86:89]
	v_mfma_f32_16x16x32_bf16 v[78:81], v[176:179], v[218:221], v[78:81]
	v_mfma_f32_16x16x32_bf16 v[70:73], v[184:187], v[218:221], v[70:73]
	s_setprio 0
	s_barrier
	s_add_i32 s75, s63, s52
	v_lshl_add_u64 v[146:147], s[46:47], 0, v[134:135]
	s_mov_b32 m0, s75
	ds_read_b128 v[188:191], v154 offset:16384
	ds_read_b128 v[192:195], v154 offset:17408
	ds_read_b128 v[198:201], v154 offset:18432
	ds_read_b128 v[202:205], v154 offset:19456
	ds_read_b128 v[206:209], v154 offset:20480
	ds_read_b128 v[210:213], v154 offset:21504
	ds_read_b128 v[214:217], v154 offset:22528
	ds_read_b128 v[218:221], v154 offset:23552
	global_load_lds_dwordx4 v[146:147], off
	s_add_i32 m0, s75, 0x2000
	s_add_u32 s76, s46, 0x100000
	v_lshl_add_u64 v[222:223], s[46:47], 0, v[130:131]
	s_addc_u32 s77, s47, 0
	s_add_i32 s75, s67, s52
	global_load_lds_dwordx4 v[222:223], off
	v_lshl_add_u64 v[224:225], s[76:77], 0, v[134:135]
	s_mov_b32 m0, s75
	v_lshl_add_u64 v[226:227], s[48:49], 0, v[132:133]
	global_load_lds_dwordx4 v[224:225], off
	v_lshl_add_u64 v[224:225], s[76:77], 0, v[130:131]
	s_add_i32 m0, s75, 0x2000
	s_nop 0
	global_load_lds_dwordx4 v[224:225], off
	v_lshl_add_u64 v[224:225], s[48:49], 0, v[136:137]
	s_mov_b32 m0, s43
	s_nop 0
	global_load_lds_dwordx4 v[224:225], off
	s_mov_b32 m0, s55
	s_nop 0
	global_load_lds_dwordx4 v[226:227], off
	s_waitcnt vmcnt(8)
	s_waitcnt lgkmcnt(0)
	s_nop 0
	s_setprio 1
	s_barrier
; #define PG8_STAGE(bufoff, gbase, voff) do { _Pragma("unroll") for (int _i = 0; _i < 2; ++_i) \
;         __builtin_amdgcn_global_load_lds((const unsigned*)((const char*)(gbase) + (voff)[_i]), (PG8_LAS unsigned*)(lds + (bufoff) + ldsw + _i * 8192), 16, 0, 0); } while (0)
; #define PG8_LDA(dst, b, h) do { _Pragma("unroll") for (int m = 0; m < 4; ++m) _Pragma("unroll") for (int k = 0; k < 2; ++k) dst[m][k] = *(const PG8_LAS bf16x8*)(lds + PG8_SA(b, h) + aoff + m * 2048 + k * 1024); } while (0)
; #define PG8_LDB(dst, b, h) do { _Pragma("unroll") for (int n = 0; n < 2; ++n) _Pragma("unroll") for (int k = 0; k < 2; ++k) dst[n][k] = *(const PG8_LAS bf16x8*)(lds + PG8_SB(b, h) + boff + n * 2048 + k * 1024); } while (0)
; #define PG8_MMA(ai, bj, At, Bt) do { __builtin_amdgcn_s_setprio(1); _Pragma("unroll") for (int m = 0; m < 4; ++m) _Pragma("unroll") for (int n = 0; n < 2; ++n) _Pragma("unroll") for (int k = 0; k < 2; ++k) \
;         acc[ai][bj][m][n] = __builtin_amdgcn_mfma_f32_16x16x32_bf16(Bt[n][k], At[m][k], acc[ai][bj][m][n], 0, 0, 0); __builtin_amdgcn_s_setprio(0); } while (0)
; #define PG8_WAIT_V(n) asm volatile("s_waitcnt vmcnt(" #n ")" ::: "memory")
; #define PG8_WAIT_L(n) asm volatile("s_waitcnt lgkmcnt(" #n ")" ::: "memory")
; #define PG8_BAR __builtin_amdgcn_s_barrier()
; #define PG8_SCHED __builtin_amdgcn_sched_barrier(0)
; template <class Epi, class Sched, bool ALIGN_EPI = false, bool SP2 = false>
; __device__ __forceinline__ void gemm_phase(PG8_LAS unsigned char* lds, const Gemm g, const Sched& S, const Epi& E) {
;     ...
;             PG8_WAIT_V(8); PG8_WAIT_L(0); PG8_BAR; PG8_MMA(1, 0, At, B0); PG8_MMA(1, 1, At, B1); PG8_BAR; PG8_SCHED;
;             PG8_LDB(B0, 1, 0); PG8_LDB(B1, 1, 1); PG8_SCHED; PG8_LDA(At, 1, 0); PG8_STAGE(PG8_SA(0, 1), a2 + hstep, voffA);
;             PG8_WAIT_V(8); PG8_WAIT_L(0); PG8_BAR; PG8_MMA(0, 0, At, B0); PG8_MMA(0, 1, At, B1); PG8_BAR; PG8_SCHED;
	v_mfma_f32_16x16x32_bf16 v[58:61], v[156:159], v[188:191], 0
	v_mfma_f32_16x16x32_bf16 v[50:53], v[164:167], v[188:191], 0
	v_mfma_f32_16x16x32_bf16 v[42:45], v[156:159], v[198:201], 0
	v_mfma_f32_16x16x32_bf16 v[34:37], v[164:167], v[198:201], 0
	v_mfma_f32_16x16x32_bf16 v[26:29], v[156:159], v[206:209], 0
	v_mfma_f32_16x16x32_bf16 v[18:21], v[164:167], v[206:209], 0
	v_mfma_f32_16x16x32_bf16 v[10:13], v[156:159], v[214:217], 0
	v_mfma_f32_16x16x32_bf16 v[6:9], v[164:167], v[214:217], 0
	v_mfma_f32_16x16x32_bf16 v[58:61], v[160:163], v[192:195], v[58:61]
	v_mfma_f32_16x16x32_bf16 v[50:53], v[168:171], v[192:195], v[50:53]
	v_mfma_f32_16x16x32_bf16 v[42:45], v[160:163], v[202:205], v[42:45]
	v_mfma_f32_16x16x32_bf16 v[34:37], v[168:171], v[202:205], v[34:37]
	v_mfma_f32_16x16x32_bf16 v[26:29], v[160:163], v[210:213], v[26:29]
	v_mfma_f32_16x16x32_bf16 v[18:21], v[168:171], v[210:213], v[18:21]
	v_mfma_f32_16x16x32_bf16 v[10:13], v[160:163], v[218:221], v[10:13]
	v_mfma_f32_16x16x32_bf16 v[6:9], v[168:171], v[218:221], v[6:9]
	s_setprio 0
	s_setprio 1
	v_mfma_f32_16x16x32_bf16 v[62:65], v[172:175], v[188:191], 0
	v_mfma_f32_16x16x32_bf16 v[54:57], v[180:183], v[188:191], 0
	v_mfma_f32_16x16x32_bf16 v[46:49], v[172:175], v[198:201], 0
	v_mfma_f32_16x16x32_bf16 v[38:41], v[180:183], v[198:201], 0
	v_mfma_f32_16x16x32_bf16 v[30:33], v[172:175], v[206:209], 0
	v_mfma_f32_16x16x32_bf16 v[22:25], v[180:183], v[206:209], 0
	v_mfma_f32_16x16x32_bf16 v[14:17], v[172:175], v[214:217], 0
	v_mfma_f32_16x16x32_bf16 v[2:5], v[180:183], v[214:217], 0
	v_mfma_f32_16x16x32_bf16 v[62:65], v[176:179], v[192:195], v[62:65]
	v_mfma_f32_16x16x32_bf16 v[54:57], v[184:187], v[192:195], v[54:57]
	v_mfma_f32_16x16x32_bf16 v[46:49], v[176:179], v[202:205], v[46:49]
	v_mfma_f32_16x16x32_bf16 v[38:41], v[184:187], v[202:205], v[38:41]
	v_mfma_f32_16x16x32_bf16 v[30:33], v[176:179], v[210:213], v[30:33]
	v_mfma_f32_16x16x32_bf16 v[22:25], v[184:187], v[210:213], v[22:25]
	v_mfma_f32_16x16x32_bf16 v[14:17], v[176:179], v[218:221], v[14:17]
	v_mfma_f32_16x16x32_bf16 v[2:5], v[184:187], v[218:221], v[2:5]
	s_setprio 0
	s_barrier
	s_add_i32 s75, 0, 0x18000
	v_add_u32_e32 v155, s75, v150
	s_add_i32 s76, 0, 0x1c000
	ds_read_b128 v[156:159], v155
	ds_read_b128 v[160:163], v155 offset:1024
	ds_read_b128 v[164:167], v155 offset:2048
	ds_read_b128 v[168:171], v155 offset:3072
	v_add_u32_e32 v155, s76, v150
	ds_read_b128 v[172:175], v155
	ds_read_b128 v[176:179], v155 offset:1024
	ds_read_b128 v[180:183], v155 offset:2048
	ds_read_b128 v[184:187], v155 offset:3072
	s_add_u32 s48, s48, 0x100000
	s_addc_u32 s49, s49, 0
	s_mov_b32 m0, s56
	v_lshl_add_u64 v[228:229], s[48:49], 0, v[136:137]
	ds_read_b128 v[188:191], v154 offset:32768
	ds_read_b128 v[192:195], v154 offset:33792
	ds_read_b128 v[198:201], v154 offset:34816
	ds_read_b128 v[202:205], v154 offset:35840
	ds_read_b128 v[206:209], v154 offset:36864
	ds_read_b128 v[210:213], v154 offset:37888
	ds_read_b128 v[214:217], v154 offset:38912
	ds_read_b128 v[218:221], v154 offset:39936
	global_load_lds_dwordx4 v[228:229], off
	v_lshl_add_u64 v[228:229], s[48:49], 0, v[132:133]
	s_mov_b32 m0, s57
	s_nop 0
	global_load_lds_dwordx4 v[228:229], off
	s_waitcnt vmcnt(8)
	s_waitcnt lgkmcnt(0)
	s_nop 0
	s_setprio 1
	s_barrier
	v_mfma_f32_16x16x32_bf16 v[122:125], v[156:159], v[188:191], v[122:125]
	v_mfma_f32_16x16x32_bf16 v[114:117], v[164:167], v[188:191], v[114:117]
	v_mfma_f32_16x16x32_bf16 v[106:109], v[156:159], v[198:201], v[106:109]
	v_mfma_f32_16x16x32_bf16 v[98:101], v[164:167], v[198:201], v[98:101]
	v_mfma_f32_16x16x32_bf16 v[90:93], v[156:159], v[206:209], v[90:93]
	v_mfma_f32_16x16x32_bf16 v[82:85], v[164:167], v[206:209], v[82:85]
	v_mfma_f32_16x16x32_bf16 v[74:77], v[156:159], v[214:217], v[74:77]
	v_mfma_f32_16x16x32_bf16 v[66:69], v[164:167], v[214:217], v[66:69]
	v_mfma_f32_16x16x32_bf16 v[122:125], v[160:163], v[192:195], v[122:125]
	v_mfma_f32_16x16x32_bf16 v[114:117], v[168:171], v[192:195], v[114:117]
	v_mfma_f32_16x16x32_bf16 v[106:109], v[160:163], v[202:205], v[106:109]
	v_mfma_f32_16x16x32_bf16 v[98:101], v[168:171], v[202:205], v[98:101]
	v_mfma_f32_16x16x32_bf16 v[90:93], v[160:163], v[210:213], v[90:93]
	v_mfma_f32_16x16x32_bf16 v[82:85], v[168:171], v[210:213], v[82:85]
	v_mfma_f32_16x16x32_bf16 v[74:77], v[160:163], v[218:221], v[74:77]
	v_mfma_f32_16x16x32_bf16 v[66:69], v[168:171], v[218:221], v[66:69]
	s_setprio 0
	s_setprio 1
	v_mfma_f32_16x16x32_bf16 v[126:129], v[172:175], v[188:191], v[126:129]
	v_mfma_f32_16x16x32_bf16 v[118:121], v[180:183], v[188:191], v[118:121]
	v_mfma_f32_16x16x32_bf16 v[110:113], v[172:175], v[198:201], v[110:113]
	v_mfma_f32_16x16x32_bf16 v[102:105], v[180:183], v[198:201], v[102:105]
	v_mfma_f32_16x16x32_bf16 v[94:97], v[172:175], v[206:209], v[94:97]
	v_mfma_f32_16x16x32_bf16 v[86:89], v[180:183], v[206:209], v[86:89]
	v_mfma_f32_16x16x32_bf16 v[78:81], v[172:175], v[214:217], v[78:81]
	v_mfma_f32_16x16x32_bf16 v[70:73], v[180:183], v[214:217], v[70:73]
	v_mfma_f32_16x16x32_bf16 v[126:129], v[176:179], v[192:195], v[126:129]
	v_mfma_f32_16x16x32_bf16 v[118:121], v[184:187], v[192:195], v[118:121]
	v_mfma_f32_16x16x32_bf16 v[110:113], v[176:179], v[202:205], v[110:113]
	v_mfma_f32_16x16x32_bf16 v[102:105], v[184:187], v[202:205], v[102:105]
	v_mfma_f32_16x16x32_bf16 v[94:97], v[176:179], v[210:213], v[94:97]
	v_mfma_f32_16x16x32_bf16 v[86:89], v[184:187], v[210:213], v[86:89]
	v_mfma_f32_16x16x32_bf16 v[78:81], v[176:179], v[218:221], v[78:81]
	v_mfma_f32_16x16x32_bf16 v[70:73], v[184:187], v[218:221], v[70:73]
	s_setprio 0
	s_barrier
; #define PG8_STAGE(bufoff, gbase, voff) do { _Pragma("unroll") for (int _i = 0; _i < 2; ++_i) \
;         __builtin_amdgcn_global_load_lds((const unsigned*)((const char*)(gbase) + (voff)[_i]), (PG8_LAS unsigned*)(lds + (bufoff) + ldsw + _i * 8192), 16, 0, 0); } while (0)
; #define PG8_LDA(dst, b, h) do { _Pragma("unroll") for (int m = 0; m < 4; ++m) _Pragma("unroll") for (int k = 0; k < 2; ++k) dst[m][k] = *(const PG8_LAS bf16x8*)(lds + PG8_SA(b, h) + aoff + m * 2048 + k * 1024); } while (0)
; #define PG8_LDB(dst, b, h) do { _Pragma("unroll") for (int n = 0; n < 2; ++n) _Pragma("unroll") for (int k = 0; k < 2; ++k) dst[n][k] = *(const PG8_LAS bf16x8*)(lds + PG8_SB(b, h) + boff + n * 2048 + k * 1024); } while (0)
; #define PG8_MMA(ai, bj, At, Bt) do { __builtin_amdgcn_s_setprio(1); _Pragma("unroll") for (int m = 0; m < 4; ++m) _Pragma("unroll") for (int n = 0; n < 2; ++n) _Pragma("unroll") for (int k = 0; k < 2; ++k) \
;         acc[ai][bj][m][n] = __builtin_amdgcn_mfma_f32_16x16x32_bf16(Bt[n][k], At[m][k], acc[ai][bj][m][n], 0, 0, 0); __builtin_amdgcn_s_setprio(0); } while (0)
; #define PG8_WAIT_V(n) asm volatile("s_waitcnt vmcnt(" #n ")" ::: "memory")
; #define PG8_WAIT_L(n) asm volatile("s_waitcnt lgkmcnt(" #n ")" ::: "memory")
; #define PG8_BAR __builtin_amdgcn_s_barrier()
; #define PG8_SCHED __builtin_amdgcn_sched_barrier(0)
; template <class Epi, class Sched, bool ALIGN_EPI = false, bool SP2 = false>
; __device__ __forceinline__ void gemm_phase(PG8_LAS unsigned char* lds, const Gemm g, const Sched& S, const Epi& E) {
;     ...
;         for (int t = 0; t < nt; t += 2) {
;             const bool last = (t == nt - 2);
;             const char* a1 = cA + (size_t)(t + 1) * kstep;
;             const char* a2 = last ? nA : cA + (size_t)(t + 2) * kstep; const char* b2 = last ? nB : cB + (size_t)(t + 2) * kstep;
;             const char* a3 = a2 + kstep; const char* b3 = b2 + kstep;
;             if (last && has_next) S.a_ready(nxt);
;             if constexpr (SP2) {
;             PG8_LDB(B0, 0, 0); PG8_LDB(B1, 0, 1); PG8_SCHED; PG8_LDA(At, 0, 0); PG8_STAGE(PG8_SA(1, 1), a1 + hstep, voffA);
;     ...
;             PG8_LDA(At, 1, 1); PG8_STAGE(PG8_SB(1, 0), b3, voffB); PG8_STAGE(PG8_SB(1, 1), b3 + hstep, voffB); PG8_STAGE(PG8_SA(1, 0), a3, voffA);
;             PG8_WAIT_V(8); PG8_WAIT_L(0); PG8_BAR; PG8_MMA(1, 0, At, B0); PG8_MMA(1, 1, At, B1); PG8_BAR; PG8_SCHED;
	s_add_i32 s48, s75, s52
	v_lshl_add_u64 v[146:147], v[146:147], 0, s[12:13]
	s_mov_b32 m0, s48
	ds_read_b128 v[188:191], v154 offset:49152
	ds_read_b128 v[192:195], v154 offset:50176
	ds_read_b128 v[198:201], v154 offset:51200
	ds_read_b128 v[202:205], v154 offset:52224
	ds_read_b128 v[206:209], v154 offset:53248
	ds_read_b128 v[210:213], v154 offset:54272
	ds_read_b128 v[214:217], v154 offset:55296
	ds_read_b128 v[218:221], v154 offset:56320
	global_load_lds_dwordx4 v[146:147], off
	s_add_i32 m0, s48, 0x2000
	s_add_u32 s46, s46, 0x100080
	v_lshl_add_u64 v[146:147], v[222:223], 0, s[12:13]
	s_addc_u32 s47, s47, 0
	s_add_i32 s48, s76, s52
	global_load_lds_dwordx4 v[146:147], off
	v_lshl_add_u64 v[146:147], s[46:47], 0, v[134:135]
	s_mov_b32 m0, s48
	s_nop 0
	global_load_lds_dwordx4 v[146:147], off
	v_lshl_add_u64 v[146:147], s[46:47], 0, v[130:131]
	s_add_i32 m0, s48, 0x2000
	s_nop 0
	global_load_lds_dwordx4 v[146:147], off
	v_lshl_add_u64 v[146:147], v[224:225], 0, s[12:13]
	s_mov_b32 m0, s59
	s_nop 0
	global_load_lds_dwordx4 v[146:147], off
	v_lshl_add_u64 v[146:147], v[226:227], 0, s[12:13]
	s_mov_b32 m0, s60
	s_nop 0
	global_load_lds_dwordx4 v[146:147], off
	s_waitcnt vmcnt(8)
	s_waitcnt lgkmcnt(0)
	s_nop 0
	s_setprio 1
	s_barrier
	v_mfma_f32_16x16x32_bf16 v[58:61], v[156:159], v[188:191], v[58:61]
	v_mfma_f32_16x16x32_bf16 v[50:53], v[164:167], v[188:191], v[50:53]
	v_mfma_f32_16x16x32_bf16 v[42:45], v[156:159], v[198:201], v[42:45]
	v_mfma_f32_16x16x32_bf16 v[34:37], v[164:167], v[198:201], v[34:37]
	v_mfma_f32_16x16x32_bf16 v[26:29], v[156:159], v[206:209], v[26:29]
	v_mfma_f32_16x16x32_bf16 v[18:21], v[164:167], v[206:209], v[18:21]
	v_mfma_f32_16x16x32_bf16 v[10:13], v[156:159], v[214:217], v[10:13]
	v_mfma_f32_16x16x32_bf16 v[6:9], v[164:167], v[214:217], v[6:9]
	v_mfma_f32_16x16x32_bf16 v[58:61], v[160:163], v[192:195], v[58:61]
	v_mfma_f32_16x16x32_bf16 v[50:53], v[168:171], v[192:195], v[50:53]
	v_mfma_f32_16x16x32_bf16 v[42:45], v[160:163], v[202:205], v[42:45]
	v_mfma_f32_16x16x32_bf16 v[34:37], v[168:171], v[202:205], v[34:37]
	v_mfma_f32_16x16x32_bf16 v[26:29], v[160:163], v[210:213], v[26:29]
	v_mfma_f32_16x16x32_bf16 v[18:21], v[168:171], v[210:213], v[18:21]
	v_mfma_f32_16x16x32_bf16 v[10:13], v[160:163], v[218:221], v[10:13]
	v_mfma_f32_16x16x32_bf16 v[6:9], v[168:171], v[218:221], v[6:9]
	s_setprio 0
	s_setprio 1
	v_mfma_f32_16x16x32_bf16 v[62:65], v[172:175], v[188:191], v[62:65]
	v_mfma_f32_16x16x32_bf16 v[54:57], v[180:183], v[188:191], v[54:57]
	v_mfma_f32_16x16x32_bf16 v[46:49], v[172:175], v[198:201], v[46:49]
	v_mfma_f32_16x16x32_bf16 v[38:41], v[180:183], v[198:201], v[38:41]
	v_mfma_f32_16x16x32_bf16 v[30:33], v[172:175], v[206:209], v[30:33]
	v_mfma_f32_16x16x32_bf16 v[22:25], v[180:183], v[206:209], v[22:25]
	v_mfma_f32_16x16x32_bf16 v[14:17], v[172:175], v[214:217], v[14:17]
	v_mfma_f32_16x16x32_bf16 v[2:5], v[180:183], v[214:217], v[2:5]
	v_mfma_f32_16x16x32_bf16 v[62:65], v[176:179], v[192:195], v[62:65]
	v_mfma_f32_16x16x32_bf16 v[54:57], v[184:187], v[192:195], v[54:57]
	v_mfma_f32_16x16x32_bf16 v[46:49], v[176:179], v[202:205], v[46:49]
	v_mfma_f32_16x16x32_bf16 v[38:41], v[184:187], v[202:205], v[38:41]
	v_mfma_f32_16x16x32_bf16 v[30:33], v[176:179], v[210:213], v[30:33]
	v_mfma_f32_16x16x32_bf16 v[22:25], v[184:187], v[210:213], v[22:25]
	v_mfma_f32_16x16x32_bf16 v[14:17], v[176:179], v[218:221], v[14:17]
	v_mfma_f32_16x16x32_bf16 v[2:5], v[184:187], v[218:221], v[2:5]
	s_setprio 0
	s_barrier
	s_add_i32 s74, s74, 2
	s_add_u32 s44, s44, 0x100
	s_addc_u32 s45, s45, 0
	s_add_u32 s72, s72, 0x100
	s_addc_u32 s73, s73, 0
	s_cmp_gt_u32 s74, 61
	.p2align	3
.LBB0_881:
	ds_read_b128 v[156:159], v152
	ds_read_b128 v[160:163], v152 offset:1024
	ds_read_b128 v[164:167], v152 offset:2048
	ds_read_b128 v[168:171], v152 offset:3072
	ds_read_b128 v[172:175], v153
	ds_read_b128 v[176:179], v153 offset:1024
	ds_read_b128 v[180:183], v153 offset:2048
	ds_read_b128 v[184:187], v153 offset:3072
	s_add_u32 s46, s44, 0xfff00080
	s_addc_u32 s47, s45, -1
	s_cmp_eq_u32 s74, 60
	s_cselect_b32 s49, s37, s47
	s_cselect_b32 s48, s70, s46
	s_cselect_b32 s47, s35, s73
	s_cselect_b32 s46, s71, s72
	v_lshl_add_u64 v[146:147], s[44:45], 0, v[138:139]
	s_add_i32 m0, s43, 0xc000
	ds_read_b128 v[188:191], v154
	ds_read_b128 v[192:195], v154 offset:1024
	ds_read_b128 v[198:201], v154 offset:2048
	ds_read_b128 v[202:205], v154 offset:3072
	ds_read_b128 v[206:209], v154 offset:4096
	ds_read_b128 v[210:213], v154 offset:5120
	ds_read_b128 v[214:217], v154 offset:6144
	ds_read_b128 v[218:221], v154 offset:7168
	global_load_lds_dwordx4 v[146:147], off
	v_lshl_add_u64 v[146:147], s[44:45], 0, v[140:141]
	s_add_i32 m0, s43, 0xe000
	s_nop 0
	global_load_lds_dwordx4 v[146:147], off
	s_waitcnt vmcnt(8)
	s_waitcnt lgkmcnt(0)
	s_nop 0
	s_setprio 1
	s_barrier
; #define PG8_STAGE(bufoff, gbase, voff) do { _Pragma("unroll") for (int _i = 0; _i < 2; ++_i) \
;         __builtin_amdgcn_global_load_lds((const unsigned*)((const char*)(gbase) + (voff)[_i]), (PG8_LAS unsigned*)(lds + (bufoff) + ldsw + _i * 8192), 16, 0, 0); } while (0)
; #define PG8_LDA(dst, b, h) do { _Pragma("unroll") for (int m = 0; m < 4; ++m) _Pragma("unroll") for (int k = 0; k < 2; ++k) dst[m][k] = *(const PG8_LAS bf16x8*)(lds + PG8_SA(b, h) + aoff + m * 2048 + k * 1024); } while (0)
; #define PG8_MMA(ai, bj, At, Bt) do { __builtin_amdgcn_s_setprio(1); _Pragma("unroll") for (int m = 0; m < 4; ++m) _Pragma("unroll") for (int n = 0; n < 2; ++n) _Pragma("unroll") for (int k = 0; k < 2; ++k) \
;         acc[ai][bj][m][n] = __builtin_amdgcn_mfma_f32_16x16x32_bf16(Bt[n][k], At[m][k], acc[ai][bj][m][n], 0, 0, 0); __builtin_amdgcn_s_setprio(0); } while (0)
; #define PG8_WAIT_V(n) asm volatile("s_waitcnt vmcnt(" #n ")" ::: "memory")
; #define PG8_WAIT_L(n) asm volatile("s_waitcnt lgkmcnt(" #n ")" ::: "memory")
; #define PG8_BAR __builtin_amdgcn_s_barrier()
; #define PG8_SCHED __builtin_amdgcn_sched_barrier(0)
; template <class Epi, class Sched, bool ALIGN_EPI = false, bool SP2 = false>
; __device__ __forceinline__ void gemm_phase(PG8_LAS unsigned char* lds, const Gemm g, const Sched& S, const Epi& E) {
;     ...
;             PG8_WAIT_V(8); PG8_WAIT_L(0); PG8_BAR; PG8_MMA(0, 0, At, B0); PG8_MMA(0, 1, At, B1); PG8_BAR; PG8_SCHED;
;             PG8_LDA(At, 0, 1); PG8_STAGE(PG8_SB(0, 0), b2, voffB); PG8_STAGE(PG8_SB(0, 1), b2 + hstep, voffB); PG8_STAGE(PG8_SA(0, 0), a2, voffA);
;             PG8_WAIT_V(8); PG8_WAIT_L(0); PG8_BAR; PG8_MMA(1, 0, At, B0); PG8_MMA(1, 1, At, B1); PG8_BAR; PG8_SCHED;
	v_mfma_f32_16x16x32_bf16 v[122:125], v[156:159], v[188:191], v[122:125]
	v_mfma_f32_16x16x32_bf16 v[114:117], v[164:167], v[188:191], v[114:117]
	v_mfma_f32_16x16x32_bf16 v[106:109], v[156:159], v[198:201], v[106:109]
	v_mfma_f32_16x16x32_bf16 v[98:101], v[164:167], v[198:201], v[98:101]
	v_mfma_f32_16x16x32_bf16 v[90:93], v[156:159], v[206:209], v[90:93]
	v_mfma_f32_16x16x32_bf16 v[82:85], v[164:167], v[206:209], v[82:85]
	v_mfma_f32_16x16x32_bf16 v[74:77], v[156:159], v[214:217], v[74:77]
	v_mfma_f32_16x16x32_bf16 v[66:69], v[164:167], v[214:217], v[66:69]
	v_mfma_f32_16x16x32_bf16 v[122:125], v[160:163], v[192:195], v[122:125]
	v_mfma_f32_16x16x32_bf16 v[114:117], v[168:171], v[192:195], v[114:117]
	v_mfma_f32_16x16x32_bf16 v[106:109], v[160:163], v[202:205], v[106:109]
	v_mfma_f32_16x16x32_bf16 v[98:101], v[168:171], v[202:205], v[98:101]
	v_mfma_f32_16x16x32_bf16 v[90:93], v[160:163], v[210:213], v[90:93]
	v_mfma_f32_16x16x32_bf16 v[82:85], v[168:171], v[210:213], v[82:85]
	v_mfma_f32_16x16x32_bf16 v[74:77], v[160:163], v[218:221], v[74:77]
	v_mfma_f32_16x16x32_bf16 v[66:69], v[168:171], v[218:221], v[66:69]
	s_setprio 0
	s_setprio 1
	v_mfma_f32_16x16x32_bf16 v[126:129], v[172:175], v[188:191], v[126:129]
	v_mfma_f32_16x16x32_bf16 v[118:121], v[180:183], v[188:191], v[118:121]
	v_mfma_f32_16x16x32_bf16 v[110:113], v[172:175], v[198:201], v[110:113]
	v_mfma_f32_16x16x32_bf16 v[102:105], v[180:183], v[198:201], v[102:105]
	v_mfma_f32_16x16x32_bf16 v[94:97], v[172:175], v[206:209], v[94:97]
	v_mfma_f32_16x16x32_bf16 v[86:89], v[180:183], v[206:209], v[86:89]
	v_mfma_f32_16x16x32_bf16 v[78:81], v[172:175], v[214:217], v[78:81]
	v_mfma_f32_16x16x32_bf16 v[70:73], v[180:183], v[214:217], v[70:73]
	v_mfma_f32_16x16x32_bf16 v[126:129], v[176:179], v[192:195], v[126:129]
	v_mfma_f32_16x16x32_bf16 v[118:121], v[184:187], v[192:195], v[118:121]
	v_mfma_f32_16x16x32_bf16 v[110:113], v[176:179], v[202:205], v[110:113]
	v_mfma_f32_16x16x32_bf16 v[102:105], v[184:187], v[202:205], v[102:105]
	v_mfma_f32_16x16x32_bf16 v[94:97], v[176:179], v[210:213], v[94:97]
	v_mfma_f32_16x16x32_bf16 v[86:89], v[184:187], v[210:213], v[86:89]
	v_mfma_f32_16x16x32_bf16 v[78:81], v[176:179], v[218:221], v[78:81]
	v_mfma_f32_16x16x32_bf16 v[70:73], v[184:187], v[218:221], v[70:73]
	s_setprio 0
	s_barrier
	s_add_i32 s75, s63, s52
	v_lshl_add_u64 v[146:147], s[46:47], 0, v[134:135]
	s_mov_b32 m0, s75
	ds_read_b128 v[188:191], v154 offset:16384
	ds_read_b128 v[192:195], v154 offset:17408
	ds_read_b128 v[198:201], v154 offset:18432
	ds_read_b128 v[202:205], v154 offset:19456
	ds_read_b128 v[206:209], v154 offset:20480
	ds_read_b128 v[210:213], v154 offset:21504
	ds_read_b128 v[214:217], v154 offset:22528
	ds_read_b128 v[218:221], v154 offset:23552
	global_load_lds_dwordx4 v[146:147], off
	s_add_i32 m0, s75, 0x2000
	s_add_u32 s76, s46, 0x100000
	v_lshl_add_u64 v[222:223], s[46:47], 0, v[130:131]
	s_addc_u32 s77, s47, 0
	s_add_i32 s75, s67, s52
	global_load_lds_dwordx4 v[222:223], off
	v_lshl_add_u64 v[224:225], s[76:77], 0, v[134:135]
	s_mov_b32 m0, s75
	v_lshl_add_u64 v[226:227], s[48:49], 0, v[132:133]
	global_load_lds_dwordx4 v[224:225], off
	v_lshl_add_u64 v[224:225], s[76:77], 0, v[130:131]
	s_add_i32 m0, s75, 0x2000
	s_nop 0
	global_load_lds_dwordx4 v[224:225], off
	v_lshl_add_u64 v[224:225], s[48:49], 0, v[136:137]
	s_mov_b32 m0, s43
	s_nop 0
	global_load_lds_dwordx4 v[224:225], off
	s_mov_b32 m0, s55
	s_nop 0
	global_load_lds_dwordx4 v[226:227], off
	s_waitcnt vmcnt(8)
	s_waitcnt lgkmcnt(0)
	s_nop 0
	s_setprio 1
	s_barrier
	v_mfma_f32_16x16x32_bf16 v[58:61], v[156:159], v[188:191], v[58:61]
	v_mfma_f32_16x16x32_bf16 v[50:53], v[164:167], v[188:191], v[50:53]
	v_mfma_f32_16x16x32_bf16 v[42:45], v[156:159], v[198:201], v[42:45]
	v_mfma_f32_16x16x32_bf16 v[34:37], v[164:167], v[198:201], v[34:37]
	v_mfma_f32_16x16x32_bf16 v[26:29], v[156:159], v[206:209], v[26:29]
	v_mfma_f32_16x16x32_bf16 v[18:21], v[164:167], v[206:209], v[18:21]
	v_mfma_f32_16x16x32_bf16 v[10:13], v[156:159], v[214:217], v[10:13]
	v_mfma_f32_16x16x32_bf16 v[6:9], v[164:167], v[214:217], v[6:9]
	v_mfma_f32_16x16x32_bf16 v[58:61], v[160:163], v[192:195], v[58:61]
	v_mfma_f32_16x16x32_bf16 v[50:53], v[168:171], v[192:195], v[50:53]
	v_mfma_f32_16x16x32_bf16 v[42:45], v[160:163], v[202:205], v[42:45]
	v_mfma_f32_16x16x32_bf16 v[34:37], v[168:171], v[202:205], v[34:37]
	v_mfma_f32_16x16x32_bf16 v[26:29], v[160:163], v[210:213], v[26:29]
	v_mfma_f32_16x16x32_bf16 v[18:21], v[168:171], v[210:213], v[18:21]
	v_mfma_f32_16x16x32_bf16 v[10:13], v[160:163], v[218:221], v[10:13]
	v_mfma_f32_16x16x32_bf16 v[6:9], v[168:171], v[218:221], v[6:9]
	s_setprio 0
	s_setprio 1
	v_mfma_f32_16x16x32_bf16 v[62:65], v[172:175], v[188:191], v[62:65]
	v_mfma_f32_16x16x32_bf16 v[54:57], v[180:183], v[188:191], v[54:57]
	v_mfma_f32_16x16x32_bf16 v[46:49], v[172:175], v[198:201], v[46:49]
	v_mfma_f32_16x16x32_bf16 v[38:41], v[180:183], v[198:201], v[38:41]
	v_mfma_f32_16x16x32_bf16 v[30:33], v[172:175], v[206:209], v[30:33]
	v_mfma_f32_16x16x32_bf16 v[22:25], v[180:183], v[206:209], v[22:25]
	v_mfma_f32_16x16x32_bf16 v[14:17], v[172:175], v[214:217], v[14:17]
	v_mfma_f32_16x16x32_bf16 v[2:5], v[180:183], v[214:217], v[2:5]
	v_mfma_f32_16x16x32_bf16 v[62:65], v[176:179], v[192:195], v[62:65]
	v_mfma_f32_16x16x32_bf16 v[54:57], v[184:187], v[192:195], v[54:57]
	v_mfma_f32_16x16x32_bf16 v[46:49], v[176:179], v[202:205], v[46:49]
	v_mfma_f32_16x16x32_bf16 v[38:41], v[184:187], v[202:205], v[38:41]
	v_mfma_f32_16x16x32_bf16 v[30:33], v[176:179], v[210:213], v[30:33]
	v_mfma_f32_16x16x32_bf16 v[22:25], v[184:187], v[210:213], v[22:25]
	v_mfma_f32_16x16x32_bf16 v[14:17], v[176:179], v[218:221], v[14:17]
	v_mfma_f32_16x16x32_bf16 v[2:5], v[184:187], v[218:221], v[2:5]
	s_setprio 0
	s_barrier
; #define PG8_STAGE(bufoff, gbase, voff) do { _Pragma("unroll") for (int _i = 0; _i < 2; ++_i) \
;         __builtin_amdgcn_global_load_lds((const unsigned*)((const char*)(gbase) + (voff)[_i]), (PG8_LAS unsigned*)(lds + (bufoff) + ldsw + _i * 8192), 16, 0, 0); } while (0)
; #define PG8_LDA(dst, b, h) do { _Pragma("unroll") for (int m = 0; m < 4; ++m) _Pragma("unroll") for (int k = 0; k < 2; ++k) dst[m][k] = *(const PG8_LAS bf16x8*)(lds + PG8_SA(b, h) + aoff + m * 2048 + k * 1024); } while (0)
; #define PG8_LDB(dst, b, h) do { _Pragma("unroll") for (int n = 0; n < 2; ++n) _Pragma("unroll") for (int k = 0; k < 2; ++k) dst[n][k] = *(const PG8_LAS bf16x8*)(lds + PG8_SB(b, h) + boff + n * 2048 + k * 1024); } while (0)
; #define PG8_MMA(ai, bj, At, Bt) do { __builtin_amdgcn_s_setprio(1); _Pragma("unroll") for (int m = 0; m < 4; ++m) _Pragma("unroll") for (int n = 0; n < 2; ++n) _Pragma("unroll") for (int k = 0; k < 2; ++k) \
;         acc[ai][bj][m][n] = __builtin_amdgcn_mfma_f32_16x16x32_bf16(Bt[n][k], At[m][k], acc[ai][bj][m][n], 0, 0, 0); __builtin_amdgcn_s_setprio(0); } while (0)
; #define PG8_WAIT_V(n) asm volatile("s_waitcnt vmcnt(" #n ")" ::: "memory")
; #define PG8_WAIT_L(n) asm volatile("s_waitcnt lgkmcnt(" #n ")" ::: "memory")
; #define PG8_BAR __builtin_amdgcn_s_barrier()
; #define PG8_SCHED __builtin_amdgcn_sched_barrier(0)
; template <class Epi, class Sched, bool ALIGN_EPI = false, bool SP2 = false>
; __device__ __forceinline__ void gemm_phase(PG8_LAS unsigned char* lds, const Gemm g, const Sched& S, const Epi& E) {
;     ...
;             PG8_LDB(B0, 1, 0); PG8_LDB(B1, 1, 1); PG8_SCHED; PG8_LDA(At, 1, 0); PG8_STAGE(PG8_SA(0, 1), a2 + hstep, voffA);
;             PG8_WAIT_V(8); PG8_WAIT_L(0); PG8_BAR; PG8_MMA(0, 0, At, B0); PG8_MMA(0, 1, At, B1); PG8_BAR; PG8_SCHED;
	s_add_i32 s75, 0, 0x18000
	v_add_u32_e32 v155, s75, v150
	s_add_i32 s76, 0, 0x1c000
	ds_read_b128 v[156:159], v155
	ds_read_b128 v[160:163], v155 offset:1024
	ds_read_b128 v[164:167], v155 offset:2048
	ds_read_b128 v[168:171], v155 offset:3072
	v_add_u32_e32 v155, s76, v150
	ds_read_b128 v[172:175], v155
	ds_read_b128 v[176:179], v155 offset:1024
	ds_read_b128 v[180:183], v155 offset:2048
	ds_read_b128 v[184:187], v155 offset:3072
	s_add_u32 s48, s48, 0x100000
	s_addc_u32 s49, s49, 0
	s_mov_b32 m0, s56
	v_lshl_add_u64 v[228:229], s[48:49], 0, v[136:137]
	ds_read_b128 v[188:191], v154 offset:32768
	ds_read_b128 v[192:195], v154 offset:33792
	ds_read_b128 v[198:201], v154 offset:34816
	ds_read_b128 v[202:205], v154 offset:35840
	ds_read_b128 v[206:209], v154 offset:36864
	ds_read_b128 v[210:213], v154 offset:37888
	ds_read_b128 v[214:217], v154 offset:38912
	ds_read_b128 v[218:221], v154 offset:39936
	global_load_lds_dwordx4 v[228:229], off
	v_lshl_add_u64 v[228:229], s[48:49], 0, v[132:133]
	s_mov_b32 m0, s57
	s_nop 0
	global_load_lds_dwordx4 v[228:229], off
	s_waitcnt vmcnt(8)
	s_waitcnt lgkmcnt(0)
	s_nop 0
	s_setprio 1
	s_barrier
	v_mfma_f32_16x16x32_bf16 v[122:125], v[156:159], v[188:191], v[122:125]
	v_mfma_f32_16x16x32_bf16 v[114:117], v[164:167], v[188:191], v[114:117]
	v_mfma_f32_16x16x32_bf16 v[106:109], v[156:159], v[198:201], v[106:109]
	v_mfma_f32_16x16x32_bf16 v[98:101], v[164:167], v[198:201], v[98:101]
	v_mfma_f32_16x16x32_bf16 v[90:93], v[156:159], v[206:209], v[90:93]
	v_mfma_f32_16x16x32_bf16 v[82:85], v[164:167], v[206:209], v[82:85]
	v_mfma_f32_16x16x32_bf16 v[74:77], v[156:159], v[214:217], v[74:77]
	v_mfma_f32_16x16x32_bf16 v[66:69], v[164:167], v[214:217], v[66:69]
	v_mfma_f32_16x16x32_bf16 v[122:125], v[160:163], v[192:195], v[122:125]
	v_mfma_f32_16x16x32_bf16 v[114:117], v[168:171], v[192:195], v[114:117]
	v_mfma_f32_16x16x32_bf16 v[106:109], v[160:163], v[202:205], v[106:109]
	v_mfma_f32_16x16x32_bf16 v[98:101], v[168:171], v[202:205], v[98:101]
	v_mfma_f32_16x16x32_bf16 v[90:93], v[160:163], v[210:213], v[90:93]
	v_mfma_f32_16x16x32_bf16 v[82:85], v[168:171], v[210:213], v[82:85]
	v_mfma_f32_16x16x32_bf16 v[74:77], v[160:163], v[218:221], v[74:77]
	v_mfma_f32_16x16x32_bf16 v[66:69], v[168:171], v[218:221], v[66:69]
	s_setprio 0
	s_setprio 1
	v_mfma_f32_16x16x32_bf16 v[126:129], v[172:175], v[188:191], v[126:129]
	v_mfma_f32_16x16x32_bf16 v[118:121], v[180:183], v[188:191], v[118:121]
	v_mfma_f32_16x16x32_bf16 v[110:113], v[172:175], v[198:201], v[110:113]
	v_mfma_f32_16x16x32_bf16 v[102:105], v[180:183], v[198:201], v[102:105]
	v_mfma_f32_16x16x32_bf16 v[94:97], v[172:175], v[206:209], v[94:97]
	v_mfma_f32_16x16x32_bf16 v[86:89], v[180:183], v[206:209], v[86:89]
	v_mfma_f32_16x16x32_bf16 v[78:81], v[172:175], v[214:217], v[78:81]
	v_mfma_f32_16x16x32_bf16 v[70:73], v[180:183], v[214:217], v[70:73]
	v_mfma_f32_16x16x32_bf16 v[126:129], v[176:179], v[192:195], v[126:129]
	v_mfma_f32_16x16x32_bf16 v[118:121], v[184:187], v[192:195], v[118:121]
	v_mfma_f32_16x16x32_bf16 v[110:113], v[176:179], v[202:205], v[110:113]
	v_mfma_f32_16x16x32_bf16 v[102:105], v[184:187], v[202:205], v[102:105]
	v_mfma_f32_16x16x32_bf16 v[94:97], v[176:179], v[210:213], v[94:97]
	v_mfma_f32_16x16x32_bf16 v[86:89], v[184:187], v[210:213], v[86:89]
	v_mfma_f32_16x16x32_bf16 v[78:81], v[176:179], v[218:221], v[78:81]
	v_mfma_f32_16x16x32_bf16 v[70:73], v[184:187], v[218:221], v[70:73]
	s_setprio 0
	s_barrier
; #define PG8_STAGE(bufoff, gbase, voff) do { _Pragma("unroll") for (int _i = 0; _i < 2; ++_i) \
;         __builtin_amdgcn_global_load_lds((const unsigned*)((const char*)(gbase) + (voff)[_i]), (PG8_LAS unsigned*)(lds + (bufoff) + ldsw + _i * 8192), 16, 0, 0); } while (0)
; #define PG8_LDA(dst, b, h) do { _Pragma("unroll") for (int m = 0; m < 4; ++m) _Pragma("unroll") for (int k = 0; k < 2; ++k) dst[m][k] = *(const PG8_LAS bf16x8*)(lds + PG8_SA(b, h) + aoff + m * 2048 + k * 1024); } while (0)
; #define PG8_MMA(ai, bj, At, Bt) do { __builtin_amdgcn_s_setprio(1); _Pragma("unroll") for (int m = 0; m < 4; ++m) _Pragma("unroll") for (int n = 0; n < 2; ++n) _Pragma("unroll") for (int k = 0; k < 2; ++k) \
;         acc[ai][bj][m][n] = __builtin_amdgcn_mfma_f32_16x16x32_bf16(Bt[n][k], At[m][k], acc[ai][bj][m][n], 0, 0, 0); __builtin_amdgcn_s_setprio(0); } while (0)
; #define PG8_WAIT_V(n) asm volatile("s_waitcnt vmcnt(" #n ")" ::: "memory")
; #define PG8_WAIT_L(n) asm volatile("s_waitcnt lgkmcnt(" #n ")" ::: "memory")
; #define PG8_BAR __builtin_amdgcn_s_barrier()
; #define PG8_SCHED __builtin_amdgcn_sched_barrier(0)
; template <class Epi, class Sched, bool ALIGN_EPI = false, bool SP2 = false>
; __device__ __forceinline__ void gemm_phase(PG8_LAS unsigned char* lds, const Gemm g, const Sched& S, const Epi& E) {
;     ...
;             PG8_LDA(At, 1, 1); PG8_STAGE(PG8_SB(1, 0), b3, voffB); PG8_STAGE(PG8_SB(1, 1), b3 + hstep, voffB); PG8_STAGE(PG8_SA(1, 0), a3, voffA);
;             PG8_WAIT_V(8); PG8_WAIT_L(0); PG8_BAR; PG8_MMA(1, 0, At, B0); PG8_MMA(1, 1, At, B1); PG8_BAR; PG8_SCHED;
;     ...
;         if constexpr (ALIGN_EPI) { if (wr == 0) PG8_BAR; }
	s_add_i32 s48, s75, s52
	v_lshl_add_u64 v[146:147], v[146:147], 0, s[12:13]
	s_mov_b32 m0, s48
	ds_read_b128 v[188:191], v154 offset:49152
	ds_read_b128 v[192:195], v154 offset:50176
	ds_read_b128 v[198:201], v154 offset:51200
	ds_read_b128 v[202:205], v154 offset:52224
	ds_read_b128 v[206:209], v154 offset:53248
	ds_read_b128 v[210:213], v154 offset:54272
	ds_read_b128 v[214:217], v154 offset:55296
	ds_read_b128 v[218:221], v154 offset:56320
	global_load_lds_dwordx4 v[146:147], off
	s_add_i32 m0, s48, 0x2000
	s_add_u32 s46, s46, 0x100080
	v_lshl_add_u64 v[146:147], v[222:223], 0, s[12:13]
	s_addc_u32 s47, s47, 0
	s_add_i32 s48, s76, s52
	global_load_lds_dwordx4 v[146:147], off
	v_lshl_add_u64 v[146:147], s[46:47], 0, v[134:135]
	s_mov_b32 m0, s48
	s_nop 0
	global_load_lds_dwordx4 v[146:147], off
	v_lshl_add_u64 v[146:147], s[46:47], 0, v[130:131]
	s_add_i32 m0, s48, 0x2000
	s_nop 0
	global_load_lds_dwordx4 v[146:147], off
	v_lshl_add_u64 v[146:147], v[224:225], 0, s[12:13]
	s_mov_b32 m0, s59
	s_nop 0
	global_load_lds_dwordx4 v[146:147], off
	v_lshl_add_u64 v[146:147], v[226:227], 0, s[12:13]
	s_mov_b32 m0, s60
	s_nop 0
	global_load_lds_dwordx4 v[146:147], off
	s_waitcnt vmcnt(8)
	s_waitcnt lgkmcnt(0)
	s_nop 0
	s_setprio 1
	s_barrier
	v_mfma_f32_16x16x32_bf16 v[58:61], v[156:159], v[188:191], v[58:61]
	v_mfma_f32_16x16x32_bf16 v[50:53], v[164:167], v[188:191], v[50:53]
	v_mfma_f32_16x16x32_bf16 v[42:45], v[156:159], v[198:201], v[42:45]
	v_mfma_f32_16x16x32_bf16 v[34:37], v[164:167], v[198:201], v[34:37]
	v_mfma_f32_16x16x32_bf16 v[26:29], v[156:159], v[206:209], v[26:29]
	v_mfma_f32_16x16x32_bf16 v[18:21], v[164:167], v[206:209], v[18:21]
	v_mfma_f32_16x16x32_bf16 v[10:13], v[156:159], v[214:217], v[10:13]
	v_mfma_f32_16x16x32_bf16 v[6:9], v[164:167], v[214:217], v[6:9]
	v_mfma_f32_16x16x32_bf16 v[58:61], v[160:163], v[192:195], v[58:61]
	v_mfma_f32_16x16x32_bf16 v[50:53], v[168:171], v[192:195], v[50:53]
	v_mfma_f32_16x16x32_bf16 v[42:45], v[160:163], v[202:205], v[42:45]
	v_mfma_f32_16x16x32_bf16 v[34:37], v[168:171], v[202:205], v[34:37]
	v_mfma_f32_16x16x32_bf16 v[26:29], v[160:163], v[210:213], v[26:29]
	v_mfma_f32_16x16x32_bf16 v[18:21], v[168:171], v[210:213], v[18:21]
	v_mfma_f32_16x16x32_bf16 v[10:13], v[160:163], v[218:221], v[10:13]
	v_mfma_f32_16x16x32_bf16 v[6:9], v[168:171], v[218:221], v[6:9]
	s_setprio 0
	s_setprio 1
	v_mfma_f32_16x16x32_bf16 v[62:65], v[172:175], v[188:191], v[62:65]
	v_mfma_f32_16x16x32_bf16 v[54:57], v[180:183], v[188:191], v[54:57]
	v_mfma_f32_16x16x32_bf16 v[46:49], v[172:175], v[198:201], v[46:49]
	v_mfma_f32_16x16x32_bf16 v[38:41], v[180:183], v[198:201], v[38:41]
	v_mfma_f32_16x16x32_bf16 v[30:33], v[172:175], v[206:209], v[30:33]
	v_mfma_f32_16x16x32_bf16 v[22:25], v[180:183], v[206:209], v[22:25]
	v_mfma_f32_16x16x32_bf16 v[14:17], v[172:175], v[214:217], v[14:17]
	v_mfma_f32_16x16x32_bf16 v[2:5], v[180:183], v[214:217], v[2:5]
	v_mfma_f32_16x16x32_bf16 v[62:65], v[176:179], v[192:195], v[62:65]
	v_mfma_f32_16x16x32_bf16 v[54:57], v[184:187], v[192:195], v[54:57]
	v_mfma_f32_16x16x32_bf16 v[46:49], v[176:179], v[202:205], v[46:49]
	v_mfma_f32_16x16x32_bf16 v[38:41], v[184:187], v[202:205], v[38:41]
	v_mfma_f32_16x16x32_bf16 v[30:33], v[176:179], v[210:213], v[30:33]
	v_mfma_f32_16x16x32_bf16 v[22:25], v[184:187], v[210:213], v[22:25]
	v_mfma_f32_16x16x32_bf16 v[14:17], v[176:179], v[218:221], v[14:17]
	v_mfma_f32_16x16x32_bf16 v[2:5], v[184:187], v[218:221], v[2:5]
	s_setprio 0
	s_barrier
	s_add_i32 s74, s74, 2
	s_add_u32 s44, s44, 0x100
	s_addc_u32 s45, s45, 0
	s_add_u32 s72, s72, 0x100
	s_addc_u32 s73, s73, 0
	s_cmp_gt_u32 s74, 61
	s_cbranch_scc0 .LBB0_881
	s_and_b64 vcc, exec, s[16:17]
	s_cbranch_vccz .LBB0_884
	s_barrier

; #define PG8_STAGE(bufoff, gbase, voff) do { _Pragma("unroll") for (int _i = 0; _i < 2; ++_i) \
;         __builtin_amdgcn_global_load_lds((const unsigned*)((const char*)(gbase) + (voff)[_i]), (PG8_LAS unsigned*)(lds + (bufoff) + ldsw + _i * 8192), 16, 0, 0); } while (0)
; #define PG8_LDA(dst, b, h) do { _Pragma("unroll") for (int m = 0; m < 4; ++m) _Pragma("unroll") for (int k = 0; k < 2; ++k) dst[m][k] = *(const PG8_LAS bf16x8*)(lds + PG8_SA(b, h) + aoff + m * 2048 + k * 1024); } while (0)
; #define PG8_LDB(dst, b, h) do { _Pragma("unroll") for (int n = 0; n < 2; ++n) _Pragma("unroll") for (int k = 0; k < 2; ++k) dst[n][k] = *(const PG8_LAS bf16x8*)(lds + PG8_SB(b, h) + boff + n * 2048 + k * 1024); } while (0)
; #define PG8_WAIT_V(n) asm volatile("s_waitcnt vmcnt(" #n ")" ::: "memory")
; #define PG8_WAIT_L(n) asm volatile("s_waitcnt lgkmcnt(" #n ")" ::: "memory")
; #define PG8_BAR __builtin_amdgcn_s_barrier()
; #define PG8_SCHED __builtin_amdgcn_sched_barrier(0)
; template <class Epi, class Sched, bool ALIGN_EPI = false, bool SP2 = false>
; __device__ __forceinline__ void gemm_phase(PG8_LAS unsigned char* lds, const Gemm g, const Sched& S, const Epi& E) {
;     ...
;         const char* nA = has_next ? (const char*)g.A + (size_t)nxt.pm * tstep : cA; const char* nB = has_next ? (const char*)g.Bt + (size_t)nxt.pn * tstep : cB;
;         for (int t = 0; t < nt; t += 2) {
;             const bool last = (t == nt - 2);
;             const char* a1 = cA + (size_t)(t + 1) * kstep;
;             const char* a2 = last ? nA : cA + (size_t)(t + 2) * kstep; const char* b2 = last ? nB : cB + (size_t)(t + 2) * kstep;
;             const char* a3 = a2 + kstep; const char* b3 = b2 + kstep;
;             if (last && has_next) S.a_ready(nxt);
;             if constexpr (SP2) {
;             PG8_LDB(B0, 0, 0); PG8_LDB(B1, 0, 1); PG8_SCHED; PG8_LDA(At, 0, 0); PG8_STAGE(PG8_SA(1, 1), a1 + hstep, voffA);
;             PG8_WAIT_V(8); PG8_WAIT_L(0); PG8_BAR; PG8_MMA(0, 0, At, B0); PG8_MMA(0, 1, At, B1); PG8_BAR; PG8_SCHED;
;             PG8_LDA(At, 0, 1); PG8_STAGE(PG8_SB(0, 0), b2, voffB); PG8_STAGE(PG8_SB(0, 1), b2 + hstep, voffB); PG8_STAGE(PG8_SA(0, 0), a2, voffA);
;             PG8_WAIT_V(8); PG8_WAIT_L(0); PG8_BAR; PG8_MMA(1, 0, At, B0); PG8_MMA(1, 1, At, B1); PG8_BAR; PG8_SCHED;
.LBB0_983:
	s_add_u32 s42, s42, 0x2b0080
	s_addc_u32 s43, s43, 0
	s_add_u32 s69, s44, 0x100
	s_addc_u32 s70, s45, 0
	s_mov_b32 s71, -2
	s_waitcnt lgkmcnt(0)
	.p2align	3
	ds_read_b128 v[146:149], v160
	ds_read_b128 v[164:167], v160 offset:1024
	ds_read_b128 v[168:171], v160 offset:2048
	ds_read_b128 v[172:175], v160 offset:3072
	ds_read_b128 v[176:179], v161
	ds_read_b128 v[180:183], v161 offset:1024
	ds_read_b128 v[184:187], v161 offset:2048
	ds_read_b128 v[188:191], v161 offset:3072
	s_add_u32 s44, s42, 0xffd50080
	s_addc_u32 s45, s43, -1
	s_cmpk_eq_i32 s71, 0xa8
	s_cselect_b32 s47, s7, s45
	s_cselect_b32 s46, s6, s44
	s_cselect_b32 s45, s41, s70
	s_cselect_b32 s44, s40, s69
	v_lshl_add_u64 v[226:227], s[42:43], 0, v[138:139]
	s_add_i32 m0, s52, 0xc000
	ds_read_b128 v[192:195], v162
	ds_read_b128 v[198:201], v162 offset:1024
	ds_read_b128 v[202:205], v162 offset:2048
	ds_read_b128 v[206:209], v162 offset:3072
	ds_read_b128 v[210:213], v162 offset:4096
	ds_read_b128 v[214:217], v162 offset:5120
	ds_read_b128 v[218:221], v162 offset:6144
	ds_read_b128 v[222:225], v162 offset:7168
	global_load_lds_dwordx4 v[226:227], off
	v_lshl_add_u64 v[226:227], s[42:43], 0, v[140:141]
	s_add_i32 m0, s52, 0xe000
	s_nop 0
	global_load_lds_dwordx4 v[226:227], off
	s_waitcnt vmcnt(8)
	s_waitcnt lgkmcnt(0)
	s_nop 0
	s_setprio 1
	s_barrier
	v_mfma_f32_16x16x32_bf16 v[126:129], v[146:149], v[192:195], 0
	v_mfma_f32_16x16x32_bf16 v[122:125], v[168:171], v[192:195], 0
	v_mfma_f32_16x16x32_bf16 v[110:113], v[146:149], v[202:205], 0
	v_mfma_f32_16x16x32_bf16 v[106:109], v[168:171], v[202:205], 0
	v_mfma_f32_16x16x32_bf16 v[94:97], v[146:149], v[210:213], 0
	v_mfma_f32_16x16x32_bf16 v[90:93], v[168:171], v[210:213], 0
	v_mfma_f32_16x16x32_bf16 v[78:81], v[146:149], v[218:221], 0
	v_mfma_f32_16x16x32_bf16 v[74:77], v[168:171], v[218:221], 0
	v_mfma_f32_16x16x32_bf16 v[126:129], v[164:167], v[198:201], v[126:129]
	v_mfma_f32_16x16x32_bf16 v[122:125], v[172:175], v[198:201], v[122:125]
	v_mfma_f32_16x16x32_bf16 v[110:113], v[164:167], v[206:209], v[110:113]
	v_mfma_f32_16x16x32_bf16 v[106:109], v[172:175], v[206:209], v[106:109]
	v_mfma_f32_16x16x32_bf16 v[94:97], v[164:167], v[214:217], v[94:97]
	v_mfma_f32_16x16x32_bf16 v[90:93], v[172:175], v[214:217], v[90:93]
	v_mfma_f32_16x16x32_bf16 v[78:81], v[164:167], v[222:225], v[78:81]
	v_mfma_f32_16x16x32_bf16 v[74:77], v[172:175], v[222:225], v[74:77]
	s_setprio 0
	s_setprio 1
	v_mfma_f32_16x16x32_bf16 v[118:121], v[176:179], v[192:195], 0
	v_mfma_f32_16x16x32_bf16 v[114:117], v[184:187], v[192:195], 0
	v_mfma_f32_16x16x32_bf16 v[102:105], v[176:179], v[202:205], 0
	v_mfma_f32_16x16x32_bf16 v[98:101], v[184:187], v[202:205], 0
	v_mfma_f32_16x16x32_bf16 v[86:89], v[176:179], v[210:213], 0
	v_mfma_f32_16x16x32_bf16 v[82:85], v[184:187], v[210:213], 0
	v_mfma_f32_16x16x32_bf16 v[70:73], v[176:179], v[218:221], 0
	v_mfma_f32_16x16x32_bf16 v[66:69], v[184:187], v[218:221], 0
	v_mfma_f32_16x16x32_bf16 v[118:121], v[180:183], v[198:201], v[118:121]
	v_mfma_f32_16x16x32_bf16 v[114:117], v[188:191], v[198:201], v[114:117]
	v_mfma_f32_16x16x32_bf16 v[102:105], v[180:183], v[206:209], v[102:105]
	v_mfma_f32_16x16x32_bf16 v[98:101], v[188:191], v[206:209], v[98:101]
	v_mfma_f32_16x16x32_bf16 v[86:89], v[180:183], v[214:217], v[86:89]
	v_mfma_f32_16x16x32_bf16 v[82:85], v[188:191], v[214:217], v[82:85]
	v_mfma_f32_16x16x32_bf16 v[70:73], v[180:183], v[222:225], v[70:73]
	v_mfma_f32_16x16x32_bf16 v[66:69], v[188:191], v[222:225], v[66:69]
	s_setprio 0
	s_barrier
	s_add_i32 s72, s62, s51
	v_lshl_add_u64 v[226:227], s[44:45], 0, v[132:133]
	s_mov_b32 m0, s72
	ds_read_b128 v[192:195], v162 offset:16384
	ds_read_b128 v[198:201], v162 offset:17408
	ds_read_b128 v[202:205], v162 offset:18432
	ds_read_b128 v[206:209], v162 offset:19456
	ds_read_b128 v[210:213], v162 offset:20480
	ds_read_b128 v[214:217], v162 offset:21504
	ds_read_b128 v[218:221], v162 offset:22528
	ds_read_b128 v[222:225], v162 offset:23552
	global_load_lds_dwordx4 v[226:227], off
	s_add_i32 m0, s72, 0x2000
	s_add_u32 s72, s44, 0x2b0000
	v_lshl_add_u64 v[228:229], s[44:45], 0, v[136:137]
	s_addc_u32 s73, s45, 0
	s_add_i32 s74, s63, s51
	global_load_lds_dwordx4 v[228:229], off
	v_lshl_add_u64 v[230:231], s[72:73], 0, v[132:133]
	s_mov_b32 m0, s74
	v_lshl_add_u64 v[232:233], s[46:47], 0, v[134:135]
	global_load_lds_dwordx4 v[230:231], off
	v_lshl_add_u64 v[230:231], s[72:73], 0, v[136:137]
	s_add_i32 m0, s74, 0x2000
	s_nop 0
	global_load_lds_dwordx4 v[230:231], off
	v_lshl_add_u64 v[230:231], s[46:47], 0, v[130:131]
	s_mov_b32 m0, s52
	s_nop 0
	global_load_lds_dwordx4 v[230:231], off
	s_mov_b32 m0, s53
	s_nop 0
	global_load_lds_dwordx4 v[232:233], off
	s_waitcnt vmcnt(8)
	s_waitcnt lgkmcnt(0)
	s_nop 0
	s_setprio 1
	s_barrier
; #define PG8_STAGE(bufoff, gbase, voff) do { _Pragma("unroll") for (int _i = 0; _i < 2; ++_i) \
;         __builtin_amdgcn_global_load_lds((const unsigned*)((const char*)(gbase) + (voff)[_i]), (PG8_LAS unsigned*)(lds + (bufoff) + ldsw + _i * 8192), 16, 0, 0); } while (0)
; #define PG8_LDA(dst, b, h) do { _Pragma("unroll") for (int m = 0; m < 4; ++m) _Pragma("unroll") for (int k = 0; k < 2; ++k) dst[m][k] = *(const PG8_LAS bf16x8*)(lds + PG8_SA(b, h) + aoff + m * 2048 + k * 1024); } while (0)
; #define PG8_LDB(dst, b, h) do { _Pragma("unroll") for (int n = 0; n < 2; ++n) _Pragma("unroll") for (int k = 0; k < 2; ++k) dst[n][k] = *(const PG8_LAS bf16x8*)(lds + PG8_SB(b, h) + boff + n * 2048 + k * 1024); } while (0)
; #define PG8_MMA(ai, bj, At, Bt) do { __builtin_amdgcn_s_setprio(1); _Pragma("unroll") for (int m = 0; m < 4; ++m) _Pragma("unroll") for (int n = 0; n < 2; ++n) _Pragma("unroll") for (int k = 0; k < 2; ++k) \
;         acc[ai][bj][m][n] = __builtin_amdgcn_mfma_f32_16x16x32_bf16(Bt[n][k], At[m][k], acc[ai][bj][m][n], 0, 0, 0); __builtin_amdgcn_s_setprio(0); } while (0)
; #define PG8_WAIT_V(n) asm volatile("s_waitcnt vmcnt(" #n ")" ::: "memory")
; #define PG8_WAIT_L(n) asm volatile("s_waitcnt lgkmcnt(" #n ")" ::: "memory")
; #define PG8_BAR __builtin_amdgcn_s_barrier()
; #define PG8_SCHED __builtin_amdgcn_sched_barrier(0)
; template <class Epi, class Sched, bool ALIGN_EPI = false, bool SP2 = false>
; __device__ __forceinline__ void gemm_phase(PG8_LAS unsigned char* lds, const Gemm g, const Sched& S, const Epi& E) {
;     ...
;             PG8_WAIT_V(8); PG8_WAIT_L(0); PG8_BAR; PG8_MMA(1, 0, At, B0); PG8_MMA(1, 1, At, B1); PG8_BAR; PG8_SCHED;
;             PG8_LDB(B0, 1, 0); PG8_LDB(B1, 1, 1); PG8_SCHED; PG8_LDA(At, 1, 0); PG8_STAGE(PG8_SA(0, 1), a2 + hstep, voffA);
;             PG8_WAIT_V(8); PG8_WAIT_L(0); PG8_BAR; PG8_MMA(0, 0, At, B0); PG8_MMA(0, 1, At, B1); PG8_BAR; PG8_SCHED;
	v_mfma_f32_16x16x32_bf16 v[62:65], v[146:149], v[192:195], 0
	v_mfma_f32_16x16x32_bf16 v[58:61], v[168:171], v[192:195], 0
	v_mfma_f32_16x16x32_bf16 v[46:49], v[146:149], v[202:205], 0
	v_mfma_f32_16x16x32_bf16 v[42:45], v[168:171], v[202:205], 0
	v_mfma_f32_16x16x32_bf16 v[30:33], v[146:149], v[210:213], 0
	v_mfma_f32_16x16x32_bf16 v[26:29], v[168:171], v[210:213], 0
	v_mfma_f32_16x16x32_bf16 v[14:17], v[146:149], v[218:221], 0
	v_mfma_f32_16x16x32_bf16 v[10:13], v[168:171], v[218:221], 0
	v_mfma_f32_16x16x32_bf16 v[62:65], v[164:167], v[198:201], v[62:65]
	v_mfma_f32_16x16x32_bf16 v[58:61], v[172:175], v[198:201], v[58:61]
	v_mfma_f32_16x16x32_bf16 v[46:49], v[164:167], v[206:209], v[46:49]
	v_mfma_f32_16x16x32_bf16 v[42:45], v[172:175], v[206:209], v[42:45]
	v_mfma_f32_16x16x32_bf16 v[30:33], v[164:167], v[214:217], v[30:33]
	v_mfma_f32_16x16x32_bf16 v[26:29], v[172:175], v[214:217], v[26:29]
	v_mfma_f32_16x16x32_bf16 v[14:17], v[164:167], v[222:225], v[14:17]
	v_mfma_f32_16x16x32_bf16 v[10:13], v[172:175], v[222:225], v[10:13]
	s_setprio 0
	s_setprio 1
	v_mfma_f32_16x16x32_bf16 v[54:57], v[176:179], v[192:195], 0
	v_mfma_f32_16x16x32_bf16 v[50:53], v[184:187], v[192:195], 0
	v_mfma_f32_16x16x32_bf16 v[38:41], v[176:179], v[202:205], 0
	v_mfma_f32_16x16x32_bf16 v[34:37], v[184:187], v[202:205], 0
	v_mfma_f32_16x16x32_bf16 v[22:25], v[176:179], v[210:213], 0
	v_mfma_f32_16x16x32_bf16 v[18:21], v[184:187], v[210:213], 0
	v_mfma_f32_16x16x32_bf16 v[6:9], v[176:179], v[218:221], 0
	v_mfma_f32_16x16x32_bf16 v[2:5], v[184:187], v[218:221], 0
	v_mfma_f32_16x16x32_bf16 v[54:57], v[180:183], v[198:201], v[54:57]
	v_mfma_f32_16x16x32_bf16 v[50:53], v[188:191], v[198:201], v[50:53]
	v_mfma_f32_16x16x32_bf16 v[38:41], v[180:183], v[206:209], v[38:41]
	v_mfma_f32_16x16x32_bf16 v[34:37], v[188:191], v[206:209], v[34:37]
	v_mfma_f32_16x16x32_bf16 v[22:25], v[180:183], v[214:217], v[22:25]
	v_mfma_f32_16x16x32_bf16 v[18:21], v[188:191], v[214:217], v[18:21]
	v_mfma_f32_16x16x32_bf16 v[6:9], v[180:183], v[222:225], v[6:9]
	v_mfma_f32_16x16x32_bf16 v[2:5], v[188:191], v[222:225], v[2:5]
	s_setprio 0
	s_barrier
	s_add_i32 s72, 0, 0x18000
	s_add_i32 s73, 0, 0x1c000
	v_add_u32_e32 v172, s72, v151
	v_add_u32_e32 v188, s73, v151
	ds_read_b128 v[146:149], v172
	ds_read_b128 v[164:167], v172 offset:1024
	ds_read_b128 v[168:171], v172 offset:2048
	ds_read_b128 v[172:175], v172 offset:3072
	ds_read_b128 v[176:179], v188
	ds_read_b128 v[180:183], v188 offset:1024
	ds_read_b128 v[184:187], v188 offset:2048
	ds_read_b128 v[188:191], v188 offset:3072
	s_add_u32 s46, s46, 0x2b0000
	s_addc_u32 s47, s47, 0
	s_mov_b32 m0, s54
	v_lshl_add_u64 v[234:235], s[46:47], 0, v[130:131]
	ds_read_b128 v[192:195], v162 offset:32768
	ds_read_b128 v[198:201], v162 offset:33792
	ds_read_b128 v[202:205], v162 offset:34816
	ds_read_b128 v[206:209], v162 offset:35840
	ds_read_b128 v[210:213], v162 offset:36864
	ds_read_b128 v[214:217], v162 offset:37888
	ds_read_b128 v[218:221], v162 offset:38912
	ds_read_b128 v[222:225], v162 offset:39936
	global_load_lds_dwordx4 v[234:235], off
	v_lshl_add_u64 v[234:235], s[46:47], 0, v[134:135]
	s_mov_b32 m0, s55
	s_nop 0
	global_load_lds_dwordx4 v[234:235], off
	s_waitcnt vmcnt(8)
	s_waitcnt lgkmcnt(0)
	s_nop 0
	s_setprio 1
	s_barrier
	v_mfma_f32_16x16x32_bf16 v[126:129], v[146:149], v[192:195], v[126:129]
	v_mfma_f32_16x16x32_bf16 v[122:125], v[168:171], v[192:195], v[122:125]
	v_mfma_f32_16x16x32_bf16 v[110:113], v[146:149], v[202:205], v[110:113]
	v_mfma_f32_16x16x32_bf16 v[106:109], v[168:171], v[202:205], v[106:109]
	v_mfma_f32_16x16x32_bf16 v[94:97], v[146:149], v[210:213], v[94:97]
	v_mfma_f32_16x16x32_bf16 v[90:93], v[168:171], v[210:213], v[90:93]
	v_mfma_f32_16x16x32_bf16 v[78:81], v[146:149], v[218:221], v[78:81]
	v_mfma_f32_16x16x32_bf16 v[74:77], v[168:171], v[218:221], v[74:77]
	v_mfma_f32_16x16x32_bf16 v[126:129], v[164:167], v[198:201], v[126:129]
	v_mfma_f32_16x16x32_bf16 v[122:125], v[172:175], v[198:201], v[122:125]
	v_mfma_f32_16x16x32_bf16 v[110:113], v[164:167], v[206:209], v[110:113]
	v_mfma_f32_16x16x32_bf16 v[106:109], v[172:175], v[206:209], v[106:109]
	v_mfma_f32_16x16x32_bf16 v[94:97], v[164:167], v[214:217], v[94:97]
	v_mfma_f32_16x16x32_bf16 v[90:93], v[172:175], v[214:217], v[90:93]
	v_mfma_f32_16x16x32_bf16 v[78:81], v[164:167], v[222:225], v[78:81]
	v_mfma_f32_16x16x32_bf16 v[74:77], v[172:175], v[222:225], v[74:77]
	s_setprio 0
	s_setprio 1
	v_mfma_f32_16x16x32_bf16 v[118:121], v[176:179], v[192:195], v[118:121]
	v_mfma_f32_16x16x32_bf16 v[114:117], v[184:187], v[192:195], v[114:117]
	v_mfma_f32_16x16x32_bf16 v[102:105], v[176:179], v[202:205], v[102:105]
	v_mfma_f32_16x16x32_bf16 v[98:101], v[184:187], v[202:205], v[98:101]
	v_mfma_f32_16x16x32_bf16 v[86:89], v[176:179], v[210:213], v[86:89]
	v_mfma_f32_16x16x32_bf16 v[82:85], v[184:187], v[210:213], v[82:85]
	v_mfma_f32_16x16x32_bf16 v[70:73], v[176:179], v[218:221], v[70:73]
	v_mfma_f32_16x16x32_bf16 v[66:69], v[184:187], v[218:221], v[66:69]
	v_mfma_f32_16x16x32_bf16 v[118:121], v[180:183], v[198:201], v[118:121]
	v_mfma_f32_16x16x32_bf16 v[114:117], v[188:191], v[198:201], v[114:117]
	v_mfma_f32_16x16x32_bf16 v[102:105], v[180:183], v[206:209], v[102:105]
	v_mfma_f32_16x16x32_bf16 v[98:101], v[188:191], v[206:209], v[98:101]
	v_mfma_f32_16x16x32_bf16 v[86:89], v[180:183], v[214:217], v[86:89]
	v_mfma_f32_16x16x32_bf16 v[82:85], v[188:191], v[214:217], v[82:85]
	v_mfma_f32_16x16x32_bf16 v[70:73], v[180:183], v[222:225], v[70:73]
	v_mfma_f32_16x16x32_bf16 v[66:69], v[188:191], v[222:225], v[66:69]
	s_setprio 0
	s_barrier
; #define PG8_STAGE(bufoff, gbase, voff) do { _Pragma("unroll") for (int _i = 0; _i < 2; ++_i) \
;         __builtin_amdgcn_global_load_lds((const unsigned*)((const char*)(gbase) + (voff)[_i]), (PG8_LAS unsigned*)(lds + (bufoff) + ldsw + _i * 8192), 16, 0, 0); } while (0)
; #define PG8_LDA(dst, b, h) do { _Pragma("unroll") for (int m = 0; m < 4; ++m) _Pragma("unroll") for (int k = 0; k < 2; ++k) dst[m][k] = *(const PG8_LAS bf16x8*)(lds + PG8_SA(b, h) + aoff + m * 2048 + k * 1024); } while (0)
; #define PG8_LDB(dst, b, h) do { _Pragma("unroll") for (int n = 0; n < 2; ++n) _Pragma("unroll") for (int k = 0; k < 2; ++k) dst[n][k] = *(const PG8_LAS bf16x8*)(lds + PG8_SB(b, h) + boff + n * 2048 + k * 1024); } while (0)
; #define PG8_MMA(ai, bj, At, Bt) do { __builtin_amdgcn_s_setprio(1); _Pragma("unroll") for (int m = 0; m < 4; ++m) _Pragma("unroll") for (int n = 0; n < 2; ++n) _Pragma("unroll") for (int k = 0; k < 2; ++k) \
;         acc[ai][bj][m][n] = __builtin_amdgcn_mfma_f32_16x16x32_bf16(Bt[n][k], At[m][k], acc[ai][bj][m][n], 0, 0, 0); __builtin_amdgcn_s_setprio(0); } while (0)
; #define PG8_WAIT_V(n) asm volatile("s_waitcnt vmcnt(" #n ")" ::: "memory")
; template <class Epi, class Sched, bool ALIGN_EPI = false, bool SP2 = false>
; __device__ __forceinline__ void gemm_phase(PG8_LAS unsigned char* lds, const Gemm g, const Sched& S, const Epi& E) {
;     ...
;             PG8_LDB(B0, 0, 0); PG8_LDB(B1, 0, 1); PG8_SCHED; PG8_LDA(At, 0, 0); PG8_STAGE(PG8_SA(1, 1), a1 + hstep, voffA);
;             PG8_WAIT_V(8); PG8_WAIT_L(0); PG8_BAR; PG8_MMA(0, 0, At, B0); PG8_MMA(0, 1, At, B1); PG8_BAR; PG8_SCHED;
;             PG8_LDA(At, 0, 1); PG8_STAGE(PG8_SB(0, 0), b2, voffB); PG8_STAGE(PG8_SB(0, 1), b2 + hstep, voffB); PG8_STAGE(PG8_SA(0, 0), a2, voffA);
;             PG8_WAIT_V(8); PG8_WAIT_L(0); PG8_BAR; PG8_MMA(1, 0, At, B0); PG8_MMA(1, 1, At, B1); PG8_BAR; PG8_SCHED;
;             PG8_LDB(B0, 1, 0); PG8_LDB(B1, 1, 1); PG8_SCHED; PG8_LDA(At, 1, 0); PG8_STAGE(PG8_SA(0, 1), a2 + hstep, voffA);
;             PG8_WAIT_V(8); PG8_WAIT_L(0); PG8_BAR; PG8_MMA(0, 0, At, B0); PG8_MMA(0, 1, At, B1); PG8_BAR; PG8_SCHED;
;             PG8_LDA(At, 1, 1); PG8_STAGE(PG8_SB(1, 0), b3, voffB); PG8_STAGE(PG8_SB(1, 1), b3 + hstep, voffB); PG8_STAGE(PG8_SA(1, 0), a3, voffA);
;             PG8_WAIT_V(8); PG8_WAIT_L(0); PG8_BAR; PG8_MMA(1, 0, At, B0); PG8_MMA(1, 1, At, B1); PG8_BAR; PG8_SCHED;
	s_add_i32 s46, s72, s51
	v_lshl_add_u64 v[226:227], v[226:227], 0, s[36:37]
	s_mov_b32 m0, s46
	ds_read_b128 v[192:195], v162 offset:49152
	ds_read_b128 v[198:201], v162 offset:50176
	ds_read_b128 v[202:205], v162 offset:51200
	ds_read_b128 v[206:209], v162 offset:52224
	ds_read_b128 v[210:213], v162 offset:53248
	ds_read_b128 v[214:217], v162 offset:54272
	ds_read_b128 v[218:221], v162 offset:55296
	ds_read_b128 v[222:225], v162 offset:56320
	global_load_lds_dwordx4 v[226:227], off
	s_add_i32 m0, s46, 0x2000
	s_add_u32 s44, s44, 0x2b0080
	v_lshl_add_u64 v[226:227], v[228:229], 0, s[36:37]
	s_addc_u32 s45, s45, 0
	s_add_i32 s46, s73, s51
	global_load_lds_dwordx4 v[226:227], off
	v_lshl_add_u64 v[226:227], s[44:45], 0, v[132:133]
	s_mov_b32 m0, s46
	s_nop 0
	global_load_lds_dwordx4 v[226:227], off
	v_lshl_add_u64 v[226:227], s[44:45], 0, v[136:137]
	s_add_i32 m0, s46, 0x2000
	s_nop 0
	global_load_lds_dwordx4 v[226:227], off
	v_lshl_add_u64 v[226:227], v[230:231], 0, s[36:37]
	s_mov_b32 m0, s57
	s_nop 0
	global_load_lds_dwordx4 v[226:227], off
	v_lshl_add_u64 v[226:227], v[232:233], 0, s[36:37]
	s_mov_b32 m0, s58
	s_nop 0
	global_load_lds_dwordx4 v[226:227], off
	s_waitcnt vmcnt(8)
	s_waitcnt lgkmcnt(0)
	s_nop 0
	s_setprio 1
	s_barrier
	v_mfma_f32_16x16x32_bf16 v[62:65], v[146:149], v[192:195], v[62:65]
	v_mfma_f32_16x16x32_bf16 v[58:61], v[168:171], v[192:195], v[58:61]
	v_mfma_f32_16x16x32_bf16 v[46:49], v[146:149], v[202:205], v[46:49]
	v_mfma_f32_16x16x32_bf16 v[42:45], v[168:171], v[202:205], v[42:45]
	v_mfma_f32_16x16x32_bf16 v[30:33], v[146:149], v[210:213], v[30:33]
	v_mfma_f32_16x16x32_bf16 v[26:29], v[168:171], v[210:213], v[26:29]
	v_mfma_f32_16x16x32_bf16 v[14:17], v[146:149], v[218:221], v[14:17]
	v_mfma_f32_16x16x32_bf16 v[10:13], v[168:171], v[218:221], v[10:13]
	v_mfma_f32_16x16x32_bf16 v[62:65], v[164:167], v[198:201], v[62:65]
	v_mfma_f32_16x16x32_bf16 v[58:61], v[172:175], v[198:201], v[58:61]
	v_mfma_f32_16x16x32_bf16 v[46:49], v[164:167], v[206:209], v[46:49]
	v_mfma_f32_16x16x32_bf16 v[42:45], v[172:175], v[206:209], v[42:45]
	v_mfma_f32_16x16x32_bf16 v[30:33], v[164:167], v[214:217], v[30:33]
	v_mfma_f32_16x16x32_bf16 v[26:29], v[172:175], v[214:217], v[26:29]
	v_mfma_f32_16x16x32_bf16 v[14:17], v[164:167], v[222:225], v[14:17]
	v_mfma_f32_16x16x32_bf16 v[10:13], v[172:175], v[222:225], v[10:13]
	s_setprio 0
	s_setprio 1
	v_mfma_f32_16x16x32_bf16 v[54:57], v[176:179], v[192:195], v[54:57]
	v_mfma_f32_16x16x32_bf16 v[50:53], v[184:187], v[192:195], v[50:53]
	v_mfma_f32_16x16x32_bf16 v[38:41], v[176:179], v[202:205], v[38:41]
	v_mfma_f32_16x16x32_bf16 v[34:37], v[184:187], v[202:205], v[34:37]
	v_mfma_f32_16x16x32_bf16 v[22:25], v[176:179], v[210:213], v[22:25]
	v_mfma_f32_16x16x32_bf16 v[18:21], v[184:187], v[210:213], v[18:21]
	v_mfma_f32_16x16x32_bf16 v[6:9], v[176:179], v[218:221], v[6:9]
	v_mfma_f32_16x16x32_bf16 v[2:5], v[184:187], v[218:221], v[2:5]
	v_mfma_f32_16x16x32_bf16 v[54:57], v[180:183], v[198:201], v[54:57]
	v_mfma_f32_16x16x32_bf16 v[50:53], v[188:191], v[198:201], v[50:53]
	v_mfma_f32_16x16x32_bf16 v[38:41], v[180:183], v[206:209], v[38:41]
	v_mfma_f32_16x16x32_bf16 v[34:37], v[188:191], v[206:209], v[34:37]
	v_mfma_f32_16x16x32_bf16 v[22:25], v[180:183], v[214:217], v[22:25]
	v_mfma_f32_16x16x32_bf16 v[18:21], v[188:191], v[214:217], v[18:21]
	v_mfma_f32_16x16x32_bf16 v[6:9], v[180:183], v[222:225], v[6:9]
	v_mfma_f32_16x16x32_bf16 v[2:5], v[188:191], v[222:225], v[2:5]
	s_setprio 0
	s_barrier
	s_add_i32 s71, s71, 2
	s_add_u32 s42, s42, 0x100
	s_addc_u32 s43, s43, 0
	s_add_u32 s69, s69, 0x100
	s_addc_u32 s70, s70, 0
	s_cmpk_gt_u32 s71, 0xa9
	.p2align	3
.LBB0_984:
	ds_read_b128 v[146:149], v160
	ds_read_b128 v[164:167], v160 offset:1024
	ds_read_b128 v[168:171], v160 offset:2048
	ds_read_b128 v[172:175], v160 offset:3072
	ds_read_b128 v[176:179], v161
	ds_read_b128 v[180:183], v161 offset:1024
	ds_read_b128 v[184:187], v161 offset:2048
	ds_read_b128 v[188:191], v161 offset:3072
	s_add_u32 s44, s42, 0xffd50080
	s_addc_u32 s45, s43, -1
	s_cmpk_eq_i32 s71, 0xa8
	s_cselect_b32 s47, s7, s45
	s_cselect_b32 s46, s6, s44
	s_cselect_b32 s45, s41, s70
	s_cselect_b32 s44, s40, s69
	v_lshl_add_u64 v[226:227], s[42:43], 0, v[138:139]
	s_add_i32 m0, s52, 0xc000
	ds_read_b128 v[192:195], v162
	ds_read_b128 v[198:201], v162 offset:1024
	ds_read_b128 v[202:205], v162 offset:2048
	ds_read_b128 v[206:209], v162 offset:3072
	ds_read_b128 v[210:213], v162 offset:4096
	ds_read_b128 v[214:217], v162 offset:5120
	ds_read_b128 v[218:221], v162 offset:6144
	ds_read_b128 v[222:225], v162 offset:7168
	global_load_lds_dwordx4 v[226:227], off
	v_lshl_add_u64 v[226:227], s[42:43], 0, v[140:141]
	s_add_i32 m0, s52, 0xe000
	s_nop 0
	global_load_lds_dwordx4 v[226:227], off
	s_waitcnt vmcnt(8)
	s_waitcnt lgkmcnt(0)
	s_nop 0
	s_setprio 1
	s_barrier
; #define PG8_STAGE(bufoff, gbase, voff) do { _Pragma("unroll") for (int _i = 0; _i < 2; ++_i) \
;         __builtin_amdgcn_global_load_lds((const unsigned*)((const char*)(gbase) + (voff)[_i]), (PG8_LAS unsigned*)(lds + (bufoff) + ldsw + _i * 8192), 16, 0, 0); } while (0)
; #define PG8_LDA(dst, b, h) do { _Pragma("unroll") for (int m = 0; m < 4; ++m) _Pragma("unroll") for (int k = 0; k < 2; ++k) dst[m][k] = *(const PG8_LAS bf16x8*)(lds + PG8_SA(b, h) + aoff + m * 2048 + k * 1024); } while (0)
; #define PG8_LDB(dst, b, h) do { _Pragma("unroll") for (int n = 0; n < 2; ++n) _Pragma("unroll") for (int k = 0; k < 2; ++k) dst[n][k] = *(const PG8_LAS bf16x8*)(lds + PG8_SB(b, h) + boff + n * 2048 + k * 1024); } while (0)
; #define PG8_MMA(ai, bj, At, Bt) do { __builtin_amdgcn_s_setprio(1); _Pragma("unroll") for (int m = 0; m < 4; ++m) _Pragma("unroll") for (int n = 0; n < 2; ++n) _Pragma("unroll") for (int k = 0; k < 2; ++k) \
;         acc[ai][bj][m][n] = __builtin_amdgcn_mfma_f32_16x16x32_bf16(Bt[n][k], At[m][k], acc[ai][bj][m][n], 0, 0, 0); __builtin_amdgcn_s_setprio(0); } while (0)
; #define PG8_WAIT_V(n) asm volatile("s_waitcnt vmcnt(" #n ")" ::: "memory")
; template <class Epi, class Sched, bool ALIGN_EPI = false, bool SP2 = false>
; __device__ __forceinline__ void gemm_phase(PG8_LAS unsigned char* lds, const Gemm g, const Sched& S, const Epi& E) {
;     ...
;             PG8_LDB(B0, 0, 0); PG8_LDB(B1, 0, 1); PG8_SCHED; PG8_LDA(At, 0, 0); PG8_STAGE(PG8_SA(1, 1), a1 + hstep, voffA);
;             PG8_WAIT_V(8); PG8_WAIT_L(0); PG8_BAR; PG8_MMA(0, 0, At, B0); PG8_MMA(0, 1, At, B1); PG8_BAR; PG8_SCHED;
;             PG8_LDA(At, 0, 1); PG8_STAGE(PG8_SB(0, 0), b2, voffB); PG8_STAGE(PG8_SB(0, 1), b2 + hstep, voffB); PG8_STAGE(PG8_SA(0, 0), a2, voffA);
;             PG8_WAIT_V(8); PG8_WAIT_L(0); PG8_BAR; PG8_MMA(1, 0, At, B0); PG8_MMA(1, 1, At, B1); PG8_BAR; PG8_SCHED;
;             PG8_LDB(B0, 1, 0); PG8_LDB(B1, 1, 1); PG8_SCHED; PG8_LDA(At, 1, 0); PG8_STAGE(PG8_SA(0, 1), a2 + hstep, voffA);
;             PG8_WAIT_V(8); PG8_WAIT_L(0); PG8_BAR; PG8_MMA(0, 0, At, B0); PG8_MMA(0, 1, At, B1); PG8_BAR; PG8_SCHED;
;             PG8_LDA(At, 1, 1); PG8_STAGE(PG8_SB(1, 0), b3, voffB); PG8_STAGE(PG8_SB(1, 1), b3 + hstep, voffB); PG8_STAGE(PG8_SA(1, 0), a3, voffA);
;             PG8_WAIT_V(8); PG8_WAIT_L(0); PG8_BAR; PG8_MMA(1, 0, At, B0); PG8_MMA(1, 1, At, B1); PG8_BAR; PG8_SCHED;
	v_mfma_f32_16x16x32_bf16 v[126:129], v[146:149], v[192:195], v[126:129]
	v_mfma_f32_16x16x32_bf16 v[122:125], v[168:171], v[192:195], v[122:125]
	v_mfma_f32_16x16x32_bf16 v[110:113], v[146:149], v[202:205], v[110:113]
	v_mfma_f32_16x16x32_bf16 v[106:109], v[168:171], v[202:205], v[106:109]
	v_mfma_f32_16x16x32_bf16 v[94:97], v[146:149], v[210:213], v[94:97]
	v_mfma_f32_16x16x32_bf16 v[90:93], v[168:171], v[210:213], v[90:93]
	v_mfma_f32_16x16x32_bf16 v[78:81], v[146:149], v[218:221], v[78:81]
	v_mfma_f32_16x16x32_bf16 v[74:77], v[168:171], v[218:221], v[74:77]
	v_mfma_f32_16x16x32_bf16 v[126:129], v[164:167], v[198:201], v[126:129]
	v_mfma_f32_16x16x32_bf16 v[122:125], v[172:175], v[198:201], v[122:125]
	v_mfma_f32_16x16x32_bf16 v[110:113], v[164:167], v[206:209], v[110:113]
	v_mfma_f32_16x16x32_bf16 v[106:109], v[172:175], v[206:209], v[106:109]
	v_mfma_f32_16x16x32_bf16 v[94:97], v[164:167], v[214:217], v[94:97]
	v_mfma_f32_16x16x32_bf16 v[90:93], v[172:175], v[214:217], v[90:93]
	v_mfma_f32_16x16x32_bf16 v[78:81], v[164:167], v[222:225], v[78:81]
	v_mfma_f32_16x16x32_bf16 v[74:77], v[172:175], v[222:225], v[74:77]
	s_setprio 0
	s_setprio 1
	v_mfma_f32_16x16x32_bf16 v[118:121], v[176:179], v[192:195], v[118:121]
	v_mfma_f32_16x16x32_bf16 v[114:117], v[184:187], v[192:195], v[114:117]
	v_mfma_f32_16x16x32_bf16 v[102:105], v[176:179], v[202:205], v[102:105]
	v_mfma_f32_16x16x32_bf16 v[98:101], v[184:187], v[202:205], v[98:101]
	v_mfma_f32_16x16x32_bf16 v[86:89], v[176:179], v[210:213], v[86:89]
	v_mfma_f32_16x16x32_bf16 v[82:85], v[184:187], v[210:213], v[82:85]
	v_mfma_f32_16x16x32_bf16 v[70:73], v[176:179], v[218:221], v[70:73]
	v_mfma_f32_16x16x32_bf16 v[66:69], v[184:187], v[218:221], v[66:69]
	v_mfma_f32_16x16x32_bf16 v[118:121], v[180:183], v[198:201], v[118:121]
	v_mfma_f32_16x16x32_bf16 v[114:117], v[188:191], v[198:201], v[114:117]
	v_mfma_f32_16x16x32_bf16 v[102:105], v[180:183], v[206:209], v[102:105]
	v_mfma_f32_16x16x32_bf16 v[98:101], v[188:191], v[206:209], v[98:101]
	v_mfma_f32_16x16x32_bf16 v[86:89], v[180:183], v[214:217], v[86:89]
	v_mfma_f32_16x16x32_bf16 v[82:85], v[188:191], v[214:217], v[82:85]
	v_mfma_f32_16x16x32_bf16 v[70:73], v[180:183], v[222:225], v[70:73]
	v_mfma_f32_16x16x32_bf16 v[66:69], v[188:191], v[222:225], v[66:69]
	s_setprio 0
	s_barrier
	s_add_i32 s72, s62, s51
	v_lshl_add_u64 v[226:227], s[44:45], 0, v[132:133]
	s_mov_b32 m0, s72
	ds_read_b128 v[192:195], v162 offset:16384
	ds_read_b128 v[198:201], v162 offset:17408
	ds_read_b128 v[202:205], v162 offset:18432
	ds_read_b128 v[206:209], v162 offset:19456
	ds_read_b128 v[210:213], v162 offset:20480
	ds_read_b128 v[214:217], v162 offset:21504
	ds_read_b128 v[218:221], v162 offset:22528
	ds_read_b128 v[222:225], v162 offset:23552
	global_load_lds_dwordx4 v[226:227], off
	s_add_i32 m0, s72, 0x2000
	s_add_u32 s72, s44, 0x2b0000
	v_lshl_add_u64 v[228:229], s[44:45], 0, v[136:137]
	s_addc_u32 s73, s45, 0
	s_add_i32 s74, s63, s51
	global_load_lds_dwordx4 v[228:229], off
	v_lshl_add_u64 v[230:231], s[72:73], 0, v[132:133]
	s_mov_b32 m0, s74
	v_lshl_add_u64 v[232:233], s[46:47], 0, v[134:135]
	global_load_lds_dwordx4 v[230:231], off
	v_lshl_add_u64 v[230:231], s[72:73], 0, v[136:137]
	s_add_i32 m0, s74, 0x2000
	s_nop 0
	global_load_lds_dwordx4 v[230:231], off
	v_lshl_add_u64 v[230:231], s[46:47], 0, v[130:131]
	s_mov_b32 m0, s52
	s_nop 0
	global_load_lds_dwordx4 v[230:231], off
	s_mov_b32 m0, s53
	s_nop 0
	global_load_lds_dwordx4 v[232:233], off
	s_waitcnt vmcnt(8)
	s_waitcnt lgkmcnt(0)
	s_nop 0
	s_setprio 1
	s_barrier
	v_mfma_f32_16x16x32_bf16 v[62:65], v[146:149], v[192:195], v[62:65]
	v_mfma_f32_16x16x32_bf16 v[58:61], v[168:171], v[192:195], v[58:61]
	v_mfma_f32_16x16x32_bf16 v[46:49], v[146:149], v[202:205], v[46:49]
	v_mfma_f32_16x16x32_bf16 v[42:45], v[168:171], v[202:205], v[42:45]
	v_mfma_f32_16x16x32_bf16 v[30:33], v[146:149], v[210:213], v[30:33]
	v_mfma_f32_16x16x32_bf16 v[26:29], v[168:171], v[210:213], v[26:29]
	v_mfma_f32_16x16x32_bf16 v[14:17], v[146:149], v[218:221], v[14:17]
	v_mfma_f32_16x16x32_bf16 v[10:13], v[168:171], v[218:221], v[10:13]
	v_mfma_f32_16x16x32_bf16 v[62:65], v[164:167], v[198:201], v[62:65]
	v_mfma_f32_16x16x32_bf16 v[58:61], v[172:175], v[198:201], v[58:61]
	v_mfma_f32_16x16x32_bf16 v[46:49], v[164:167], v[206:209], v[46:49]
	v_mfma_f32_16x16x32_bf16 v[42:45], v[172:175], v[206:209], v[42:45]
	v_mfma_f32_16x16x32_bf16 v[30:33], v[164:167], v[214:217], v[30:33]
	v_mfma_f32_16x16x32_bf16 v[26:29], v[172:175], v[214:217], v[26:29]
	v_mfma_f32_16x16x32_bf16 v[14:17], v[164:167], v[222:225], v[14:17]
	v_mfma_f32_16x16x32_bf16 v[10:13], v[172:175], v[222:225], v[10:13]
	s_setprio 0
	s_setprio 1
	v_mfma_f32_16x16x32_bf16 v[54:57], v[176:179], v[192:195], v[54:57]
	v_mfma_f32_16x16x32_bf16 v[50:53], v[184:187], v[192:195], v[50:53]
	v_mfma_f32_16x16x32_bf16 v[38:41], v[176:179], v[202:205], v[38:41]
	v_mfma_f32_16x16x32_bf16 v[34:37], v[184:187], v[202:205], v[34:37]
	v_mfma_f32_16x16x32_bf16 v[22:25], v[176:179], v[210:213], v[22:25]
	v_mfma_f32_16x16x32_bf16 v[18:21], v[184:187], v[210:213], v[18:21]
	v_mfma_f32_16x16x32_bf16 v[6:9], v[176:179], v[218:221], v[6:9]
	v_mfma_f32_16x16x32_bf16 v[2:5], v[184:187], v[218:221], v[2:5]
	v_mfma_f32_16x16x32_bf16 v[54:57], v[180:183], v[198:201], v[54:57]
	v_mfma_f32_16x16x32_bf16 v[50:53], v[188:191], v[198:201], v[50:53]
	v_mfma_f32_16x16x32_bf16 v[38:41], v[180:183], v[206:209], v[38:41]
	v_mfma_f32_16x16x32_bf16 v[34:37], v[188:191], v[206:209], v[34:37]
	v_mfma_f32_16x16x32_bf16 v[22:25], v[180:183], v[214:217], v[22:25]
	v_mfma_f32_16x16x32_bf16 v[18:21], v[188:191], v[214:217], v[18:21]
	v_mfma_f32_16x16x32_bf16 v[6:9], v[180:183], v[222:225], v[6:9]
	v_mfma_f32_16x16x32_bf16 v[2:5], v[188:191], v[222:225], v[2:5]
	s_setprio 0
	s_barrier
; #define PG8_STAGE(bufoff, gbase, voff) do { _Pragma("unroll") for (int _i = 0; _i < 2; ++_i) \
;         __builtin_amdgcn_global_load_lds((const unsigned*)((const char*)(gbase) + (voff)[_i]), (PG8_LAS unsigned*)(lds + (bufoff) + ldsw + _i * 8192), 16, 0, 0); } while (0)
; #define PG8_LDA(dst, b, h) do { _Pragma("unroll") for (int m = 0; m < 4; ++m) _Pragma("unroll") for (int k = 0; k < 2; ++k) dst[m][k] = *(const PG8_LAS bf16x8*)(lds + PG8_SA(b, h) + aoff + m * 2048 + k * 1024); } while (0)
; #define PG8_LDB(dst, b, h) do { _Pragma("unroll") for (int n = 0; n < 2; ++n) _Pragma("unroll") for (int k = 0; k < 2; ++k) dst[n][k] = *(const PG8_LAS bf16x8*)(lds + PG8_SB(b, h) + boff + n * 2048 + k * 1024); } while (0)
; #define PG8_MMA(ai, bj, At, Bt) do { __builtin_amdgcn_s_setprio(1); _Pragma("unroll") for (int m = 0; m < 4; ++m) _Pragma("unroll") for (int n = 0; n < 2; ++n) _Pragma("unroll") for (int k = 0; k < 2; ++k) \
;         acc[ai][bj][m][n] = __builtin_amdgcn_mfma_f32_16x16x32_bf16(Bt[n][k], At[m][k], acc[ai][bj][m][n], 0, 0, 0); __builtin_amdgcn_s_setprio(0); } while (0)
; #define PG8_WAIT_V(n) asm volatile("s_waitcnt vmcnt(" #n ")" ::: "memory")
; #define PG8_WAIT_L(n) asm volatile("s_waitcnt lgkmcnt(" #n ")" ::: "memory")
; #define PG8_BAR __builtin_amdgcn_s_barrier()
; #define PG8_SCHED __builtin_amdgcn_sched_barrier(0)
; template <class Epi, class Sched, bool ALIGN_EPI = false, bool SP2 = false>
; __device__ __forceinline__ void gemm_phase(PG8_LAS unsigned char* lds, const Gemm g, const Sched& S, const Epi& E) {
;     ...
;             PG8_LDB(B0, 1, 0); PG8_LDB(B1, 1, 1); PG8_SCHED; PG8_LDA(At, 1, 0); PG8_STAGE(PG8_SA(0, 1), a2 + hstep, voffA);
;             PG8_WAIT_V(8); PG8_WAIT_L(0); PG8_BAR; PG8_MMA(0, 0, At, B0); PG8_MMA(0, 1, At, B1); PG8_BAR; PG8_SCHED;
	s_add_i32 s72, 0, 0x18000
	s_add_i32 s73, 0, 0x1c000
	v_add_u32_e32 v172, s72, v151
	v_add_u32_e32 v188, s73, v151
	ds_read_b128 v[146:149], v172
	ds_read_b128 v[164:167], v172 offset:1024
	ds_read_b128 v[168:171], v172 offset:2048
	ds_read_b128 v[172:175], v172 offset:3072
	ds_read_b128 v[176:179], v188
	ds_read_b128 v[180:183], v188 offset:1024
	ds_read_b128 v[184:187], v188 offset:2048
	ds_read_b128 v[188:191], v188 offset:3072
	s_add_u32 s46, s46, 0x2b0000
	s_addc_u32 s47, s47, 0
	s_mov_b32 m0, s54
	v_lshl_add_u64 v[234:235], s[46:47], 0, v[130:131]
	ds_read_b128 v[192:195], v162 offset:32768
	ds_read_b128 v[198:201], v162 offset:33792
	ds_read_b128 v[202:205], v162 offset:34816
	ds_read_b128 v[206:209], v162 offset:35840
	ds_read_b128 v[210:213], v162 offset:36864
	ds_read_b128 v[214:217], v162 offset:37888
	ds_read_b128 v[218:221], v162 offset:38912
	ds_read_b128 v[222:225], v162 offset:39936
	global_load_lds_dwordx4 v[234:235], off
	v_lshl_add_u64 v[234:235], s[46:47], 0, v[134:135]
	s_mov_b32 m0, s55
	s_nop 0
	global_load_lds_dwordx4 v[234:235], off
	s_waitcnt vmcnt(8)
	s_waitcnt lgkmcnt(0)
	s_nop 0
	s_setprio 1
	s_barrier
	v_mfma_f32_16x16x32_bf16 v[126:129], v[146:149], v[192:195], v[126:129]
	v_mfma_f32_16x16x32_bf16 v[122:125], v[168:171], v[192:195], v[122:125]
	v_mfma_f32_16x16x32_bf16 v[110:113], v[146:149], v[202:205], v[110:113]
	v_mfma_f32_16x16x32_bf16 v[106:109], v[168:171], v[202:205], v[106:109]
	v_mfma_f32_16x16x32_bf16 v[94:97], v[146:149], v[210:213], v[94:97]
	v_mfma_f32_16x16x32_bf16 v[90:93], v[168:171], v[210:213], v[90:93]
	v_mfma_f32_16x16x32_bf16 v[78:81], v[146:149], v[218:221], v[78:81]
	v_mfma_f32_16x16x32_bf16 v[74:77], v[168:171], v[218:221], v[74:77]
	v_mfma_f32_16x16x32_bf16 v[126:129], v[164:167], v[198:201], v[126:129]
	v_mfma_f32_16x16x32_bf16 v[122:125], v[172:175], v[198:201], v[122:125]
	v_mfma_f32_16x16x32_bf16 v[110:113], v[164:167], v[206:209], v[110:113]
	v_mfma_f32_16x16x32_bf16 v[106:109], v[172:175], v[206:209], v[106:109]
	v_mfma_f32_16x16x32_bf16 v[94:97], v[164:167], v[214:217], v[94:97]
	v_mfma_f32_16x16x32_bf16 v[90:93], v[172:175], v[214:217], v[90:93]
	v_mfma_f32_16x16x32_bf16 v[78:81], v[164:167], v[222:225], v[78:81]
	v_mfma_f32_16x16x32_bf16 v[74:77], v[172:175], v[222:225], v[74:77]
	s_setprio 0
	s_setprio 1
	v_mfma_f32_16x16x32_bf16 v[118:121], v[176:179], v[192:195], v[118:121]
	v_mfma_f32_16x16x32_bf16 v[114:117], v[184:187], v[192:195], v[114:117]
	v_mfma_f32_16x16x32_bf16 v[102:105], v[176:179], v[202:205], v[102:105]
	v_mfma_f32_16x16x32_bf16 v[98:101], v[184:187], v[202:205], v[98:101]
	v_mfma_f32_16x16x32_bf16 v[86:89], v[176:179], v[210:213], v[86:89]
	v_mfma_f32_16x16x32_bf16 v[82:85], v[184:187], v[210:213], v[82:85]
	v_mfma_f32_16x16x32_bf16 v[70:73], v[176:179], v[218:221], v[70:73]
	v_mfma_f32_16x16x32_bf16 v[66:69], v[184:187], v[218:221], v[66:69]
	v_mfma_f32_16x16x32_bf16 v[118:121], v[180:183], v[198:201], v[118:121]
	v_mfma_f32_16x16x32_bf16 v[114:117], v[188:191], v[198:201], v[114:117]
	v_mfma_f32_16x16x32_bf16 v[102:105], v[180:183], v[206:209], v[102:105]
	v_mfma_f32_16x16x32_bf16 v[98:101], v[188:191], v[206:209], v[98:101]
	v_mfma_f32_16x16x32_bf16 v[86:89], v[180:183], v[214:217], v[86:89]
	v_mfma_f32_16x16x32_bf16 v[82:85], v[188:191], v[214:217], v[82:85]
	v_mfma_f32_16x16x32_bf16 v[70:73], v[180:183], v[222:225], v[70:73]
	v_mfma_f32_16x16x32_bf16 v[66:69], v[188:191], v[222:225], v[66:69]
	s_setprio 0
	s_barrier
; #define PG8_STAGE(bufoff, gbase, voff) do { _Pragma("unroll") for (int _i = 0; _i < 2; ++_i) \
;         __builtin_amdgcn_global_load_lds((const unsigned*)((const char*)(gbase) + (voff)[_i]), (PG8_LAS unsigned*)(lds + (bufoff) + ldsw + _i * 8192), 16, 0, 0); } while (0)
; #define PG8_LDA(dst, b, h) do { _Pragma("unroll") for (int m = 0; m < 4; ++m) _Pragma("unroll") for (int k = 0; k < 2; ++k) dst[m][k] = *(const PG8_LAS bf16x8*)(lds + PG8_SA(b, h) + aoff + m * 2048 + k * 1024); } while (0)
; #define PG8_MMA(ai, bj, At, Bt) do { __builtin_amdgcn_s_setprio(1); _Pragma("unroll") for (int m = 0; m < 4; ++m) _Pragma("unroll") for (int n = 0; n < 2; ++n) _Pragma("unroll") for (int k = 0; k < 2; ++k) \
;         acc[ai][bj][m][n] = __builtin_amdgcn_mfma_f32_16x16x32_bf16(Bt[n][k], At[m][k], acc[ai][bj][m][n], 0, 0, 0); __builtin_amdgcn_s_setprio(0); } while (0)
; #define PG8_WAIT_V(n) asm volatile("s_waitcnt vmcnt(" #n ")" ::: "memory")
; #define PG8_WAIT_L(n) asm volatile("s_waitcnt lgkmcnt(" #n ")" ::: "memory")
; #define PG8_BAR __builtin_amdgcn_s_barrier()
; #define PG8_SCHED __builtin_amdgcn_sched_barrier(0)
; template <class Epi, class Sched, bool ALIGN_EPI = false, bool SP2 = false>
; __device__ __forceinline__ void gemm_phase(PG8_LAS unsigned char* lds, const Gemm g, const Sched& S, const Epi& E) {
;     ...
;             PG8_LDA(At, 1, 1); PG8_STAGE(PG8_SB(1, 0), b3, voffB); PG8_STAGE(PG8_SB(1, 1), b3 + hstep, voffB); PG8_STAGE(PG8_SA(1, 0), a3, voffA);
;             PG8_WAIT_V(8); PG8_WAIT_L(0); PG8_BAR; PG8_MMA(1, 0, At, B0); PG8_MMA(1, 1, At, B1); PG8_BAR; PG8_SCHED;
;     ...
;         if constexpr (ALIGN_EPI) { if (wr == 0) PG8_BAR; }
	s_add_i32 s46, s72, s51
	v_lshl_add_u64 v[226:227], v[226:227], 0, s[36:37]
	s_mov_b32 m0, s46
	ds_read_b128 v[192:195], v162 offset:49152
	ds_read_b128 v[198:201], v162 offset:50176
	ds_read_b128 v[202:205], v162 offset:51200
	ds_read_b128 v[206:209], v162 offset:52224
	ds_read_b128 v[210:213], v162 offset:53248
	ds_read_b128 v[214:217], v162 offset:54272
	ds_read_b128 v[218:221], v162 offset:55296
	ds_read_b128 v[222:225], v162 offset:56320
	global_load_lds_dwordx4 v[226:227], off
	s_add_i32 m0, s46, 0x2000
	s_add_u32 s44, s44, 0x2b0080
	v_lshl_add_u64 v[226:227], v[228:229], 0, s[36:37]
	s_addc_u32 s45, s45, 0
	s_add_i32 s46, s73, s51
	global_load_lds_dwordx4 v[226:227], off
	v_lshl_add_u64 v[226:227], s[44:45], 0, v[132:133]
	s_mov_b32 m0, s46
	s_nop 0
	global_load_lds_dwordx4 v[226:227], off
	v_lshl_add_u64 v[226:227], s[44:45], 0, v[136:137]
	s_add_i32 m0, s46, 0x2000
	s_nop 0
	global_load_lds_dwordx4 v[226:227], off
	v_lshl_add_u64 v[226:227], v[230:231], 0, s[36:37]
	s_mov_b32 m0, s57
	s_nop 0
	global_load_lds_dwordx4 v[226:227], off
	v_lshl_add_u64 v[226:227], v[232:233], 0, s[36:37]
	s_mov_b32 m0, s58
	s_nop 0
	global_load_lds_dwordx4 v[226:227], off
	s_waitcnt vmcnt(8)
	s_waitcnt lgkmcnt(0)
	s_nop 0
	s_setprio 1
	s_barrier
	v_mfma_f32_16x16x32_bf16 v[62:65], v[146:149], v[192:195], v[62:65]
	v_mfma_f32_16x16x32_bf16 v[58:61], v[168:171], v[192:195], v[58:61]
	v_mfma_f32_16x16x32_bf16 v[46:49], v[146:149], v[202:205], v[46:49]
	v_mfma_f32_16x16x32_bf16 v[42:45], v[168:171], v[202:205], v[42:45]
	v_mfma_f32_16x16x32_bf16 v[30:33], v[146:149], v[210:213], v[30:33]
	v_mfma_f32_16x16x32_bf16 v[26:29], v[168:171], v[210:213], v[26:29]
	v_mfma_f32_16x16x32_bf16 v[14:17], v[146:149], v[218:221], v[14:17]
	v_mfma_f32_16x16x32_bf16 v[10:13], v[168:171], v[218:221], v[10:13]
	v_mfma_f32_16x16x32_bf16 v[62:65], v[164:167], v[198:201], v[62:65]
	v_mfma_f32_16x16x32_bf16 v[58:61], v[172:175], v[198:201], v[58:61]
	v_mfma_f32_16x16x32_bf16 v[46:49], v[164:167], v[206:209], v[46:49]
	v_mfma_f32_16x16x32_bf16 v[42:45], v[172:175], v[206:209], v[42:45]
	v_mfma_f32_16x16x32_bf16 v[30:33], v[164:167], v[214:217], v[30:33]
	v_mfma_f32_16x16x32_bf16 v[26:29], v[172:175], v[214:217], v[26:29]
	v_mfma_f32_16x16x32_bf16 v[14:17], v[164:167], v[222:225], v[14:17]
	v_mfma_f32_16x16x32_bf16 v[10:13], v[172:175], v[222:225], v[10:13]
	s_setprio 0
	s_setprio 1
	v_mfma_f32_16x16x32_bf16 v[54:57], v[176:179], v[192:195], v[54:57]
	v_mfma_f32_16x16x32_bf16 v[50:53], v[184:187], v[192:195], v[50:53]
	v_mfma_f32_16x16x32_bf16 v[38:41], v[176:179], v[202:205], v[38:41]
	v_mfma_f32_16x16x32_bf16 v[34:37], v[184:187], v[202:205], v[34:37]
	v_mfma_f32_16x16x32_bf16 v[22:25], v[176:179], v[210:213], v[22:25]
	v_mfma_f32_16x16x32_bf16 v[18:21], v[184:187], v[210:213], v[18:21]
	v_mfma_f32_16x16x32_bf16 v[6:9], v[176:179], v[218:221], v[6:9]
	v_mfma_f32_16x16x32_bf16 v[2:5], v[184:187], v[218:221], v[2:5]
	v_mfma_f32_16x16x32_bf16 v[54:57], v[180:183], v[198:201], v[54:57]
	v_mfma_f32_16x16x32_bf16 v[50:53], v[188:191], v[198:201], v[50:53]
	v_mfma_f32_16x16x32_bf16 v[38:41], v[180:183], v[206:209], v[38:41]
	v_mfma_f32_16x16x32_bf16 v[34:37], v[188:191], v[206:209], v[34:37]
	v_mfma_f32_16x16x32_bf16 v[22:25], v[180:183], v[214:217], v[22:25]
	v_mfma_f32_16x16x32_bf16 v[18:21], v[188:191], v[214:217], v[18:21]
	v_mfma_f32_16x16x32_bf16 v[6:9], v[180:183], v[222:225], v[6:9]
	v_mfma_f32_16x16x32_bf16 v[2:5], v[188:191], v[222:225], v[2:5]
	s_setprio 0
	s_barrier
	s_add_i32 s71, s71, 2
	s_add_u32 s42, s42, 0x100
	s_addc_u32 s43, s43, 0
	s_add_u32 s69, s69, 0x100
	s_addc_u32 s70, s70, 0
	s_cmpk_gt_u32 s71, 0xa9
	s_cbranch_scc0 .LBB0_984
	s_and_b64 vcc, exec, s[38:39]
	s_cbranch_vccz .LBB0_987
	s_barrier
